# gdn gate (phase 4) and norm1 (phase 6) rewritten with all of a wave's rows requested up front
# baseline (speedup 1.0000x reference)
; DI unsigned pk_bf16(float a, float b) { f32x2 v = {a, b}; bf2_t r = __builtin_convertvector(v, bf2_t); return __builtin_bit_cast(unsigned, r); }
; DI float bflo(unsigned u) { return __uint_as_float(u << 16); }
; DI float bfhi(unsigned u) { return __uint_as_float(u & 0xffff0000u); }
; DI float silu_f(float x) { return x * __builtin_amdgcn_rcpf(1.f + __expf(-x)); }
; DI void phase_gdn_gate(const Params& p) {
;     const int lane = threadIdx.x & 63, gw = blockIdx.x * 8 + (threadIdx.x >> 6), nw = gridDim.x * 8;
;     const bf16_t* oraw = (const bf16_t*)(p.ws + WS_ORAW); const bf16_t* P0 = (const bf16_t*)(p.ws + WS_P0); bf16_t* og = (bf16_t*)(p.ws + WS_OG);
;     for (int tok = gw; tok < T_TOK; tok += nw) {
;         const u32x4 a0 = *(const u32x4*)(oraw + (size_t)tok * 1024 + 16 * lane), a1 = *(const u32x4*)(oraw + (size_t)tok * 1024 + 16 * lane + 8);
;         const u32x4 z0 = *(const u32x4*)(P0 + (size_t)tok * LDP0 + 3072 + 16 * lane), z1 = *(const u32x4*)(P0 + (size_t)tok * LDP0 + 3072 + 16 * lane + 8);
;         float o[16], z[16];
;         const unsigned au[8] = {a0.x, a0.y, a0.z, a0.w, a1.x, a1.y, a1.z, a1.w}, zu[8] = {z0.x, z0.y, z0.z, z0.w, z1.x, z1.y, z1.z, z1.w};
;         float ss = 0.f;
; #pragma unroll
;         for (int i = 0; i < 8; ++i) { o[2 * i] = bflo(au[i]); o[2 * i + 1] = bfhi(au[i]); z[2 * i] = bflo(zu[i]); z[2 * i + 1] = bfhi(zu[i]); ss += o[2 * i] * o[2 * i] + o[2 * i + 1] * o[2 * i + 1]; }
;         ss += __shfl_xor(ss, 1); ss += __shfl_xor(ss, 2); ss += __shfl_xor(ss, 4);
;         const float rstd = rsqrtf(ss * (1.f / 128.f) + 1e-6f);
;         const int d0 = (16 * lane) & 127;
;         unsigned r[8];
; #pragma unroll
;         for (int i = 0; i < 8; ++i) { const float v0 = o[2 * i] * rstd * p.onorm_a[d0 + 2 * i] * silu_f(z[2 * i]), v1 = o[2 * i + 1] * rstd * p.onorm_a[d0 + 2 * i + 1] * silu_f(z[2 * i + 1]); r[i] = pk_bf16(v0, v1); }
;         *(u32x4*)(og + (size_t)tok * 1024 + 16 * lane) = (u32x4){r[0], r[1], r[2], r[3]};
.LBB0_930:
	s_cmp_lt_i32 s80, 5
	s_cselect_b64 s[4:5], -1, 0
	v_add_u32_e32 v162, s83, v155
	s_movk_i32 s3, 0x4400
	s_and_b64 s[0:1], s[4:5], s[0:1]
	v_cmp_gt_i32_e64 s[44:45], s3, v162
	s_lshl_b32 s46, s94, 3
	s_and_b64 s[0:1], s[44:45], s[0:1]
	v_ashrrev_i32_e32 v163, 31, v162
	v_mbcnt_lo_u32_b32 v197, -1, 0
	v_and_b32_e32 v196, 63, v1
	s_and_saveexec_b64 s[6:7], s[0:1]
	s_cbranch_execz .LBB0_933
	v_readlane_b32 s14, v238, 6
	v_readlane_b32 s15, v238, 7
	v_lshlrev_b32_e32 v2, 5, v196
	v_and_b32_e32 v3, 7, v196
	v_lshlrev_b32_e32 v3, 6, v3
	s_add_u32 s10, s78, 0x3c80000
	s_addc_u32 s11, s79, 0
	s_add_u32 s12, s78, 0x1d481800
	s_addc_u32 s13, s79, 0
	s_add_u32 s16, s78, 0x8080000
	s_addc_u32 s17, s79, 0
	v_readfirstlane_b32 s8, v162
	v_mov_b32_e32 v15, 0x358637bd
	s_cmpk_lt_u32 s8, 0x400
	s_cbranch_scc0 .Lg4_no9a
	s_mul_i32 s9, s46, 8
	s_add_i32 s9, s9, s8
	s_lshl_b32 s3, s9, 11
	s_add_u32 s20, s10, s3
	s_addc_u32 s21, s11, 0
	s_mul_i32 s3, s9, 0x2200
	s_add_u32 s22, s12, s3
	s_addc_u32 s23, s13, 0
	global_load_dwordx4 v[198:201], v2, s[20:21]
	global_load_dwordx4 v[202:205], v2, s[20:21] offset:16
	global_load_dwordx4 v[206:209], v2, s[22:23]
	global_load_dwordx4 v[210:213], v2, s[22:23] offset:16
.Lg4_no9a:
	global_load_dwordx4 v[16:19], v3, s[14:15]
	global_load_dwordx4 v[20:23], v3, s[14:15] offset:16
	global_load_dwordx4 v[24:27], v3, s[14:15] offset:32
	global_load_dwordx4 v[28:31], v3, s[14:15] offset:48
	s_mul_i32 s9, s46, 0
	s_add_i32 s9, s9, s8
	s_lshl_b32 s3, s9, 11
	s_add_u32 s20, s10, s3
	s_addc_u32 s21, s11, 0
	s_mul_i32 s3, s9, 0x2200
	s_add_u32 s22, s12, s3
	s_addc_u32 s23, s13, 0
	global_load_dwordx4 v[32:35], v2, s[20:21]
	global_load_dwordx4 v[36:39], v2, s[20:21] offset:16
	global_load_dwordx4 v[40:43], v2, s[22:23]
	global_load_dwordx4 v[44:47], v2, s[22:23] offset:16
	s_mul_i32 s9, s46, 1
	s_add_i32 s9, s9, s8
	s_lshl_b32 s3, s9, 11
	s_add_u32 s20, s10, s3
	s_addc_u32 s21, s11, 0
	s_mul_i32 s3, s9, 0x2200
	s_add_u32 s22, s12, s3
	s_addc_u32 s23, s13, 0
	global_load_dwordx4 v[48:51], v2, s[20:21]
	global_load_dwordx4 v[52:55], v2, s[20:21] offset:16
	global_load_dwordx4 v[56:59], v2, s[22:23]
	global_load_dwordx4 v[60:63], v2, s[22:23] offset:16
	s_mul_i32 s9, s46, 2
	s_add_i32 s9, s9, s8
	s_lshl_b32 s3, s9, 11
	s_add_u32 s20, s10, s3
	s_addc_u32 s21, s11, 0
	s_mul_i32 s3, s9, 0x2200
	s_add_u32 s22, s12, s3
	s_addc_u32 s23, s13, 0
	global_load_dwordx4 v[64:67], v2, s[20:21]
	global_load_dwordx4 v[68:71], v2, s[20:21] offset:16
	global_load_dwordx4 v[72:75], v2, s[22:23]
	global_load_dwordx4 v[76:79], v2, s[22:23] offset:16
	s_mul_i32 s9, s46, 3
	s_add_i32 s9, s9, s8
	s_lshl_b32 s3, s9, 11
	s_add_u32 s20, s10, s3
	s_addc_u32 s21, s11, 0
	s_mul_i32 s3, s9, 0x2200
	s_add_u32 s22, s12, s3
	s_addc_u32 s23, s13, 0
	global_load_dwordx4 v[80:83], v2, s[20:21]
	global_load_dwordx4 v[84:87], v2, s[20:21] offset:16
	global_load_dwordx4 v[88:91], v2, s[22:23]
	global_load_dwordx4 v[92:95], v2, s[22:23] offset:16
	s_mul_i32 s9, s46, 4
	s_add_i32 s9, s9, s8
	s_lshl_b32 s3, s9, 11
	s_add_u32 s20, s10, s3
	s_addc_u32 s21, s11, 0
	s_mul_i32 s3, s9, 0x2200
	s_add_u32 s22, s12, s3
	s_addc_u32 s23, s13, 0
	global_load_dwordx4 v[96:99], v2, s[20:21]
	global_load_dwordx4 v[100:103], v2, s[20:21] offset:16
	global_load_dwordx4 v[104:107], v2, s[22:23]
	global_load_dwordx4 v[108:111], v2, s[22:23] offset:16
	s_mul_i32 s9, s46, 5
	s_add_i32 s9, s9, s8
	s_lshl_b32 s3, s9, 11
	s_add_u32 s20, s10, s3
	s_addc_u32 s21, s11, 0
	s_mul_i32 s3, s9, 0x2200
	s_add_u32 s22, s12, s3
	s_addc_u32 s23, s13, 0
	global_load_dwordx4 v[112:115], v2, s[20:21]
	global_load_dwordx4 v[116:119], v2, s[20:21] offset:16
	global_load_dwordx4 v[120:123], v2, s[22:23]
	global_load_dwordx4 v[124:127], v2, s[22:23] offset:16
	s_mul_i32 s9, s46, 6
	s_add_i32 s9, s9, s8
	s_lshl_b32 s3, s9, 11
	s_add_u32 s20, s10, s3
	s_addc_u32 s21, s11, 0
	s_mul_i32 s3, s9, 0x2200
	s_add_u32 s22, s12, s3
	s_addc_u32 s23, s13, 0
	global_load_dwordx4 v[128:131], v2, s[20:21]
	global_load_dwordx4 v[132:135], v2, s[20:21] offset:16
	global_load_dwordx4 v[136:139], v2, s[22:23]
	global_load_dwordx4 v[140:143], v2, s[22:23] offset:16
	s_mul_i32 s9, s46, 7
	s_add_i32 s9, s9, s8
	s_lshl_b32 s3, s9, 11
	s_add_u32 s20, s10, s3
	s_addc_u32 s21, s11, 0
	s_mul_i32 s3, s9, 0x2200
	s_add_u32 s22, s12, s3
	s_addc_u32 s23, s13, 0
	global_load_dwordx4 v[168:171], v2, s[20:21]
	global_load_dwordx4 v[172:175], v2, s[20:21] offset:16
	global_load_dwordx4 v[176:179], v2, s[22:23]
	global_load_dwordx4 v[180:183], v2, s[22:23] offset:16
	s_waitcnt vmcnt(28)
; DI unsigned pk_bf16(float a, float b) { f32x2 v = {a, b}; bf2_t r = __builtin_convertvector(v, bf2_t); return __builtin_bit_cast(unsigned, r); }
; DI float bflo(unsigned u) { return __uint_as_float(u << 16); }
; DI float bfhi(unsigned u) { return __uint_as_float(u & 0xffff0000u); }
; DI float silu_f(float x) { return x * __builtin_amdgcn_rcpf(1.f + __expf(-x)); }
; DI void phase_gdn_gate(const Params& p) {
;     ...
;         const u32x4 a0 = *(const u32x4*)(oraw + (size_t)tok * 1024 + 16 * lane), a1 = *(const u32x4*)(oraw + (size_t)tok * 1024 + 16 * lane + 8);
;         const u32x4 z0 = *(const u32x4*)(P0 + (size_t)tok * LDP0 + 3072 + 16 * lane), z1 = *(const u32x4*)(P0 + (size_t)tok * LDP0 + 3072 + 16 * lane + 8);
;         float o[16], z[16];
;         const unsigned au[8] = {a0.x, a0.y, a0.z, a0.w, a1.x, a1.y, a1.z, a1.w}, zu[8] = {z0.x, z0.y, z0.z, z0.w, z1.x, z1.y, z1.z, z1.w};
;         float ss = 0.f;
; #pragma unroll
;         for (int i = 0; i < 8; ++i) { o[2 * i] = bflo(au[i]); o[2 * i + 1] = bfhi(au[i]); z[2 * i] = bflo(zu[i]); z[2 * i + 1] = bfhi(zu[i]); ss += o[2 * i] * o[2 * i] + o[2 * i + 1] * o[2 * i + 1]; }
;         ss += __shfl_xor(ss, 1); ss += __shfl_xor(ss, 2); ss += __shfl_xor(ss, 4);
;         const float rstd = rsqrtf(ss * (1.f / 128.f) + 1e-6f);
;         const int d0 = (16 * lane) & 127;
;         unsigned r[8];
; #pragma unroll
;         for (int i = 0; i < 8; ++i) { const float v0 = o[2 * i] * rstd * p.onorm_a[d0 + 2 * i] * silu_f(z[2 * i]), v1 = o[2 * i + 1] * rstd * p.onorm_a[d0 + 2 * i + 1] * silu_f(z[2 * i + 1]); r[i] = pk_bf16(v0, v1); }
;         *(u32x4*)(og + (size_t)tok * 1024 + 16 * lane) = (u32x4){r[0], r[1], r[2], r[3]};
;         *(u32x4*)(og + (size_t)tok * 1024 + 16 * lane + 8) = (u32x4){r[4], r[5], r[6], r[7]};
	v_lshlrev_b32_e32 v214, 16, v32
	v_and_b32_e32 v215, 0xffff0000, v32
	v_lshlrev_b32_e32 v216, 16, v33
	v_and_b32_e32 v217, 0xffff0000, v33
	v_lshlrev_b32_e32 v218, 16, v34
	v_and_b32_e32 v219, 0xffff0000, v34
	v_lshlrev_b32_e32 v220, 16, v35
	v_and_b32_e32 v221, 0xffff0000, v35
	v_lshlrev_b32_e32 v222, 16, v36
	v_and_b32_e32 v223, 0xffff0000, v36
	v_lshlrev_b32_e32 v224, 16, v37
	v_and_b32_e32 v225, 0xffff0000, v37
	v_lshlrev_b32_e32 v226, 16, v38
	v_and_b32_e32 v227, 0xffff0000, v38
	v_lshlrev_b32_e32 v228, 16, v39
	v_and_b32_e32 v229, 0xffff0000, v39
	v_mul_f32_e32 v144, v214, v214
	v_fmac_f32_e32 v144, v215, v215
	v_fmac_f32_e32 v144, v216, v216
	v_fmac_f32_e32 v144, v217, v217
	v_fmac_f32_e32 v144, v218, v218
	v_fmac_f32_e32 v144, v219, v219
	v_fmac_f32_e32 v144, v220, v220
	v_fmac_f32_e32 v144, v221, v221
	v_mul_f32_e32 v145, v222, v222
	v_fmac_f32_e32 v145, v223, v223
	v_fmac_f32_e32 v145, v224, v224
	v_fmac_f32_e32 v145, v225, v225
	v_fmac_f32_e32 v145, v226, v226
	v_fmac_f32_e32 v145, v227, v227
	v_fmac_f32_e32 v145, v228, v228
	v_fmac_f32_e32 v145, v229, v229
	v_add_f32_e32 v144, v144, v145
	v_lshlrev_b32_e32 v240, 16, v40
	v_and_b32_e32 v241, 0xffff0000, v40
	v_lshlrev_b32_e32 v242, 16, v41
	v_and_b32_e32 v243, 0xffff0000, v41
	v_lshlrev_b32_e32 v244, 16, v42
	v_and_b32_e32 v245, 0xffff0000, v42
	v_lshlrev_b32_e32 v246, 16, v43
	v_and_b32_e32 v247, 0xffff0000, v43
	v_lshlrev_b32_e32 v248, 16, v44
	v_and_b32_e32 v249, 0xffff0000, v44
	v_lshlrev_b32_e32 v250, 16, v45
	v_and_b32_e32 v251, 0xffff0000, v45
	v_lshlrev_b32_e32 v252, 16, v46
	v_and_b32_e32 v253, 0xffff0000, v46
	v_lshlrev_b32_e32 v254, 16, v47
	v_and_b32_e32 v255, 0xffff0000, v47
	s_nop 1
	v_add_f32_dpp v144, v144, v144 quad_perm:[1,0,3,2] row_mask:0xf bank_mask:0xf
	s_nop 1
	v_add_f32_dpp v144, v144, v144 quad_perm:[2,3,0,1] row_mask:0xf bank_mask:0xf
	s_nop 1
	v_add_f32_dpp v144, v144, v144 row_half_mirror row_mask:0xf bank_mask:0xf
	v_fmamk_f32 v144, v144, 0x3c000000, v15
	v_rsq_f32_e32 v144, v144
	v_mul_f32_e32 v148, 0xbfb8aa3b, v240
	v_mul_f32_e32 v149, 0xbfb8aa3b, v241
	v_mul_f32_e32 v150, 0xbfb8aa3b, v242
	v_mul_f32_e32 v151, 0xbfb8aa3b, v243
	v_mul_f32_e32 v4, 0xbfb8aa3b, v244
	v_mul_f32_e32 v5, 0xbfb8aa3b, v245
	v_mul_f32_e32 v6, 0xbfb8aa3b, v246
	v_mul_f32_e32 v7, 0xbfb8aa3b, v247
	v_exp_f32_e32 v148, v148
	v_exp_f32_e32 v149, v149
	v_exp_f32_e32 v150, v150
	v_exp_f32_e32 v151, v151
	v_exp_f32_e32 v4, v4
	v_exp_f32_e32 v5, v5
	v_exp_f32_e32 v6, v6
	v_exp_f32_e32 v7, v7
	v_add_f32_e32 v148, 1.0, v148
	v_add_f32_e32 v149, 1.0, v149
	v_add_f32_e32 v150, 1.0, v150
	v_add_f32_e32 v151, 1.0, v151
	v_add_f32_e32 v4, 1.0, v4
	v_add_f32_e32 v5, 1.0, v5
	v_add_f32_e32 v6, 1.0, v6
	v_add_f32_e32 v7, 1.0, v7
	v_rcp_f32_e32 v148, v148
	v_rcp_f32_e32 v149, v149
	v_rcp_f32_e32 v150, v150
	v_rcp_f32_e32 v151, v151
	v_rcp_f32_e32 v4, v4
	v_rcp_f32_e32 v5, v5
	v_rcp_f32_e32 v6, v6
	v_rcp_f32_e32 v7, v7
	v_mul_f32_e32 v240, v148, v240
	v_mul_f32_e32 v241, v149, v241
	v_mul_f32_e32 v242, v150, v242
	v_mul_f32_e32 v243, v151, v243
	v_mul_f32_e32 v244, v4, v244
	v_mul_f32_e32 v245, v5, v245
	v_mul_f32_e32 v246, v6, v246
	v_mul_f32_e32 v247, v7, v247
	v_mul_f32_e32 v148, 0xbfb8aa3b, v248
	v_mul_f32_e32 v149, 0xbfb8aa3b, v249
	v_mul_f32_e32 v150, 0xbfb8aa3b, v250
	v_mul_f32_e32 v151, 0xbfb8aa3b, v251
	v_mul_f32_e32 v4, 0xbfb8aa3b, v252
	v_mul_f32_e32 v5, 0xbfb8aa3b, v253
	v_mul_f32_e32 v6, 0xbfb8aa3b, v254
	v_mul_f32_e32 v7, 0xbfb8aa3b, v255
	v_exp_f32_e32 v148, v148
	v_exp_f32_e32 v149, v149
	v_exp_f32_e32 v150, v150
	v_exp_f32_e32 v151, v151
	v_exp_f32_e32 v4, v4
	v_exp_f32_e32 v5, v5
	v_exp_f32_e32 v6, v6
	v_exp_f32_e32 v7, v7
	v_add_f32_e32 v148, 1.0, v148
	v_add_f32_e32 v149, 1.0, v149
	v_add_f32_e32 v150, 1.0, v150
	v_add_f32_e32 v151, 1.0, v151
	v_add_f32_e32 v4, 1.0, v4
	v_add_f32_e32 v5, 1.0, v5
	v_add_f32_e32 v6, 1.0, v6
	v_add_f32_e32 v7, 1.0, v7
	v_rcp_f32_e32 v148, v148
	v_rcp_f32_e32 v149, v149
	v_rcp_f32_e32 v150, v150
	v_rcp_f32_e32 v151, v151
	v_rcp_f32_e32 v4, v4
	v_rcp_f32_e32 v5, v5
	v_rcp_f32_e32 v6, v6
	v_rcp_f32_e32 v7, v7
	v_mul_f32_e32 v248, v148, v248
	v_mul_f32_e32 v249, v149, v249
	v_mul_f32_e32 v250, v150, v250
	v_mul_f32_e32 v251, v151, v251
	v_mul_f32_e32 v252, v4, v252
	v_mul_f32_e32 v253, v5, v253
	v_mul_f32_e32 v254, v6, v254
	v_mul_f32_e32 v255, v7, v255
	v_mul_f32_e32 v214, v144, v214
	v_mul_f32_e32 v215, v144, v215
	v_mul_f32_e32 v216, v144, v216
	v_mul_f32_e32 v217, v144, v217
	v_mul_f32_e32 v218, v144, v218
	v_mul_f32_e32 v219, v144, v219
	v_mul_f32_e32 v220, v144, v220
	v_mul_f32_e32 v221, v144, v221
	v_mul_f32_e32 v222, v144, v222
	v_mul_f32_e32 v223, v144, v223
	v_mul_f32_e32 v224, v144, v224
	v_mul_f32_e32 v225, v144, v225
	v_mul_f32_e32 v226, v144, v226
	v_mul_f32_e32 v227, v144, v227
	v_mul_f32_e32 v228, v144, v228
	v_mul_f32_e32 v229, v144, v229
	v_mul_f32_e32 v214, v16, v214
	v_mul_f32_e32 v215, v17, v215
	v_mul_f32_e32 v216, v18, v216
	v_mul_f32_e32 v217, v19, v217
	v_mul_f32_e32 v218, v20, v218
	v_mul_f32_e32 v219, v21, v219
	v_mul_f32_e32 v220, v22, v220
	v_mul_f32_e32 v221, v23, v221
	v_mul_f32_e32 v222, v24, v222
	v_mul_f32_e32 v223, v25, v223
	v_mul_f32_e32 v224, v26, v224
	v_mul_f32_e32 v225, v27, v225
	v_mul_f32_e32 v226, v28, v226
	v_mul_f32_e32 v227, v29, v227
	v_mul_f32_e32 v228, v30, v228
	v_mul_f32_e32 v229, v31, v229
	v_mul_f32_e32 v214, v240, v214
	v_mul_f32_e32 v215, v241, v215
	v_mul_f32_e32 v216, v242, v216
	v_mul_f32_e32 v217, v243, v217
	v_mul_f32_e32 v218, v244, v218
	v_mul_f32_e32 v219, v245, v219
	v_mul_f32_e32 v220, v246, v220
	v_mul_f32_e32 v221, v247, v221
	v_mul_f32_e32 v222, v248, v222
	v_mul_f32_e32 v223, v249, v223
	v_mul_f32_e32 v224, v250, v224
	v_mul_f32_e32 v225, v251, v225
	v_mul_f32_e32 v226, v252, v226
	v_mul_f32_e32 v227, v253, v227
	v_mul_f32_e32 v228, v254, v228
	v_mul_f32_e32 v229, v255, v229
	v_cvt_pk_bf16_f32 v144, v214, v215
	v_cvt_pk_bf16_f32 v145, v216, v217
	v_cvt_pk_bf16_f32 v146, v218, v219
	v_cvt_pk_bf16_f32 v147, v220, v221
	v_cvt_pk_bf16_f32 v148, v222, v223
	v_cvt_pk_bf16_f32 v149, v224, v225
	v_cvt_pk_bf16_f32 v150, v226, v227
	v_cvt_pk_bf16_f32 v151, v228, v229
	s_mul_i32 s9, s46, 0
	s_add_i32 s9, s9, s8
	s_lshl_b32 s3, s9, 11
	s_add_u32 s24, s16, s3
	s_addc_u32 s25, s17, 0
	global_store_dwordx4 v2, v[144:147], s[24:25]
	global_store_dwordx4 v2, v[148:151], s[24:25] offset:16
	s_waitcnt vmcnt(26)
; DI unsigned pk_bf16(float a, float b) { f32x2 v = {a, b}; bf2_t r = __builtin_convertvector(v, bf2_t); return __builtin_bit_cast(unsigned, r); }
; DI float bflo(unsigned u) { return __uint_as_float(u << 16); }
; DI float bfhi(unsigned u) { return __uint_as_float(u & 0xffff0000u); }
; DI float silu_f(float x) { return x * __builtin_amdgcn_rcpf(1.f + __expf(-x)); }
; DI void phase_gdn_gate(const Params& p) {
;     ...
;         const u32x4 a0 = *(const u32x4*)(oraw + (size_t)tok * 1024 + 16 * lane), a1 = *(const u32x4*)(oraw + (size_t)tok * 1024 + 16 * lane + 8);
;         const u32x4 z0 = *(const u32x4*)(P0 + (size_t)tok * LDP0 + 3072 + 16 * lane), z1 = *(const u32x4*)(P0 + (size_t)tok * LDP0 + 3072 + 16 * lane + 8);
;         float o[16], z[16];
;         const unsigned au[8] = {a0.x, a0.y, a0.z, a0.w, a1.x, a1.y, a1.z, a1.w}, zu[8] = {z0.x, z0.y, z0.z, z0.w, z1.x, z1.y, z1.z, z1.w};
;         float ss = 0.f;
; #pragma unroll
;         for (int i = 0; i < 8; ++i) { o[2 * i] = bflo(au[i]); o[2 * i + 1] = bfhi(au[i]); z[2 * i] = bflo(zu[i]); z[2 * i + 1] = bfhi(zu[i]); ss += o[2 * i] * o[2 * i] + o[2 * i + 1] * o[2 * i + 1]; }
;         ss += __shfl_xor(ss, 1); ss += __shfl_xor(ss, 2); ss += __shfl_xor(ss, 4);
;         const float rstd = rsqrtf(ss * (1.f / 128.f) + 1e-6f);
;         const int d0 = (16 * lane) & 127;
;         unsigned r[8];
; #pragma unroll
;         for (int i = 0; i < 8; ++i) { const float v0 = o[2 * i] * rstd * p.onorm_a[d0 + 2 * i] * silu_f(z[2 * i]), v1 = o[2 * i + 1] * rstd * p.onorm_a[d0 + 2 * i + 1] * silu_f(z[2 * i + 1]); r[i] = pk_bf16(v0, v1); }
;         *(u32x4*)(og + (size_t)tok * 1024 + 16 * lane) = (u32x4){r[0], r[1], r[2], r[3]};
;         *(u32x4*)(og + (size_t)tok * 1024 + 16 * lane + 8) = (u32x4){r[4], r[5], r[6], r[7]};
	v_lshlrev_b32_e32 v214, 16, v48
	v_and_b32_e32 v215, 0xffff0000, v48
	v_lshlrev_b32_e32 v216, 16, v49
	v_and_b32_e32 v217, 0xffff0000, v49
	v_lshlrev_b32_e32 v218, 16, v50
	v_and_b32_e32 v219, 0xffff0000, v50
	v_lshlrev_b32_e32 v220, 16, v51
	v_and_b32_e32 v221, 0xffff0000, v51
	v_lshlrev_b32_e32 v222, 16, v52
	v_and_b32_e32 v223, 0xffff0000, v52
	v_lshlrev_b32_e32 v224, 16, v53
	v_and_b32_e32 v225, 0xffff0000, v53
	v_lshlrev_b32_e32 v226, 16, v54
	v_and_b32_e32 v227, 0xffff0000, v54
	v_lshlrev_b32_e32 v228, 16, v55
	v_and_b32_e32 v229, 0xffff0000, v55
	v_mul_f32_e32 v144, v214, v214
	v_fmac_f32_e32 v144, v215, v215
	v_fmac_f32_e32 v144, v216, v216
	v_fmac_f32_e32 v144, v217, v217
	v_fmac_f32_e32 v144, v218, v218
	v_fmac_f32_e32 v144, v219, v219
	v_fmac_f32_e32 v144, v220, v220
	v_fmac_f32_e32 v144, v221, v221
	v_mul_f32_e32 v145, v222, v222
	v_fmac_f32_e32 v145, v223, v223
	v_fmac_f32_e32 v145, v224, v224
	v_fmac_f32_e32 v145, v225, v225
	v_fmac_f32_e32 v145, v226, v226
	v_fmac_f32_e32 v145, v227, v227
	v_fmac_f32_e32 v145, v228, v228
	v_fmac_f32_e32 v145, v229, v229
	v_add_f32_e32 v144, v144, v145
	v_lshlrev_b32_e32 v240, 16, v56
	v_and_b32_e32 v241, 0xffff0000, v56
	v_lshlrev_b32_e32 v242, 16, v57
	v_and_b32_e32 v243, 0xffff0000, v57
	v_lshlrev_b32_e32 v244, 16, v58
	v_and_b32_e32 v245, 0xffff0000, v58
	v_lshlrev_b32_e32 v246, 16, v59
	v_and_b32_e32 v247, 0xffff0000, v59
	v_lshlrev_b32_e32 v248, 16, v60
	v_and_b32_e32 v249, 0xffff0000, v60
	v_lshlrev_b32_e32 v250, 16, v61
	v_and_b32_e32 v251, 0xffff0000, v61
	v_lshlrev_b32_e32 v252, 16, v62
	v_and_b32_e32 v253, 0xffff0000, v62
	v_lshlrev_b32_e32 v254, 16, v63
	v_and_b32_e32 v255, 0xffff0000, v63
	s_nop 1
	v_add_f32_dpp v144, v144, v144 quad_perm:[1,0,3,2] row_mask:0xf bank_mask:0xf
	s_nop 1
	v_add_f32_dpp v144, v144, v144 quad_perm:[2,3,0,1] row_mask:0xf bank_mask:0xf
	s_nop 1
	v_add_f32_dpp v144, v144, v144 row_half_mirror row_mask:0xf bank_mask:0xf
	v_fmamk_f32 v144, v144, 0x3c000000, v15
	v_rsq_f32_e32 v144, v144
	v_mul_f32_e32 v148, 0xbfb8aa3b, v240
	v_mul_f32_e32 v149, 0xbfb8aa3b, v241
	v_mul_f32_e32 v150, 0xbfb8aa3b, v242
	v_mul_f32_e32 v151, 0xbfb8aa3b, v243
	v_mul_f32_e32 v4, 0xbfb8aa3b, v244
	v_mul_f32_e32 v5, 0xbfb8aa3b, v245
	v_mul_f32_e32 v6, 0xbfb8aa3b, v246
	v_mul_f32_e32 v7, 0xbfb8aa3b, v247
	v_exp_f32_e32 v148, v148
	v_exp_f32_e32 v149, v149
	v_exp_f32_e32 v150, v150
	v_exp_f32_e32 v151, v151
	v_exp_f32_e32 v4, v4
	v_exp_f32_e32 v5, v5
	v_exp_f32_e32 v6, v6
	v_exp_f32_e32 v7, v7
	v_add_f32_e32 v148, 1.0, v148
	v_add_f32_e32 v149, 1.0, v149
	v_add_f32_e32 v150, 1.0, v150
	v_add_f32_e32 v151, 1.0, v151
	v_add_f32_e32 v4, 1.0, v4
	v_add_f32_e32 v5, 1.0, v5
	v_add_f32_e32 v6, 1.0, v6
	v_add_f32_e32 v7, 1.0, v7
	v_rcp_f32_e32 v148, v148
	v_rcp_f32_e32 v149, v149
	v_rcp_f32_e32 v150, v150
	v_rcp_f32_e32 v151, v151
	v_rcp_f32_e32 v4, v4
	v_rcp_f32_e32 v5, v5
	v_rcp_f32_e32 v6, v6
	v_rcp_f32_e32 v7, v7
	v_mul_f32_e32 v240, v148, v240
	v_mul_f32_e32 v241, v149, v241
	v_mul_f32_e32 v242, v150, v242
	v_mul_f32_e32 v243, v151, v243
	v_mul_f32_e32 v244, v4, v244
	v_mul_f32_e32 v245, v5, v245
	v_mul_f32_e32 v246, v6, v246
	v_mul_f32_e32 v247, v7, v247
	v_mul_f32_e32 v148, 0xbfb8aa3b, v248
	v_mul_f32_e32 v149, 0xbfb8aa3b, v249
	v_mul_f32_e32 v150, 0xbfb8aa3b, v250
	v_mul_f32_e32 v151, 0xbfb8aa3b, v251
	v_mul_f32_e32 v4, 0xbfb8aa3b, v252
	v_mul_f32_e32 v5, 0xbfb8aa3b, v253
	v_mul_f32_e32 v6, 0xbfb8aa3b, v254
	v_mul_f32_e32 v7, 0xbfb8aa3b, v255
	v_exp_f32_e32 v148, v148
	v_exp_f32_e32 v149, v149
	v_exp_f32_e32 v150, v150
	v_exp_f32_e32 v151, v151
	v_exp_f32_e32 v4, v4
	v_exp_f32_e32 v5, v5
	v_exp_f32_e32 v6, v6
	v_exp_f32_e32 v7, v7
	v_add_f32_e32 v148, 1.0, v148
	v_add_f32_e32 v149, 1.0, v149
	v_add_f32_e32 v150, 1.0, v150
	v_add_f32_e32 v151, 1.0, v151
	v_add_f32_e32 v4, 1.0, v4
	v_add_f32_e32 v5, 1.0, v5
	v_add_f32_e32 v6, 1.0, v6
	v_add_f32_e32 v7, 1.0, v7
	v_rcp_f32_e32 v148, v148
	v_rcp_f32_e32 v149, v149
	v_rcp_f32_e32 v150, v150
	v_rcp_f32_e32 v151, v151
	v_rcp_f32_e32 v4, v4
	v_rcp_f32_e32 v5, v5
	v_rcp_f32_e32 v6, v6
	v_rcp_f32_e32 v7, v7
	v_mul_f32_e32 v248, v148, v248
	v_mul_f32_e32 v249, v149, v249
	v_mul_f32_e32 v250, v150, v250
	v_mul_f32_e32 v251, v151, v251
	v_mul_f32_e32 v252, v4, v252
	v_mul_f32_e32 v253, v5, v253
	v_mul_f32_e32 v254, v6, v254
	v_mul_f32_e32 v255, v7, v255
	v_mul_f32_e32 v214, v144, v214
	v_mul_f32_e32 v215, v144, v215
	v_mul_f32_e32 v216, v144, v216
	v_mul_f32_e32 v217, v144, v217
	v_mul_f32_e32 v218, v144, v218
	v_mul_f32_e32 v219, v144, v219
	v_mul_f32_e32 v220, v144, v220
	v_mul_f32_e32 v221, v144, v221
	v_mul_f32_e32 v222, v144, v222
	v_mul_f32_e32 v223, v144, v223
	v_mul_f32_e32 v224, v144, v224
	v_mul_f32_e32 v225, v144, v225
	v_mul_f32_e32 v226, v144, v226
	v_mul_f32_e32 v227, v144, v227
	v_mul_f32_e32 v228, v144, v228
	v_mul_f32_e32 v229, v144, v229
	v_mul_f32_e32 v214, v16, v214
	v_mul_f32_e32 v215, v17, v215
	v_mul_f32_e32 v216, v18, v216
	v_mul_f32_e32 v217, v19, v217
	v_mul_f32_e32 v218, v20, v218
	v_mul_f32_e32 v219, v21, v219
	v_mul_f32_e32 v220, v22, v220
	v_mul_f32_e32 v221, v23, v221
	v_mul_f32_e32 v222, v24, v222
	v_mul_f32_e32 v223, v25, v223
	v_mul_f32_e32 v224, v26, v224
	v_mul_f32_e32 v225, v27, v225
	v_mul_f32_e32 v226, v28, v226
	v_mul_f32_e32 v227, v29, v227
	v_mul_f32_e32 v228, v30, v228
	v_mul_f32_e32 v229, v31, v229
	v_mul_f32_e32 v214, v240, v214
	v_mul_f32_e32 v215, v241, v215
	v_mul_f32_e32 v216, v242, v216
	v_mul_f32_e32 v217, v243, v217
	v_mul_f32_e32 v218, v244, v218
	v_mul_f32_e32 v219, v245, v219
	v_mul_f32_e32 v220, v246, v220
	v_mul_f32_e32 v221, v247, v221
	v_mul_f32_e32 v222, v248, v222
	v_mul_f32_e32 v223, v249, v223
	v_mul_f32_e32 v224, v250, v224
	v_mul_f32_e32 v225, v251, v225
	v_mul_f32_e32 v226, v252, v226
	v_mul_f32_e32 v227, v253, v227
	v_mul_f32_e32 v228, v254, v228
	v_mul_f32_e32 v229, v255, v229
	v_cvt_pk_bf16_f32 v144, v214, v215
	v_cvt_pk_bf16_f32 v145, v216, v217
	v_cvt_pk_bf16_f32 v146, v218, v219
	v_cvt_pk_bf16_f32 v147, v220, v221
	v_cvt_pk_bf16_f32 v148, v222, v223
	v_cvt_pk_bf16_f32 v149, v224, v225
	v_cvt_pk_bf16_f32 v150, v226, v227
	v_cvt_pk_bf16_f32 v151, v228, v229
	s_mul_i32 s9, s46, 1
	s_add_i32 s9, s9, s8
	s_lshl_b32 s3, s9, 11
	s_add_u32 s24, s16, s3
	s_addc_u32 s25, s17, 0
	global_store_dwordx4 v2, v[144:147], s[24:25]
	global_store_dwordx4 v2, v[148:151], s[24:25] offset:16
	s_waitcnt vmcnt(24)
; DI unsigned pk_bf16(float a, float b) { f32x2 v = {a, b}; bf2_t r = __builtin_convertvector(v, bf2_t); return __builtin_bit_cast(unsigned, r); }
; DI float bflo(unsigned u) { return __uint_as_float(u << 16); }
; DI float bfhi(unsigned u) { return __uint_as_float(u & 0xffff0000u); }
; DI float silu_f(float x) { return x * __builtin_amdgcn_rcpf(1.f + __expf(-x)); }
; DI void phase_gdn_gate(const Params& p) {
;     ...
;         const u32x4 a0 = *(const u32x4*)(oraw + (size_t)tok * 1024 + 16 * lane), a1 = *(const u32x4*)(oraw + (size_t)tok * 1024 + 16 * lane + 8);
;         const u32x4 z0 = *(const u32x4*)(P0 + (size_t)tok * LDP0 + 3072 + 16 * lane), z1 = *(const u32x4*)(P0 + (size_t)tok * LDP0 + 3072 + 16 * lane + 8);
;         float o[16], z[16];
;         const unsigned au[8] = {a0.x, a0.y, a0.z, a0.w, a1.x, a1.y, a1.z, a1.w}, zu[8] = {z0.x, z0.y, z0.z, z0.w, z1.x, z1.y, z1.z, z1.w};
;         float ss = 0.f;
; #pragma unroll
;         for (int i = 0; i < 8; ++i) { o[2 * i] = bflo(au[i]); o[2 * i + 1] = bfhi(au[i]); z[2 * i] = bflo(zu[i]); z[2 * i + 1] = bfhi(zu[i]); ss += o[2 * i] * o[2 * i] + o[2 * i + 1] * o[2 * i + 1]; }
;         ss += __shfl_xor(ss, 1); ss += __shfl_xor(ss, 2); ss += __shfl_xor(ss, 4);
;         const float rstd = rsqrtf(ss * (1.f / 128.f) + 1e-6f);
;         const int d0 = (16 * lane) & 127;
;         unsigned r[8];
; #pragma unroll
;         for (int i = 0; i < 8; ++i) { const float v0 = o[2 * i] * rstd * p.onorm_a[d0 + 2 * i] * silu_f(z[2 * i]), v1 = o[2 * i + 1] * rstd * p.onorm_a[d0 + 2 * i + 1] * silu_f(z[2 * i + 1]); r[i] = pk_bf16(v0, v1); }
;         *(u32x4*)(og + (size_t)tok * 1024 + 16 * lane) = (u32x4){r[0], r[1], r[2], r[3]};
;         *(u32x4*)(og + (size_t)tok * 1024 + 16 * lane + 8) = (u32x4){r[4], r[5], r[6], r[7]};
	v_lshlrev_b32_e32 v214, 16, v64
	v_and_b32_e32 v215, 0xffff0000, v64
	v_lshlrev_b32_e32 v216, 16, v65
	v_and_b32_e32 v217, 0xffff0000, v65
	v_lshlrev_b32_e32 v218, 16, v66
	v_and_b32_e32 v219, 0xffff0000, v66
	v_lshlrev_b32_e32 v220, 16, v67
	v_and_b32_e32 v221, 0xffff0000, v67
	v_lshlrev_b32_e32 v222, 16, v68
	v_and_b32_e32 v223, 0xffff0000, v68
	v_lshlrev_b32_e32 v224, 16, v69
	v_and_b32_e32 v225, 0xffff0000, v69
	v_lshlrev_b32_e32 v226, 16, v70
	v_and_b32_e32 v227, 0xffff0000, v70
	v_lshlrev_b32_e32 v228, 16, v71
	v_and_b32_e32 v229, 0xffff0000, v71
	v_mul_f32_e32 v144, v214, v214
	v_fmac_f32_e32 v144, v215, v215
	v_fmac_f32_e32 v144, v216, v216
	v_fmac_f32_e32 v144, v217, v217
	v_fmac_f32_e32 v144, v218, v218
	v_fmac_f32_e32 v144, v219, v219
	v_fmac_f32_e32 v144, v220, v220
	v_fmac_f32_e32 v144, v221, v221
	v_mul_f32_e32 v145, v222, v222
	v_fmac_f32_e32 v145, v223, v223
	v_fmac_f32_e32 v145, v224, v224
	v_fmac_f32_e32 v145, v225, v225
	v_fmac_f32_e32 v145, v226, v226
	v_fmac_f32_e32 v145, v227, v227
	v_fmac_f32_e32 v145, v228, v228
	v_fmac_f32_e32 v145, v229, v229
	v_add_f32_e32 v144, v144, v145
	v_lshlrev_b32_e32 v240, 16, v72
	v_and_b32_e32 v241, 0xffff0000, v72
	v_lshlrev_b32_e32 v242, 16, v73
	v_and_b32_e32 v243, 0xffff0000, v73
	v_lshlrev_b32_e32 v244, 16, v74
	v_and_b32_e32 v245, 0xffff0000, v74
	v_lshlrev_b32_e32 v246, 16, v75
	v_and_b32_e32 v247, 0xffff0000, v75
	v_lshlrev_b32_e32 v248, 16, v76
	v_and_b32_e32 v249, 0xffff0000, v76
	v_lshlrev_b32_e32 v250, 16, v77
	v_and_b32_e32 v251, 0xffff0000, v77
	v_lshlrev_b32_e32 v252, 16, v78
	v_and_b32_e32 v253, 0xffff0000, v78
	v_lshlrev_b32_e32 v254, 16, v79
	v_and_b32_e32 v255, 0xffff0000, v79
	s_nop 1
	v_add_f32_dpp v144, v144, v144 quad_perm:[1,0,3,2] row_mask:0xf bank_mask:0xf
	s_nop 1
	v_add_f32_dpp v144, v144, v144 quad_perm:[2,3,0,1] row_mask:0xf bank_mask:0xf
	s_nop 1
	v_add_f32_dpp v144, v144, v144 row_half_mirror row_mask:0xf bank_mask:0xf
	v_fmamk_f32 v144, v144, 0x3c000000, v15
	v_rsq_f32_e32 v144, v144
	v_mul_f32_e32 v148, 0xbfb8aa3b, v240
	v_mul_f32_e32 v149, 0xbfb8aa3b, v241
	v_mul_f32_e32 v150, 0xbfb8aa3b, v242
	v_mul_f32_e32 v151, 0xbfb8aa3b, v243
	v_mul_f32_e32 v4, 0xbfb8aa3b, v244
	v_mul_f32_e32 v5, 0xbfb8aa3b, v245
	v_mul_f32_e32 v6, 0xbfb8aa3b, v246
	v_mul_f32_e32 v7, 0xbfb8aa3b, v247
	v_exp_f32_e32 v148, v148
	v_exp_f32_e32 v149, v149
	v_exp_f32_e32 v150, v150
	v_exp_f32_e32 v151, v151
	v_exp_f32_e32 v4, v4
	v_exp_f32_e32 v5, v5
	v_exp_f32_e32 v6, v6
	v_exp_f32_e32 v7, v7
	v_add_f32_e32 v148, 1.0, v148
	v_add_f32_e32 v149, 1.0, v149
	v_add_f32_e32 v150, 1.0, v150
	v_add_f32_e32 v151, 1.0, v151
	v_add_f32_e32 v4, 1.0, v4
	v_add_f32_e32 v5, 1.0, v5
	v_add_f32_e32 v6, 1.0, v6
	v_add_f32_e32 v7, 1.0, v7
	v_rcp_f32_e32 v148, v148
	v_rcp_f32_e32 v149, v149
	v_rcp_f32_e32 v150, v150
	v_rcp_f32_e32 v151, v151
	v_rcp_f32_e32 v4, v4
	v_rcp_f32_e32 v5, v5
	v_rcp_f32_e32 v6, v6
	v_rcp_f32_e32 v7, v7
	v_mul_f32_e32 v240, v148, v240
	v_mul_f32_e32 v241, v149, v241
	v_mul_f32_e32 v242, v150, v242
	v_mul_f32_e32 v243, v151, v243
	v_mul_f32_e32 v244, v4, v244
	v_mul_f32_e32 v245, v5, v245
	v_mul_f32_e32 v246, v6, v246
	v_mul_f32_e32 v247, v7, v247
	v_mul_f32_e32 v148, 0xbfb8aa3b, v248
	v_mul_f32_e32 v149, 0xbfb8aa3b, v249
	v_mul_f32_e32 v150, 0xbfb8aa3b, v250
	v_mul_f32_e32 v151, 0xbfb8aa3b, v251
	v_mul_f32_e32 v4, 0xbfb8aa3b, v252
	v_mul_f32_e32 v5, 0xbfb8aa3b, v253
	v_mul_f32_e32 v6, 0xbfb8aa3b, v254
	v_mul_f32_e32 v7, 0xbfb8aa3b, v255
	v_exp_f32_e32 v148, v148
	v_exp_f32_e32 v149, v149
	v_exp_f32_e32 v150, v150
	v_exp_f32_e32 v151, v151
	v_exp_f32_e32 v4, v4
	v_exp_f32_e32 v5, v5
	v_exp_f32_e32 v6, v6
	v_exp_f32_e32 v7, v7
	v_add_f32_e32 v148, 1.0, v148
	v_add_f32_e32 v149, 1.0, v149
	v_add_f32_e32 v150, 1.0, v150
	v_add_f32_e32 v151, 1.0, v151
	v_add_f32_e32 v4, 1.0, v4
	v_add_f32_e32 v5, 1.0, v5
	v_add_f32_e32 v6, 1.0, v6
	v_add_f32_e32 v7, 1.0, v7
	v_rcp_f32_e32 v148, v148
	v_rcp_f32_e32 v149, v149
	v_rcp_f32_e32 v150, v150
	v_rcp_f32_e32 v151, v151
	v_rcp_f32_e32 v4, v4
	v_rcp_f32_e32 v5, v5
	v_rcp_f32_e32 v6, v6
	v_rcp_f32_e32 v7, v7
	v_mul_f32_e32 v248, v148, v248
	v_mul_f32_e32 v249, v149, v249
	v_mul_f32_e32 v250, v150, v250
	v_mul_f32_e32 v251, v151, v251
	v_mul_f32_e32 v252, v4, v252
	v_mul_f32_e32 v253, v5, v253
	v_mul_f32_e32 v254, v6, v254
	v_mul_f32_e32 v255, v7, v255
	v_mul_f32_e32 v214, v144, v214
	v_mul_f32_e32 v215, v144, v215
	v_mul_f32_e32 v216, v144, v216
	v_mul_f32_e32 v217, v144, v217
	v_mul_f32_e32 v218, v144, v218
	v_mul_f32_e32 v219, v144, v219
	v_mul_f32_e32 v220, v144, v220
	v_mul_f32_e32 v221, v144, v221
	v_mul_f32_e32 v222, v144, v222
	v_mul_f32_e32 v223, v144, v223
	v_mul_f32_e32 v224, v144, v224
	v_mul_f32_e32 v225, v144, v225
	v_mul_f32_e32 v226, v144, v226
	v_mul_f32_e32 v227, v144, v227
	v_mul_f32_e32 v228, v144, v228
	v_mul_f32_e32 v229, v144, v229
	v_mul_f32_e32 v214, v16, v214
	v_mul_f32_e32 v215, v17, v215
	v_mul_f32_e32 v216, v18, v216
	v_mul_f32_e32 v217, v19, v217
	v_mul_f32_e32 v218, v20, v218
	v_mul_f32_e32 v219, v21, v219
	v_mul_f32_e32 v220, v22, v220
	v_mul_f32_e32 v221, v23, v221
	v_mul_f32_e32 v222, v24, v222
	v_mul_f32_e32 v223, v25, v223
	v_mul_f32_e32 v224, v26, v224
	v_mul_f32_e32 v225, v27, v225
	v_mul_f32_e32 v226, v28, v226
	v_mul_f32_e32 v227, v29, v227
	v_mul_f32_e32 v228, v30, v228
	v_mul_f32_e32 v229, v31, v229
	v_mul_f32_e32 v214, v240, v214
	v_mul_f32_e32 v215, v241, v215
	v_mul_f32_e32 v216, v242, v216
	v_mul_f32_e32 v217, v243, v217
	v_mul_f32_e32 v218, v244, v218
	v_mul_f32_e32 v219, v245, v219
	v_mul_f32_e32 v220, v246, v220
	v_mul_f32_e32 v221, v247, v221
	v_mul_f32_e32 v222, v248, v222
	v_mul_f32_e32 v223, v249, v223
	v_mul_f32_e32 v224, v250, v224
	v_mul_f32_e32 v225, v251, v225
	v_mul_f32_e32 v226, v252, v226
	v_mul_f32_e32 v227, v253, v227
	v_mul_f32_e32 v228, v254, v228
	v_mul_f32_e32 v229, v255, v229
	v_cvt_pk_bf16_f32 v144, v214, v215
	v_cvt_pk_bf16_f32 v145, v216, v217
	v_cvt_pk_bf16_f32 v146, v218, v219
	v_cvt_pk_bf16_f32 v147, v220, v221
	v_cvt_pk_bf16_f32 v148, v222, v223
	v_cvt_pk_bf16_f32 v149, v224, v225
	v_cvt_pk_bf16_f32 v150, v226, v227
	v_cvt_pk_bf16_f32 v151, v228, v229
	s_mul_i32 s9, s46, 2
	s_add_i32 s9, s9, s8
	s_lshl_b32 s3, s9, 11
	s_add_u32 s24, s16, s3
	s_addc_u32 s25, s17, 0
	global_store_dwordx4 v2, v[144:147], s[24:25]
	global_store_dwordx4 v2, v[148:151], s[24:25] offset:16
	s_waitcnt vmcnt(22)
; DI unsigned pk_bf16(float a, float b) { f32x2 v = {a, b}; bf2_t r = __builtin_convertvector(v, bf2_t); return __builtin_bit_cast(unsigned, r); }
; DI float bflo(unsigned u) { return __uint_as_float(u << 16); }
; DI float bfhi(unsigned u) { return __uint_as_float(u & 0xffff0000u); }
; DI float silu_f(float x) { return x * __builtin_amdgcn_rcpf(1.f + __expf(-x)); }
; DI void phase_gdn_gate(const Params& p) {
;     ...
;         const u32x4 a0 = *(const u32x4*)(oraw + (size_t)tok * 1024 + 16 * lane), a1 = *(const u32x4*)(oraw + (size_t)tok * 1024 + 16 * lane + 8);
;         const u32x4 z0 = *(const u32x4*)(P0 + (size_t)tok * LDP0 + 3072 + 16 * lane), z1 = *(const u32x4*)(P0 + (size_t)tok * LDP0 + 3072 + 16 * lane + 8);
;         float o[16], z[16];
;         const unsigned au[8] = {a0.x, a0.y, a0.z, a0.w, a1.x, a1.y, a1.z, a1.w}, zu[8] = {z0.x, z0.y, z0.z, z0.w, z1.x, z1.y, z1.z, z1.w};
;         float ss = 0.f;
; #pragma unroll
;         for (int i = 0; i < 8; ++i) { o[2 * i] = bflo(au[i]); o[2 * i + 1] = bfhi(au[i]); z[2 * i] = bflo(zu[i]); z[2 * i + 1] = bfhi(zu[i]); ss += o[2 * i] * o[2 * i] + o[2 * i + 1] * o[2 * i + 1]; }
;         ss += __shfl_xor(ss, 1); ss += __shfl_xor(ss, 2); ss += __shfl_xor(ss, 4);
;         const float rstd = rsqrtf(ss * (1.f / 128.f) + 1e-6f);
;         const int d0 = (16 * lane) & 127;
;         unsigned r[8];
; #pragma unroll
;         for (int i = 0; i < 8; ++i) { const float v0 = o[2 * i] * rstd * p.onorm_a[d0 + 2 * i] * silu_f(z[2 * i]), v1 = o[2 * i + 1] * rstd * p.onorm_a[d0 + 2 * i + 1] * silu_f(z[2 * i + 1]); r[i] = pk_bf16(v0, v1); }
;         *(u32x4*)(og + (size_t)tok * 1024 + 16 * lane) = (u32x4){r[0], r[1], r[2], r[3]};
;         *(u32x4*)(og + (size_t)tok * 1024 + 16 * lane + 8) = (u32x4){r[4], r[5], r[6], r[7]};
	v_lshlrev_b32_e32 v214, 16, v80
	v_and_b32_e32 v215, 0xffff0000, v80
	v_lshlrev_b32_e32 v216, 16, v81
	v_and_b32_e32 v217, 0xffff0000, v81
	v_lshlrev_b32_e32 v218, 16, v82
	v_and_b32_e32 v219, 0xffff0000, v82
	v_lshlrev_b32_e32 v220, 16, v83
	v_and_b32_e32 v221, 0xffff0000, v83
	v_lshlrev_b32_e32 v222, 16, v84
	v_and_b32_e32 v223, 0xffff0000, v84
	v_lshlrev_b32_e32 v224, 16, v85
	v_and_b32_e32 v225, 0xffff0000, v85
	v_lshlrev_b32_e32 v226, 16, v86
	v_and_b32_e32 v227, 0xffff0000, v86
	v_lshlrev_b32_e32 v228, 16, v87
	v_and_b32_e32 v229, 0xffff0000, v87
	v_mul_f32_e32 v144, v214, v214
	v_fmac_f32_e32 v144, v215, v215
	v_fmac_f32_e32 v144, v216, v216
	v_fmac_f32_e32 v144, v217, v217
	v_fmac_f32_e32 v144, v218, v218
	v_fmac_f32_e32 v144, v219, v219
	v_fmac_f32_e32 v144, v220, v220
	v_fmac_f32_e32 v144, v221, v221
	v_mul_f32_e32 v145, v222, v222
	v_fmac_f32_e32 v145, v223, v223
	v_fmac_f32_e32 v145, v224, v224
	v_fmac_f32_e32 v145, v225, v225
	v_fmac_f32_e32 v145, v226, v226
	v_fmac_f32_e32 v145, v227, v227
	v_fmac_f32_e32 v145, v228, v228
	v_fmac_f32_e32 v145, v229, v229
	v_add_f32_e32 v144, v144, v145
	v_lshlrev_b32_e32 v240, 16, v88
	v_and_b32_e32 v241, 0xffff0000, v88
	v_lshlrev_b32_e32 v242, 16, v89
	v_and_b32_e32 v243, 0xffff0000, v89
	v_lshlrev_b32_e32 v244, 16, v90
	v_and_b32_e32 v245, 0xffff0000, v90
	v_lshlrev_b32_e32 v246, 16, v91
	v_and_b32_e32 v247, 0xffff0000, v91
	v_lshlrev_b32_e32 v248, 16, v92
	v_and_b32_e32 v249, 0xffff0000, v92
	v_lshlrev_b32_e32 v250, 16, v93
	v_and_b32_e32 v251, 0xffff0000, v93
	v_lshlrev_b32_e32 v252, 16, v94
	v_and_b32_e32 v253, 0xffff0000, v94
	v_lshlrev_b32_e32 v254, 16, v95
	v_and_b32_e32 v255, 0xffff0000, v95
	s_nop 1
	v_add_f32_dpp v144, v144, v144 quad_perm:[1,0,3,2] row_mask:0xf bank_mask:0xf
	s_nop 1
	v_add_f32_dpp v144, v144, v144 quad_perm:[2,3,0,1] row_mask:0xf bank_mask:0xf
	s_nop 1
	v_add_f32_dpp v144, v144, v144 row_half_mirror row_mask:0xf bank_mask:0xf
	v_fmamk_f32 v144, v144, 0x3c000000, v15
	v_rsq_f32_e32 v144, v144
	v_mul_f32_e32 v148, 0xbfb8aa3b, v240
	v_mul_f32_e32 v149, 0xbfb8aa3b, v241
	v_mul_f32_e32 v150, 0xbfb8aa3b, v242
	v_mul_f32_e32 v151, 0xbfb8aa3b, v243
	v_mul_f32_e32 v4, 0xbfb8aa3b, v244
	v_mul_f32_e32 v5, 0xbfb8aa3b, v245
	v_mul_f32_e32 v6, 0xbfb8aa3b, v246
	v_mul_f32_e32 v7, 0xbfb8aa3b, v247
	v_exp_f32_e32 v148, v148
	v_exp_f32_e32 v149, v149
	v_exp_f32_e32 v150, v150
	v_exp_f32_e32 v151, v151
	v_exp_f32_e32 v4, v4
	v_exp_f32_e32 v5, v5
	v_exp_f32_e32 v6, v6
	v_exp_f32_e32 v7, v7
	v_add_f32_e32 v148, 1.0, v148
	v_add_f32_e32 v149, 1.0, v149
	v_add_f32_e32 v150, 1.0, v150
	v_add_f32_e32 v151, 1.0, v151
	v_add_f32_e32 v4, 1.0, v4
	v_add_f32_e32 v5, 1.0, v5
	v_add_f32_e32 v6, 1.0, v6
	v_add_f32_e32 v7, 1.0, v7
	v_rcp_f32_e32 v148, v148
	v_rcp_f32_e32 v149, v149
	v_rcp_f32_e32 v150, v150
	v_rcp_f32_e32 v151, v151
	v_rcp_f32_e32 v4, v4
	v_rcp_f32_e32 v5, v5
	v_rcp_f32_e32 v6, v6
	v_rcp_f32_e32 v7, v7
	v_mul_f32_e32 v240, v148, v240
	v_mul_f32_e32 v241, v149, v241
	v_mul_f32_e32 v242, v150, v242
	v_mul_f32_e32 v243, v151, v243
	v_mul_f32_e32 v244, v4, v244
	v_mul_f32_e32 v245, v5, v245
	v_mul_f32_e32 v246, v6, v246
	v_mul_f32_e32 v247, v7, v247
	v_mul_f32_e32 v148, 0xbfb8aa3b, v248
	v_mul_f32_e32 v149, 0xbfb8aa3b, v249
	v_mul_f32_e32 v150, 0xbfb8aa3b, v250
	v_mul_f32_e32 v151, 0xbfb8aa3b, v251
	v_mul_f32_e32 v4, 0xbfb8aa3b, v252
	v_mul_f32_e32 v5, 0xbfb8aa3b, v253
	v_mul_f32_e32 v6, 0xbfb8aa3b, v254
	v_mul_f32_e32 v7, 0xbfb8aa3b, v255
	v_exp_f32_e32 v148, v148
	v_exp_f32_e32 v149, v149
	v_exp_f32_e32 v150, v150
	v_exp_f32_e32 v151, v151
	v_exp_f32_e32 v4, v4
	v_exp_f32_e32 v5, v5
	v_exp_f32_e32 v6, v6
	v_exp_f32_e32 v7, v7
	v_add_f32_e32 v148, 1.0, v148
	v_add_f32_e32 v149, 1.0, v149
	v_add_f32_e32 v150, 1.0, v150
	v_add_f32_e32 v151, 1.0, v151
	v_add_f32_e32 v4, 1.0, v4
	v_add_f32_e32 v5, 1.0, v5
	v_add_f32_e32 v6, 1.0, v6
	v_add_f32_e32 v7, 1.0, v7
	v_rcp_f32_e32 v148, v148
	v_rcp_f32_e32 v149, v149
	v_rcp_f32_e32 v150, v150
	v_rcp_f32_e32 v151, v151
	v_rcp_f32_e32 v4, v4
	v_rcp_f32_e32 v5, v5
	v_rcp_f32_e32 v6, v6
	v_rcp_f32_e32 v7, v7
	v_mul_f32_e32 v248, v148, v248
	v_mul_f32_e32 v249, v149, v249
	v_mul_f32_e32 v250, v150, v250
	v_mul_f32_e32 v251, v151, v251
	v_mul_f32_e32 v252, v4, v252
	v_mul_f32_e32 v253, v5, v253
	v_mul_f32_e32 v254, v6, v254
	v_mul_f32_e32 v255, v7, v255
	v_mul_f32_e32 v214, v144, v214
	v_mul_f32_e32 v215, v144, v215
	v_mul_f32_e32 v216, v144, v216
	v_mul_f32_e32 v217, v144, v217
	v_mul_f32_e32 v218, v144, v218
	v_mul_f32_e32 v219, v144, v219
	v_mul_f32_e32 v220, v144, v220
	v_mul_f32_e32 v221, v144, v221
	v_mul_f32_e32 v222, v144, v222
	v_mul_f32_e32 v223, v144, v223
	v_mul_f32_e32 v224, v144, v224
	v_mul_f32_e32 v225, v144, v225
	v_mul_f32_e32 v226, v144, v226
	v_mul_f32_e32 v227, v144, v227
	v_mul_f32_e32 v228, v144, v228
	v_mul_f32_e32 v229, v144, v229
	v_mul_f32_e32 v214, v16, v214
	v_mul_f32_e32 v215, v17, v215
	v_mul_f32_e32 v216, v18, v216
	v_mul_f32_e32 v217, v19, v217
	v_mul_f32_e32 v218, v20, v218
	v_mul_f32_e32 v219, v21, v219
	v_mul_f32_e32 v220, v22, v220
	v_mul_f32_e32 v221, v23, v221
	v_mul_f32_e32 v222, v24, v222
	v_mul_f32_e32 v223, v25, v223
	v_mul_f32_e32 v224, v26, v224
	v_mul_f32_e32 v225, v27, v225
	v_mul_f32_e32 v226, v28, v226
	v_mul_f32_e32 v227, v29, v227
	v_mul_f32_e32 v228, v30, v228
	v_mul_f32_e32 v229, v31, v229
	v_mul_f32_e32 v214, v240, v214
	v_mul_f32_e32 v215, v241, v215
	v_mul_f32_e32 v216, v242, v216
	v_mul_f32_e32 v217, v243, v217
	v_mul_f32_e32 v218, v244, v218
	v_mul_f32_e32 v219, v245, v219
	v_mul_f32_e32 v220, v246, v220
	v_mul_f32_e32 v221, v247, v221
	v_mul_f32_e32 v222, v248, v222
	v_mul_f32_e32 v223, v249, v223
	v_mul_f32_e32 v224, v250, v224
	v_mul_f32_e32 v225, v251, v225
	v_mul_f32_e32 v226, v252, v226
	v_mul_f32_e32 v227, v253, v227
	v_mul_f32_e32 v228, v254, v228
	v_mul_f32_e32 v229, v255, v229
	v_cvt_pk_bf16_f32 v144, v214, v215
	v_cvt_pk_bf16_f32 v145, v216, v217
	v_cvt_pk_bf16_f32 v146, v218, v219
	v_cvt_pk_bf16_f32 v147, v220, v221
	v_cvt_pk_bf16_f32 v148, v222, v223
	v_cvt_pk_bf16_f32 v149, v224, v225
	v_cvt_pk_bf16_f32 v150, v226, v227
	v_cvt_pk_bf16_f32 v151, v228, v229
	s_mul_i32 s9, s46, 3
	s_add_i32 s9, s9, s8
	s_lshl_b32 s3, s9, 11
	s_add_u32 s24, s16, s3
	s_addc_u32 s25, s17, 0
	global_store_dwordx4 v2, v[144:147], s[24:25]
	global_store_dwordx4 v2, v[148:151], s[24:25] offset:16
	s_waitcnt vmcnt(20)
; DI unsigned pk_bf16(float a, float b) { f32x2 v = {a, b}; bf2_t r = __builtin_convertvector(v, bf2_t); return __builtin_bit_cast(unsigned, r); }
; DI float bflo(unsigned u) { return __uint_as_float(u << 16); }
; DI float bfhi(unsigned u) { return __uint_as_float(u & 0xffff0000u); }
; DI float silu_f(float x) { return x * __builtin_amdgcn_rcpf(1.f + __expf(-x)); }
; DI void phase_gdn_gate(const Params& p) {
;     ...
;         const u32x4 a0 = *(const u32x4*)(oraw + (size_t)tok * 1024 + 16 * lane), a1 = *(const u32x4*)(oraw + (size_t)tok * 1024 + 16 * lane + 8);
;         const u32x4 z0 = *(const u32x4*)(P0 + (size_t)tok * LDP0 + 3072 + 16 * lane), z1 = *(const u32x4*)(P0 + (size_t)tok * LDP0 + 3072 + 16 * lane + 8);
;         float o[16], z[16];
;         const unsigned au[8] = {a0.x, a0.y, a0.z, a0.w, a1.x, a1.y, a1.z, a1.w}, zu[8] = {z0.x, z0.y, z0.z, z0.w, z1.x, z1.y, z1.z, z1.w};
;         float ss = 0.f;
; #pragma unroll
;         for (int i = 0; i < 8; ++i) { o[2 * i] = bflo(au[i]); o[2 * i + 1] = bfhi(au[i]); z[2 * i] = bflo(zu[i]); z[2 * i + 1] = bfhi(zu[i]); ss += o[2 * i] * o[2 * i] + o[2 * i + 1] * o[2 * i + 1]; }
;         ss += __shfl_xor(ss, 1); ss += __shfl_xor(ss, 2); ss += __shfl_xor(ss, 4);
;         const float rstd = rsqrtf(ss * (1.f / 128.f) + 1e-6f);
;         const int d0 = (16 * lane) & 127;
;         unsigned r[8];
; #pragma unroll
;         for (int i = 0; i < 8; ++i) { const float v0 = o[2 * i] * rstd * p.onorm_a[d0 + 2 * i] * silu_f(z[2 * i]), v1 = o[2 * i + 1] * rstd * p.onorm_a[d0 + 2 * i + 1] * silu_f(z[2 * i + 1]); r[i] = pk_bf16(v0, v1); }
;         *(u32x4*)(og + (size_t)tok * 1024 + 16 * lane) = (u32x4){r[0], r[1], r[2], r[3]};
;         *(u32x4*)(og + (size_t)tok * 1024 + 16 * lane + 8) = (u32x4){r[4], r[5], r[6], r[7]};
	v_lshlrev_b32_e32 v214, 16, v96
	v_and_b32_e32 v215, 0xffff0000, v96
	v_lshlrev_b32_e32 v216, 16, v97
	v_and_b32_e32 v217, 0xffff0000, v97
	v_lshlrev_b32_e32 v218, 16, v98
	v_and_b32_e32 v219, 0xffff0000, v98
	v_lshlrev_b32_e32 v220, 16, v99
	v_and_b32_e32 v221, 0xffff0000, v99
	v_lshlrev_b32_e32 v222, 16, v100
	v_and_b32_e32 v223, 0xffff0000, v100
	v_lshlrev_b32_e32 v224, 16, v101
	v_and_b32_e32 v225, 0xffff0000, v101
	v_lshlrev_b32_e32 v226, 16, v102
	v_and_b32_e32 v227, 0xffff0000, v102
	v_lshlrev_b32_e32 v228, 16, v103
	v_and_b32_e32 v229, 0xffff0000, v103
	v_mul_f32_e32 v144, v214, v214
	v_fmac_f32_e32 v144, v215, v215
	v_fmac_f32_e32 v144, v216, v216
	v_fmac_f32_e32 v144, v217, v217
	v_fmac_f32_e32 v144, v218, v218
	v_fmac_f32_e32 v144, v219, v219
	v_fmac_f32_e32 v144, v220, v220
	v_fmac_f32_e32 v144, v221, v221
	v_mul_f32_e32 v145, v222, v222
	v_fmac_f32_e32 v145, v223, v223
	v_fmac_f32_e32 v145, v224, v224
	v_fmac_f32_e32 v145, v225, v225
	v_fmac_f32_e32 v145, v226, v226
	v_fmac_f32_e32 v145, v227, v227
	v_fmac_f32_e32 v145, v228, v228
	v_fmac_f32_e32 v145, v229, v229
	v_add_f32_e32 v144, v144, v145
	v_lshlrev_b32_e32 v240, 16, v104
	v_and_b32_e32 v241, 0xffff0000, v104
	v_lshlrev_b32_e32 v242, 16, v105
	v_and_b32_e32 v243, 0xffff0000, v105
	v_lshlrev_b32_e32 v244, 16, v106
	v_and_b32_e32 v245, 0xffff0000, v106
	v_lshlrev_b32_e32 v246, 16, v107
	v_and_b32_e32 v247, 0xffff0000, v107
	v_lshlrev_b32_e32 v248, 16, v108
	v_and_b32_e32 v249, 0xffff0000, v108
	v_lshlrev_b32_e32 v250, 16, v109
	v_and_b32_e32 v251, 0xffff0000, v109
	v_lshlrev_b32_e32 v252, 16, v110
	v_and_b32_e32 v253, 0xffff0000, v110
	v_lshlrev_b32_e32 v254, 16, v111
	v_and_b32_e32 v255, 0xffff0000, v111
	s_nop 1
	v_add_f32_dpp v144, v144, v144 quad_perm:[1,0,3,2] row_mask:0xf bank_mask:0xf
	s_nop 1
	v_add_f32_dpp v144, v144, v144 quad_perm:[2,3,0,1] row_mask:0xf bank_mask:0xf
	s_nop 1
	v_add_f32_dpp v144, v144, v144 row_half_mirror row_mask:0xf bank_mask:0xf
	v_fmamk_f32 v144, v144, 0x3c000000, v15
	v_rsq_f32_e32 v144, v144
	v_mul_f32_e32 v148, 0xbfb8aa3b, v240
	v_mul_f32_e32 v149, 0xbfb8aa3b, v241
	v_mul_f32_e32 v150, 0xbfb8aa3b, v242
	v_mul_f32_e32 v151, 0xbfb8aa3b, v243
	v_mul_f32_e32 v4, 0xbfb8aa3b, v244
	v_mul_f32_e32 v5, 0xbfb8aa3b, v245
	v_mul_f32_e32 v6, 0xbfb8aa3b, v246
	v_mul_f32_e32 v7, 0xbfb8aa3b, v247
	v_exp_f32_e32 v148, v148
	v_exp_f32_e32 v149, v149
	v_exp_f32_e32 v150, v150
	v_exp_f32_e32 v151, v151
	v_exp_f32_e32 v4, v4
	v_exp_f32_e32 v5, v5
	v_exp_f32_e32 v6, v6
	v_exp_f32_e32 v7, v7
	v_add_f32_e32 v148, 1.0, v148
	v_add_f32_e32 v149, 1.0, v149
	v_add_f32_e32 v150, 1.0, v150
	v_add_f32_e32 v151, 1.0, v151
	v_add_f32_e32 v4, 1.0, v4
	v_add_f32_e32 v5, 1.0, v5
	v_add_f32_e32 v6, 1.0, v6
	v_add_f32_e32 v7, 1.0, v7
	v_rcp_f32_e32 v148, v148
	v_rcp_f32_e32 v149, v149
	v_rcp_f32_e32 v150, v150
	v_rcp_f32_e32 v151, v151
	v_rcp_f32_e32 v4, v4
	v_rcp_f32_e32 v5, v5
	v_rcp_f32_e32 v6, v6
	v_rcp_f32_e32 v7, v7
	v_mul_f32_e32 v240, v148, v240
	v_mul_f32_e32 v241, v149, v241
	v_mul_f32_e32 v242, v150, v242
	v_mul_f32_e32 v243, v151, v243
	v_mul_f32_e32 v244, v4, v244
	v_mul_f32_e32 v245, v5, v245
	v_mul_f32_e32 v246, v6, v246
	v_mul_f32_e32 v247, v7, v247
	v_mul_f32_e32 v148, 0xbfb8aa3b, v248
	v_mul_f32_e32 v149, 0xbfb8aa3b, v249
	v_mul_f32_e32 v150, 0xbfb8aa3b, v250
	v_mul_f32_e32 v151, 0xbfb8aa3b, v251
	v_mul_f32_e32 v4, 0xbfb8aa3b, v252
	v_mul_f32_e32 v5, 0xbfb8aa3b, v253
	v_mul_f32_e32 v6, 0xbfb8aa3b, v254
	v_mul_f32_e32 v7, 0xbfb8aa3b, v255
	v_exp_f32_e32 v148, v148
	v_exp_f32_e32 v149, v149
	v_exp_f32_e32 v150, v150
	v_exp_f32_e32 v151, v151
	v_exp_f32_e32 v4, v4
	v_exp_f32_e32 v5, v5
	v_exp_f32_e32 v6, v6
	v_exp_f32_e32 v7, v7
	v_add_f32_e32 v148, 1.0, v148
	v_add_f32_e32 v149, 1.0, v149
	v_add_f32_e32 v150, 1.0, v150
	v_add_f32_e32 v151, 1.0, v151
	v_add_f32_e32 v4, 1.0, v4
	v_add_f32_e32 v5, 1.0, v5
	v_add_f32_e32 v6, 1.0, v6
	v_add_f32_e32 v7, 1.0, v7
	v_rcp_f32_e32 v148, v148
	v_rcp_f32_e32 v149, v149
	v_rcp_f32_e32 v150, v150
	v_rcp_f32_e32 v151, v151
	v_rcp_f32_e32 v4, v4
	v_rcp_f32_e32 v5, v5
	v_rcp_f32_e32 v6, v6
	v_rcp_f32_e32 v7, v7
	v_mul_f32_e32 v248, v148, v248
	v_mul_f32_e32 v249, v149, v249
	v_mul_f32_e32 v250, v150, v250
	v_mul_f32_e32 v251, v151, v251
	v_mul_f32_e32 v252, v4, v252
	v_mul_f32_e32 v253, v5, v253
	v_mul_f32_e32 v254, v6, v254
	v_mul_f32_e32 v255, v7, v255
	v_mul_f32_e32 v214, v144, v214
	v_mul_f32_e32 v215, v144, v215
	v_mul_f32_e32 v216, v144, v216
	v_mul_f32_e32 v217, v144, v217
	v_mul_f32_e32 v218, v144, v218
	v_mul_f32_e32 v219, v144, v219
	v_mul_f32_e32 v220, v144, v220
	v_mul_f32_e32 v221, v144, v221
	v_mul_f32_e32 v222, v144, v222
	v_mul_f32_e32 v223, v144, v223
	v_mul_f32_e32 v224, v144, v224
	v_mul_f32_e32 v225, v144, v225
	v_mul_f32_e32 v226, v144, v226
	v_mul_f32_e32 v227, v144, v227
	v_mul_f32_e32 v228, v144, v228
	v_mul_f32_e32 v229, v144, v229
	v_mul_f32_e32 v214, v16, v214
	v_mul_f32_e32 v215, v17, v215
	v_mul_f32_e32 v216, v18, v216
	v_mul_f32_e32 v217, v19, v217
	v_mul_f32_e32 v218, v20, v218
	v_mul_f32_e32 v219, v21, v219
	v_mul_f32_e32 v220, v22, v220
	v_mul_f32_e32 v221, v23, v221
	v_mul_f32_e32 v222, v24, v222
	v_mul_f32_e32 v223, v25, v223
	v_mul_f32_e32 v224, v26, v224
	v_mul_f32_e32 v225, v27, v225
	v_mul_f32_e32 v226, v28, v226
	v_mul_f32_e32 v227, v29, v227
	v_mul_f32_e32 v228, v30, v228
	v_mul_f32_e32 v229, v31, v229
	v_mul_f32_e32 v214, v240, v214
	v_mul_f32_e32 v215, v241, v215
	v_mul_f32_e32 v216, v242, v216
	v_mul_f32_e32 v217, v243, v217
	v_mul_f32_e32 v218, v244, v218
	v_mul_f32_e32 v219, v245, v219
	v_mul_f32_e32 v220, v246, v220
	v_mul_f32_e32 v221, v247, v221
	v_mul_f32_e32 v222, v248, v222
	v_mul_f32_e32 v223, v249, v223
	v_mul_f32_e32 v224, v250, v224
	v_mul_f32_e32 v225, v251, v225
	v_mul_f32_e32 v226, v252, v226
	v_mul_f32_e32 v227, v253, v227
	v_mul_f32_e32 v228, v254, v228
	v_mul_f32_e32 v229, v255, v229
	v_cvt_pk_bf16_f32 v144, v214, v215
	v_cvt_pk_bf16_f32 v145, v216, v217
	v_cvt_pk_bf16_f32 v146, v218, v219
	v_cvt_pk_bf16_f32 v147, v220, v221
	v_cvt_pk_bf16_f32 v148, v222, v223
	v_cvt_pk_bf16_f32 v149, v224, v225
	v_cvt_pk_bf16_f32 v150, v226, v227
	v_cvt_pk_bf16_f32 v151, v228, v229
	s_mul_i32 s9, s46, 4
	s_add_i32 s9, s9, s8
	s_lshl_b32 s3, s9, 11
	s_add_u32 s24, s16, s3
	s_addc_u32 s25, s17, 0
	global_store_dwordx4 v2, v[144:147], s[24:25]
	global_store_dwordx4 v2, v[148:151], s[24:25] offset:16
	s_waitcnt vmcnt(18)
; DI unsigned pk_bf16(float a, float b) { f32x2 v = {a, b}; bf2_t r = __builtin_convertvector(v, bf2_t); return __builtin_bit_cast(unsigned, r); }
; DI float bflo(unsigned u) { return __uint_as_float(u << 16); }
; DI float bfhi(unsigned u) { return __uint_as_float(u & 0xffff0000u); }
; DI float silu_f(float x) { return x * __builtin_amdgcn_rcpf(1.f + __expf(-x)); }
; DI void phase_gdn_gate(const Params& p) {
;     ...
;         const u32x4 a0 = *(const u32x4*)(oraw + (size_t)tok * 1024 + 16 * lane), a1 = *(const u32x4*)(oraw + (size_t)tok * 1024 + 16 * lane + 8);
;         const u32x4 z0 = *(const u32x4*)(P0 + (size_t)tok * LDP0 + 3072 + 16 * lane), z1 = *(const u32x4*)(P0 + (size_t)tok * LDP0 + 3072 + 16 * lane + 8);
;         float o[16], z[16];
;         const unsigned au[8] = {a0.x, a0.y, a0.z, a0.w, a1.x, a1.y, a1.z, a1.w}, zu[8] = {z0.x, z0.y, z0.z, z0.w, z1.x, z1.y, z1.z, z1.w};
;         float ss = 0.f;
; #pragma unroll
;         for (int i = 0; i < 8; ++i) { o[2 * i] = bflo(au[i]); o[2 * i + 1] = bfhi(au[i]); z[2 * i] = bflo(zu[i]); z[2 * i + 1] = bfhi(zu[i]); ss += o[2 * i] * o[2 * i] + o[2 * i + 1] * o[2 * i + 1]; }
;         ss += __shfl_xor(ss, 1); ss += __shfl_xor(ss, 2); ss += __shfl_xor(ss, 4);
;         const float rstd = rsqrtf(ss * (1.f / 128.f) + 1e-6f);
;         const int d0 = (16 * lane) & 127;
;         unsigned r[8];
; #pragma unroll
;         for (int i = 0; i < 8; ++i) { const float v0 = o[2 * i] * rstd * p.onorm_a[d0 + 2 * i] * silu_f(z[2 * i]), v1 = o[2 * i + 1] * rstd * p.onorm_a[d0 + 2 * i + 1] * silu_f(z[2 * i + 1]); r[i] = pk_bf16(v0, v1); }
;         *(u32x4*)(og + (size_t)tok * 1024 + 16 * lane) = (u32x4){r[0], r[1], r[2], r[3]};
;         *(u32x4*)(og + (size_t)tok * 1024 + 16 * lane + 8) = (u32x4){r[4], r[5], r[6], r[7]};
	v_lshlrev_b32_e32 v214, 16, v112
	v_and_b32_e32 v215, 0xffff0000, v112
	v_lshlrev_b32_e32 v216, 16, v113
	v_and_b32_e32 v217, 0xffff0000, v113
	v_lshlrev_b32_e32 v218, 16, v114
	v_and_b32_e32 v219, 0xffff0000, v114
	v_lshlrev_b32_e32 v220, 16, v115
	v_and_b32_e32 v221, 0xffff0000, v115
	v_lshlrev_b32_e32 v222, 16, v116
	v_and_b32_e32 v223, 0xffff0000, v116
	v_lshlrev_b32_e32 v224, 16, v117
	v_and_b32_e32 v225, 0xffff0000, v117
	v_lshlrev_b32_e32 v226, 16, v118
	v_and_b32_e32 v227, 0xffff0000, v118
	v_lshlrev_b32_e32 v228, 16, v119
	v_and_b32_e32 v229, 0xffff0000, v119
	v_mul_f32_e32 v144, v214, v214
	v_fmac_f32_e32 v144, v215, v215
	v_fmac_f32_e32 v144, v216, v216
	v_fmac_f32_e32 v144, v217, v217
	v_fmac_f32_e32 v144, v218, v218
	v_fmac_f32_e32 v144, v219, v219
	v_fmac_f32_e32 v144, v220, v220
	v_fmac_f32_e32 v144, v221, v221
	v_mul_f32_e32 v145, v222, v222
	v_fmac_f32_e32 v145, v223, v223
	v_fmac_f32_e32 v145, v224, v224
	v_fmac_f32_e32 v145, v225, v225
	v_fmac_f32_e32 v145, v226, v226
	v_fmac_f32_e32 v145, v227, v227
	v_fmac_f32_e32 v145, v228, v228
	v_fmac_f32_e32 v145, v229, v229
	v_add_f32_e32 v144, v144, v145
	v_lshlrev_b32_e32 v240, 16, v120
	v_and_b32_e32 v241, 0xffff0000, v120
	v_lshlrev_b32_e32 v242, 16, v121
	v_and_b32_e32 v243, 0xffff0000, v121
	v_lshlrev_b32_e32 v244, 16, v122
	v_and_b32_e32 v245, 0xffff0000, v122
	v_lshlrev_b32_e32 v246, 16, v123
	v_and_b32_e32 v247, 0xffff0000, v123
	v_lshlrev_b32_e32 v248, 16, v124
	v_and_b32_e32 v249, 0xffff0000, v124
	v_lshlrev_b32_e32 v250, 16, v125
	v_and_b32_e32 v251, 0xffff0000, v125
	v_lshlrev_b32_e32 v252, 16, v126
	v_and_b32_e32 v253, 0xffff0000, v126
	v_lshlrev_b32_e32 v254, 16, v127
	v_and_b32_e32 v255, 0xffff0000, v127
	s_nop 1
	v_add_f32_dpp v144, v144, v144 quad_perm:[1,0,3,2] row_mask:0xf bank_mask:0xf
	s_nop 1
	v_add_f32_dpp v144, v144, v144 quad_perm:[2,3,0,1] row_mask:0xf bank_mask:0xf
	s_nop 1
	v_add_f32_dpp v144, v144, v144 row_half_mirror row_mask:0xf bank_mask:0xf
	v_fmamk_f32 v144, v144, 0x3c000000, v15
	v_rsq_f32_e32 v144, v144
	v_mul_f32_e32 v148, 0xbfb8aa3b, v240
	v_mul_f32_e32 v149, 0xbfb8aa3b, v241
	v_mul_f32_e32 v150, 0xbfb8aa3b, v242
	v_mul_f32_e32 v151, 0xbfb8aa3b, v243
	v_mul_f32_e32 v4, 0xbfb8aa3b, v244
	v_mul_f32_e32 v5, 0xbfb8aa3b, v245
	v_mul_f32_e32 v6, 0xbfb8aa3b, v246
	v_mul_f32_e32 v7, 0xbfb8aa3b, v247
	v_exp_f32_e32 v148, v148
	v_exp_f32_e32 v149, v149
	v_exp_f32_e32 v150, v150
	v_exp_f32_e32 v151, v151
	v_exp_f32_e32 v4, v4
	v_exp_f32_e32 v5, v5
	v_exp_f32_e32 v6, v6
	v_exp_f32_e32 v7, v7
	v_add_f32_e32 v148, 1.0, v148
	v_add_f32_e32 v149, 1.0, v149
	v_add_f32_e32 v150, 1.0, v150
	v_add_f32_e32 v151, 1.0, v151
	v_add_f32_e32 v4, 1.0, v4
	v_add_f32_e32 v5, 1.0, v5
	v_add_f32_e32 v6, 1.0, v6
	v_add_f32_e32 v7, 1.0, v7
	v_rcp_f32_e32 v148, v148
	v_rcp_f32_e32 v149, v149
	v_rcp_f32_e32 v150, v150
	v_rcp_f32_e32 v151, v151
	v_rcp_f32_e32 v4, v4
	v_rcp_f32_e32 v5, v5
	v_rcp_f32_e32 v6, v6
	v_rcp_f32_e32 v7, v7
	v_mul_f32_e32 v240, v148, v240
	v_mul_f32_e32 v241, v149, v241
	v_mul_f32_e32 v242, v150, v242
	v_mul_f32_e32 v243, v151, v243
	v_mul_f32_e32 v244, v4, v244
	v_mul_f32_e32 v245, v5, v245
	v_mul_f32_e32 v246, v6, v246
	v_mul_f32_e32 v247, v7, v247
	v_mul_f32_e32 v148, 0xbfb8aa3b, v248
	v_mul_f32_e32 v149, 0xbfb8aa3b, v249
	v_mul_f32_e32 v150, 0xbfb8aa3b, v250
	v_mul_f32_e32 v151, 0xbfb8aa3b, v251
	v_mul_f32_e32 v4, 0xbfb8aa3b, v252
	v_mul_f32_e32 v5, 0xbfb8aa3b, v253
	v_mul_f32_e32 v6, 0xbfb8aa3b, v254
	v_mul_f32_e32 v7, 0xbfb8aa3b, v255
	v_exp_f32_e32 v148, v148
	v_exp_f32_e32 v149, v149
	v_exp_f32_e32 v150, v150
	v_exp_f32_e32 v151, v151
	v_exp_f32_e32 v4, v4
	v_exp_f32_e32 v5, v5
	v_exp_f32_e32 v6, v6
	v_exp_f32_e32 v7, v7
	v_add_f32_e32 v148, 1.0, v148
	v_add_f32_e32 v149, 1.0, v149
	v_add_f32_e32 v150, 1.0, v150
	v_add_f32_e32 v151, 1.0, v151
	v_add_f32_e32 v4, 1.0, v4
	v_add_f32_e32 v5, 1.0, v5
	v_add_f32_e32 v6, 1.0, v6
	v_add_f32_e32 v7, 1.0, v7
	v_rcp_f32_e32 v148, v148
	v_rcp_f32_e32 v149, v149
	v_rcp_f32_e32 v150, v150
	v_rcp_f32_e32 v151, v151
	v_rcp_f32_e32 v4, v4
	v_rcp_f32_e32 v5, v5
	v_rcp_f32_e32 v6, v6
	v_rcp_f32_e32 v7, v7
	v_mul_f32_e32 v248, v148, v248
	v_mul_f32_e32 v249, v149, v249
	v_mul_f32_e32 v250, v150, v250
	v_mul_f32_e32 v251, v151, v251
	v_mul_f32_e32 v252, v4, v252
	v_mul_f32_e32 v253, v5, v253
	v_mul_f32_e32 v254, v6, v254
	v_mul_f32_e32 v255, v7, v255
	v_mul_f32_e32 v214, v144, v214
	v_mul_f32_e32 v215, v144, v215
	v_mul_f32_e32 v216, v144, v216
	v_mul_f32_e32 v217, v144, v217
	v_mul_f32_e32 v218, v144, v218
	v_mul_f32_e32 v219, v144, v219
	v_mul_f32_e32 v220, v144, v220
	v_mul_f32_e32 v221, v144, v221
	v_mul_f32_e32 v222, v144, v222
	v_mul_f32_e32 v223, v144, v223
	v_mul_f32_e32 v224, v144, v224
	v_mul_f32_e32 v225, v144, v225
	v_mul_f32_e32 v226, v144, v226
	v_mul_f32_e32 v227, v144, v227
	v_mul_f32_e32 v228, v144, v228
	v_mul_f32_e32 v229, v144, v229
	v_mul_f32_e32 v214, v16, v214
	v_mul_f32_e32 v215, v17, v215
	v_mul_f32_e32 v216, v18, v216
	v_mul_f32_e32 v217, v19, v217
	v_mul_f32_e32 v218, v20, v218
	v_mul_f32_e32 v219, v21, v219
	v_mul_f32_e32 v220, v22, v220
	v_mul_f32_e32 v221, v23, v221
	v_mul_f32_e32 v222, v24, v222
	v_mul_f32_e32 v223, v25, v223
	v_mul_f32_e32 v224, v26, v224
	v_mul_f32_e32 v225, v27, v225
	v_mul_f32_e32 v226, v28, v226
	v_mul_f32_e32 v227, v29, v227
	v_mul_f32_e32 v228, v30, v228
	v_mul_f32_e32 v229, v31, v229
	v_mul_f32_e32 v214, v240, v214
	v_mul_f32_e32 v215, v241, v215
	v_mul_f32_e32 v216, v242, v216
	v_mul_f32_e32 v217, v243, v217
	v_mul_f32_e32 v218, v244, v218
	v_mul_f32_e32 v219, v245, v219
	v_mul_f32_e32 v220, v246, v220
	v_mul_f32_e32 v221, v247, v221
	v_mul_f32_e32 v222, v248, v222
	v_mul_f32_e32 v223, v249, v223
	v_mul_f32_e32 v224, v250, v224
	v_mul_f32_e32 v225, v251, v225
	v_mul_f32_e32 v226, v252, v226
	v_mul_f32_e32 v227, v253, v227
	v_mul_f32_e32 v228, v254, v228
	v_mul_f32_e32 v229, v255, v229
	v_cvt_pk_bf16_f32 v144, v214, v215
	v_cvt_pk_bf16_f32 v145, v216, v217
	v_cvt_pk_bf16_f32 v146, v218, v219
	v_cvt_pk_bf16_f32 v147, v220, v221
	v_cvt_pk_bf16_f32 v148, v222, v223
	v_cvt_pk_bf16_f32 v149, v224, v225
	v_cvt_pk_bf16_f32 v150, v226, v227
	v_cvt_pk_bf16_f32 v151, v228, v229
	s_mul_i32 s9, s46, 5
	s_add_i32 s9, s9, s8
	s_lshl_b32 s3, s9, 11
	s_add_u32 s24, s16, s3
	s_addc_u32 s25, s17, 0
	global_store_dwordx4 v2, v[144:147], s[24:25]
	global_store_dwordx4 v2, v[148:151], s[24:25] offset:16
	s_waitcnt vmcnt(16)
; DI unsigned pk_bf16(float a, float b) { f32x2 v = {a, b}; bf2_t r = __builtin_convertvector(v, bf2_t); return __builtin_bit_cast(unsigned, r); }
; DI float bflo(unsigned u) { return __uint_as_float(u << 16); }
; DI float bfhi(unsigned u) { return __uint_as_float(u & 0xffff0000u); }
; DI float silu_f(float x) { return x * __builtin_amdgcn_rcpf(1.f + __expf(-x)); }
; DI void phase_gdn_gate(const Params& p) {
;     ...
;         const u32x4 a0 = *(const u32x4*)(oraw + (size_t)tok * 1024 + 16 * lane), a1 = *(const u32x4*)(oraw + (size_t)tok * 1024 + 16 * lane + 8);
;         const u32x4 z0 = *(const u32x4*)(P0 + (size_t)tok * LDP0 + 3072 + 16 * lane), z1 = *(const u32x4*)(P0 + (size_t)tok * LDP0 + 3072 + 16 * lane + 8);
;         float o[16], z[16];
;         const unsigned au[8] = {a0.x, a0.y, a0.z, a0.w, a1.x, a1.y, a1.z, a1.w}, zu[8] = {z0.x, z0.y, z0.z, z0.w, z1.x, z1.y, z1.z, z1.w};
;         float ss = 0.f;
; #pragma unroll
;         for (int i = 0; i < 8; ++i) { o[2 * i] = bflo(au[i]); o[2 * i + 1] = bfhi(au[i]); z[2 * i] = bflo(zu[i]); z[2 * i + 1] = bfhi(zu[i]); ss += o[2 * i] * o[2 * i] + o[2 * i + 1] * o[2 * i + 1]; }
;         ss += __shfl_xor(ss, 1); ss += __shfl_xor(ss, 2); ss += __shfl_xor(ss, 4);
;         const float rstd = rsqrtf(ss * (1.f / 128.f) + 1e-6f);
;         const int d0 = (16 * lane) & 127;
;         unsigned r[8];
; #pragma unroll
;         for (int i = 0; i < 8; ++i) { const float v0 = o[2 * i] * rstd * p.onorm_a[d0 + 2 * i] * silu_f(z[2 * i]), v1 = o[2 * i + 1] * rstd * p.onorm_a[d0 + 2 * i + 1] * silu_f(z[2 * i + 1]); r[i] = pk_bf16(v0, v1); }
;         *(u32x4*)(og + (size_t)tok * 1024 + 16 * lane) = (u32x4){r[0], r[1], r[2], r[3]};
;         *(u32x4*)(og + (size_t)tok * 1024 + 16 * lane + 8) = (u32x4){r[4], r[5], r[6], r[7]};
	v_lshlrev_b32_e32 v214, 16, v128
	v_and_b32_e32 v215, 0xffff0000, v128
	v_lshlrev_b32_e32 v216, 16, v129
	v_and_b32_e32 v217, 0xffff0000, v129
	v_lshlrev_b32_e32 v218, 16, v130
	v_and_b32_e32 v219, 0xffff0000, v130
	v_lshlrev_b32_e32 v220, 16, v131
	v_and_b32_e32 v221, 0xffff0000, v131
	v_lshlrev_b32_e32 v222, 16, v132
	v_and_b32_e32 v223, 0xffff0000, v132
	v_lshlrev_b32_e32 v224, 16, v133
	v_and_b32_e32 v225, 0xffff0000, v133
	v_lshlrev_b32_e32 v226, 16, v134
	v_and_b32_e32 v227, 0xffff0000, v134
	v_lshlrev_b32_e32 v228, 16, v135
	v_and_b32_e32 v229, 0xffff0000, v135
	v_mul_f32_e32 v144, v214, v214
	v_fmac_f32_e32 v144, v215, v215
	v_fmac_f32_e32 v144, v216, v216
	v_fmac_f32_e32 v144, v217, v217
	v_fmac_f32_e32 v144, v218, v218
	v_fmac_f32_e32 v144, v219, v219
	v_fmac_f32_e32 v144, v220, v220
	v_fmac_f32_e32 v144, v221, v221
	v_mul_f32_e32 v145, v222, v222
	v_fmac_f32_e32 v145, v223, v223
	v_fmac_f32_e32 v145, v224, v224
	v_fmac_f32_e32 v145, v225, v225
	v_fmac_f32_e32 v145, v226, v226
	v_fmac_f32_e32 v145, v227, v227
	v_fmac_f32_e32 v145, v228, v228
	v_fmac_f32_e32 v145, v229, v229
	v_add_f32_e32 v144, v144, v145
	v_lshlrev_b32_e32 v240, 16, v136
	v_and_b32_e32 v241, 0xffff0000, v136
	v_lshlrev_b32_e32 v242, 16, v137
	v_and_b32_e32 v243, 0xffff0000, v137
	v_lshlrev_b32_e32 v244, 16, v138
	v_and_b32_e32 v245, 0xffff0000, v138
	v_lshlrev_b32_e32 v246, 16, v139
	v_and_b32_e32 v247, 0xffff0000, v139
	v_lshlrev_b32_e32 v248, 16, v140
	v_and_b32_e32 v249, 0xffff0000, v140
	v_lshlrev_b32_e32 v250, 16, v141
	v_and_b32_e32 v251, 0xffff0000, v141
	v_lshlrev_b32_e32 v252, 16, v142
	v_and_b32_e32 v253, 0xffff0000, v142
	v_lshlrev_b32_e32 v254, 16, v143
	v_and_b32_e32 v255, 0xffff0000, v143
	s_nop 1
	v_add_f32_dpp v144, v144, v144 quad_perm:[1,0,3,2] row_mask:0xf bank_mask:0xf
	s_nop 1
	v_add_f32_dpp v144, v144, v144 quad_perm:[2,3,0,1] row_mask:0xf bank_mask:0xf
	s_nop 1
	v_add_f32_dpp v144, v144, v144 row_half_mirror row_mask:0xf bank_mask:0xf
	v_fmamk_f32 v144, v144, 0x3c000000, v15
	v_rsq_f32_e32 v144, v144
	v_mul_f32_e32 v148, 0xbfb8aa3b, v240
	v_mul_f32_e32 v149, 0xbfb8aa3b, v241
	v_mul_f32_e32 v150, 0xbfb8aa3b, v242
	v_mul_f32_e32 v151, 0xbfb8aa3b, v243
	v_mul_f32_e32 v4, 0xbfb8aa3b, v244
	v_mul_f32_e32 v5, 0xbfb8aa3b, v245
	v_mul_f32_e32 v6, 0xbfb8aa3b, v246
	v_mul_f32_e32 v7, 0xbfb8aa3b, v247
	v_exp_f32_e32 v148, v148
	v_exp_f32_e32 v149, v149
	v_exp_f32_e32 v150, v150
	v_exp_f32_e32 v151, v151
	v_exp_f32_e32 v4, v4
	v_exp_f32_e32 v5, v5
	v_exp_f32_e32 v6, v6
	v_exp_f32_e32 v7, v7
	v_add_f32_e32 v148, 1.0, v148
	v_add_f32_e32 v149, 1.0, v149
	v_add_f32_e32 v150, 1.0, v150
	v_add_f32_e32 v151, 1.0, v151
	v_add_f32_e32 v4, 1.0, v4
	v_add_f32_e32 v5, 1.0, v5
	v_add_f32_e32 v6, 1.0, v6
	v_add_f32_e32 v7, 1.0, v7
	v_rcp_f32_e32 v148, v148
	v_rcp_f32_e32 v149, v149
	v_rcp_f32_e32 v150, v150
	v_rcp_f32_e32 v151, v151
	v_rcp_f32_e32 v4, v4
	v_rcp_f32_e32 v5, v5
	v_rcp_f32_e32 v6, v6
	v_rcp_f32_e32 v7, v7
	v_mul_f32_e32 v240, v148, v240
	v_mul_f32_e32 v241, v149, v241
	v_mul_f32_e32 v242, v150, v242
	v_mul_f32_e32 v243, v151, v243
	v_mul_f32_e32 v244, v4, v244
	v_mul_f32_e32 v245, v5, v245
	v_mul_f32_e32 v246, v6, v246
	v_mul_f32_e32 v247, v7, v247
	v_mul_f32_e32 v148, 0xbfb8aa3b, v248
	v_mul_f32_e32 v149, 0xbfb8aa3b, v249
	v_mul_f32_e32 v150, 0xbfb8aa3b, v250
	v_mul_f32_e32 v151, 0xbfb8aa3b, v251
	v_mul_f32_e32 v4, 0xbfb8aa3b, v252
	v_mul_f32_e32 v5, 0xbfb8aa3b, v253
	v_mul_f32_e32 v6, 0xbfb8aa3b, v254
	v_mul_f32_e32 v7, 0xbfb8aa3b, v255
	v_exp_f32_e32 v148, v148
	v_exp_f32_e32 v149, v149
	v_exp_f32_e32 v150, v150
	v_exp_f32_e32 v151, v151
	v_exp_f32_e32 v4, v4
	v_exp_f32_e32 v5, v5
	v_exp_f32_e32 v6, v6
	v_exp_f32_e32 v7, v7
	v_add_f32_e32 v148, 1.0, v148
	v_add_f32_e32 v149, 1.0, v149
	v_add_f32_e32 v150, 1.0, v150
	v_add_f32_e32 v151, 1.0, v151
	v_add_f32_e32 v4, 1.0, v4
	v_add_f32_e32 v5, 1.0, v5
	v_add_f32_e32 v6, 1.0, v6
	v_add_f32_e32 v7, 1.0, v7
	v_rcp_f32_e32 v148, v148
	v_rcp_f32_e32 v149, v149
	v_rcp_f32_e32 v150, v150
	v_rcp_f32_e32 v151, v151
	v_rcp_f32_e32 v4, v4
	v_rcp_f32_e32 v5, v5
	v_rcp_f32_e32 v6, v6
	v_rcp_f32_e32 v7, v7
	v_mul_f32_e32 v248, v148, v248
	v_mul_f32_e32 v249, v149, v249
	v_mul_f32_e32 v250, v150, v250
	v_mul_f32_e32 v251, v151, v251
	v_mul_f32_e32 v252, v4, v252
	v_mul_f32_e32 v253, v5, v253
	v_mul_f32_e32 v254, v6, v254
	v_mul_f32_e32 v255, v7, v255
	v_mul_f32_e32 v214, v144, v214
	v_mul_f32_e32 v215, v144, v215
	v_mul_f32_e32 v216, v144, v216
	v_mul_f32_e32 v217, v144, v217
	v_mul_f32_e32 v218, v144, v218
	v_mul_f32_e32 v219, v144, v219
	v_mul_f32_e32 v220, v144, v220
	v_mul_f32_e32 v221, v144, v221
	v_mul_f32_e32 v222, v144, v222
	v_mul_f32_e32 v223, v144, v223
	v_mul_f32_e32 v224, v144, v224
	v_mul_f32_e32 v225, v144, v225
	v_mul_f32_e32 v226, v144, v226
	v_mul_f32_e32 v227, v144, v227
	v_mul_f32_e32 v228, v144, v228
	v_mul_f32_e32 v229, v144, v229
	v_mul_f32_e32 v214, v16, v214
	v_mul_f32_e32 v215, v17, v215
	v_mul_f32_e32 v216, v18, v216
	v_mul_f32_e32 v217, v19, v217
	v_mul_f32_e32 v218, v20, v218
	v_mul_f32_e32 v219, v21, v219
	v_mul_f32_e32 v220, v22, v220
	v_mul_f32_e32 v221, v23, v221
	v_mul_f32_e32 v222, v24, v222
	v_mul_f32_e32 v223, v25, v223
	v_mul_f32_e32 v224, v26, v224
	v_mul_f32_e32 v225, v27, v225
	v_mul_f32_e32 v226, v28, v226
	v_mul_f32_e32 v227, v29, v227
	v_mul_f32_e32 v228, v30, v228
	v_mul_f32_e32 v229, v31, v229
	v_mul_f32_e32 v214, v240, v214
	v_mul_f32_e32 v215, v241, v215
	v_mul_f32_e32 v216, v242, v216
	v_mul_f32_e32 v217, v243, v217
	v_mul_f32_e32 v218, v244, v218
	v_mul_f32_e32 v219, v245, v219
	v_mul_f32_e32 v220, v246, v220
	v_mul_f32_e32 v221, v247, v221
	v_mul_f32_e32 v222, v248, v222
	v_mul_f32_e32 v223, v249, v223
	v_mul_f32_e32 v224, v250, v224
	v_mul_f32_e32 v225, v251, v225
	v_mul_f32_e32 v226, v252, v226
	v_mul_f32_e32 v227, v253, v227
	v_mul_f32_e32 v228, v254, v228
	v_mul_f32_e32 v229, v255, v229
	v_cvt_pk_bf16_f32 v144, v214, v215
	v_cvt_pk_bf16_f32 v145, v216, v217
	v_cvt_pk_bf16_f32 v146, v218, v219
	v_cvt_pk_bf16_f32 v147, v220, v221
	v_cvt_pk_bf16_f32 v148, v222, v223
	v_cvt_pk_bf16_f32 v149, v224, v225
	v_cvt_pk_bf16_f32 v150, v226, v227
	v_cvt_pk_bf16_f32 v151, v228, v229
	s_mul_i32 s9, s46, 6
	s_add_i32 s9, s9, s8
	s_lshl_b32 s3, s9, 11
	s_add_u32 s24, s16, s3
	s_addc_u32 s25, s17, 0
	global_store_dwordx4 v2, v[144:147], s[24:25]
	global_store_dwordx4 v2, v[148:151], s[24:25] offset:16
	s_waitcnt vmcnt(14)
; DI unsigned pk_bf16(float a, float b) { f32x2 v = {a, b}; bf2_t r = __builtin_convertvector(v, bf2_t); return __builtin_bit_cast(unsigned, r); }
; DI float bflo(unsigned u) { return __uint_as_float(u << 16); }
; DI float bfhi(unsigned u) { return __uint_as_float(u & 0xffff0000u); }
; DI float silu_f(float x) { return x * __builtin_amdgcn_rcpf(1.f + __expf(-x)); }
; DI void phase_gdn_gate(const Params& p) {
;     ...
;         const u32x4 a0 = *(const u32x4*)(oraw + (size_t)tok * 1024 + 16 * lane), a1 = *(const u32x4*)(oraw + (size_t)tok * 1024 + 16 * lane + 8);
;         const u32x4 z0 = *(const u32x4*)(P0 + (size_t)tok * LDP0 + 3072 + 16 * lane), z1 = *(const u32x4*)(P0 + (size_t)tok * LDP0 + 3072 + 16 * lane + 8);
;         float o[16], z[16];
;         const unsigned au[8] = {a0.x, a0.y, a0.z, a0.w, a1.x, a1.y, a1.z, a1.w}, zu[8] = {z0.x, z0.y, z0.z, z0.w, z1.x, z1.y, z1.z, z1.w};
;         float ss = 0.f;
; #pragma unroll
;         for (int i = 0; i < 8; ++i) { o[2 * i] = bflo(au[i]); o[2 * i + 1] = bfhi(au[i]); z[2 * i] = bflo(zu[i]); z[2 * i + 1] = bfhi(zu[i]); ss += o[2 * i] * o[2 * i] + o[2 * i + 1] * o[2 * i + 1]; }
;         ss += __shfl_xor(ss, 1); ss += __shfl_xor(ss, 2); ss += __shfl_xor(ss, 4);
;         const float rstd = rsqrtf(ss * (1.f / 128.f) + 1e-6f);
;         const int d0 = (16 * lane) & 127;
;         unsigned r[8];
; #pragma unroll
;         for (int i = 0; i < 8; ++i) { const float v0 = o[2 * i] * rstd * p.onorm_a[d0 + 2 * i] * silu_f(z[2 * i]), v1 = o[2 * i + 1] * rstd * p.onorm_a[d0 + 2 * i + 1] * silu_f(z[2 * i + 1]); r[i] = pk_bf16(v0, v1); }
;         *(u32x4*)(og + (size_t)tok * 1024 + 16 * lane) = (u32x4){r[0], r[1], r[2], r[3]};
;         *(u32x4*)(og + (size_t)tok * 1024 + 16 * lane + 8) = (u32x4){r[4], r[5], r[6], r[7]};
	v_lshlrev_b32_e32 v214, 16, v168
	v_and_b32_e32 v215, 0xffff0000, v168
	v_lshlrev_b32_e32 v216, 16, v169
	v_and_b32_e32 v217, 0xffff0000, v169
	v_lshlrev_b32_e32 v218, 16, v170
	v_and_b32_e32 v219, 0xffff0000, v170
	v_lshlrev_b32_e32 v220, 16, v171
	v_and_b32_e32 v221, 0xffff0000, v171
	v_lshlrev_b32_e32 v222, 16, v172
	v_and_b32_e32 v223, 0xffff0000, v172
	v_lshlrev_b32_e32 v224, 16, v173
	v_and_b32_e32 v225, 0xffff0000, v173
	v_lshlrev_b32_e32 v226, 16, v174
	v_and_b32_e32 v227, 0xffff0000, v174
	v_lshlrev_b32_e32 v228, 16, v175
	v_and_b32_e32 v229, 0xffff0000, v175
	v_mul_f32_e32 v144, v214, v214
	v_fmac_f32_e32 v144, v215, v215
	v_fmac_f32_e32 v144, v216, v216
	v_fmac_f32_e32 v144, v217, v217
	v_fmac_f32_e32 v144, v218, v218
	v_fmac_f32_e32 v144, v219, v219
	v_fmac_f32_e32 v144, v220, v220
	v_fmac_f32_e32 v144, v221, v221
	v_mul_f32_e32 v145, v222, v222
	v_fmac_f32_e32 v145, v223, v223
	v_fmac_f32_e32 v145, v224, v224
	v_fmac_f32_e32 v145, v225, v225
	v_fmac_f32_e32 v145, v226, v226
	v_fmac_f32_e32 v145, v227, v227
	v_fmac_f32_e32 v145, v228, v228
	v_fmac_f32_e32 v145, v229, v229
	v_add_f32_e32 v144, v144, v145
	v_lshlrev_b32_e32 v240, 16, v176
	v_and_b32_e32 v241, 0xffff0000, v176
	v_lshlrev_b32_e32 v242, 16, v177
	v_and_b32_e32 v243, 0xffff0000, v177
	v_lshlrev_b32_e32 v244, 16, v178
	v_and_b32_e32 v245, 0xffff0000, v178
	v_lshlrev_b32_e32 v246, 16, v179
	v_and_b32_e32 v247, 0xffff0000, v179
	v_lshlrev_b32_e32 v248, 16, v180
	v_and_b32_e32 v249, 0xffff0000, v180
	v_lshlrev_b32_e32 v250, 16, v181
	v_and_b32_e32 v251, 0xffff0000, v181
	v_lshlrev_b32_e32 v252, 16, v182
	v_and_b32_e32 v253, 0xffff0000, v182
	v_lshlrev_b32_e32 v254, 16, v183
	v_and_b32_e32 v255, 0xffff0000, v183
	s_nop 1
	v_add_f32_dpp v144, v144, v144 quad_perm:[1,0,3,2] row_mask:0xf bank_mask:0xf
	s_nop 1
	v_add_f32_dpp v144, v144, v144 quad_perm:[2,3,0,1] row_mask:0xf bank_mask:0xf
	s_nop 1
	v_add_f32_dpp v144, v144, v144 row_half_mirror row_mask:0xf bank_mask:0xf
	v_fmamk_f32 v144, v144, 0x3c000000, v15
	v_rsq_f32_e32 v144, v144
	v_mul_f32_e32 v148, 0xbfb8aa3b, v240
	v_mul_f32_e32 v149, 0xbfb8aa3b, v241
	v_mul_f32_e32 v150, 0xbfb8aa3b, v242
	v_mul_f32_e32 v151, 0xbfb8aa3b, v243
	v_mul_f32_e32 v4, 0xbfb8aa3b, v244
	v_mul_f32_e32 v5, 0xbfb8aa3b, v245
	v_mul_f32_e32 v6, 0xbfb8aa3b, v246
	v_mul_f32_e32 v7, 0xbfb8aa3b, v247
	v_exp_f32_e32 v148, v148
	v_exp_f32_e32 v149, v149
	v_exp_f32_e32 v150, v150
	v_exp_f32_e32 v151, v151
	v_exp_f32_e32 v4, v4
	v_exp_f32_e32 v5, v5
	v_exp_f32_e32 v6, v6
	v_exp_f32_e32 v7, v7
	v_add_f32_e32 v148, 1.0, v148
	v_add_f32_e32 v149, 1.0, v149
	v_add_f32_e32 v150, 1.0, v150
	v_add_f32_e32 v151, 1.0, v151
	v_add_f32_e32 v4, 1.0, v4
	v_add_f32_e32 v5, 1.0, v5
	v_add_f32_e32 v6, 1.0, v6
	v_add_f32_e32 v7, 1.0, v7
	v_rcp_f32_e32 v148, v148
	v_rcp_f32_e32 v149, v149
	v_rcp_f32_e32 v150, v150
	v_rcp_f32_e32 v151, v151
	v_rcp_f32_e32 v4, v4
	v_rcp_f32_e32 v5, v5
	v_rcp_f32_e32 v6, v6
	v_rcp_f32_e32 v7, v7
	v_mul_f32_e32 v240, v148, v240
	v_mul_f32_e32 v241, v149, v241
	v_mul_f32_e32 v242, v150, v242
	v_mul_f32_e32 v243, v151, v243
	v_mul_f32_e32 v244, v4, v244
	v_mul_f32_e32 v245, v5, v245
	v_mul_f32_e32 v246, v6, v246
	v_mul_f32_e32 v247, v7, v247
	v_mul_f32_e32 v148, 0xbfb8aa3b, v248
	v_mul_f32_e32 v149, 0xbfb8aa3b, v249
	v_mul_f32_e32 v150, 0xbfb8aa3b, v250
	v_mul_f32_e32 v151, 0xbfb8aa3b, v251
	v_mul_f32_e32 v4, 0xbfb8aa3b, v252
	v_mul_f32_e32 v5, 0xbfb8aa3b, v253
	v_mul_f32_e32 v6, 0xbfb8aa3b, v254
	v_mul_f32_e32 v7, 0xbfb8aa3b, v255
	v_exp_f32_e32 v148, v148
	v_exp_f32_e32 v149, v149
	v_exp_f32_e32 v150, v150
	v_exp_f32_e32 v151, v151
	v_exp_f32_e32 v4, v4
	v_exp_f32_e32 v5, v5
	v_exp_f32_e32 v6, v6
	v_exp_f32_e32 v7, v7
	v_add_f32_e32 v148, 1.0, v148
	v_add_f32_e32 v149, 1.0, v149
	v_add_f32_e32 v150, 1.0, v150
	v_add_f32_e32 v151, 1.0, v151
	v_add_f32_e32 v4, 1.0, v4
	v_add_f32_e32 v5, 1.0, v5
	v_add_f32_e32 v6, 1.0, v6
	v_add_f32_e32 v7, 1.0, v7
	v_rcp_f32_e32 v148, v148
	v_rcp_f32_e32 v149, v149
	v_rcp_f32_e32 v150, v150
	v_rcp_f32_e32 v151, v151
	v_rcp_f32_e32 v4, v4
	v_rcp_f32_e32 v5, v5
	v_rcp_f32_e32 v6, v6
	v_rcp_f32_e32 v7, v7
	v_mul_f32_e32 v248, v148, v248
	v_mul_f32_e32 v249, v149, v249
	v_mul_f32_e32 v250, v150, v250
	v_mul_f32_e32 v251, v151, v251
	v_mul_f32_e32 v252, v4, v252
	v_mul_f32_e32 v253, v5, v253
	v_mul_f32_e32 v254, v6, v254
	v_mul_f32_e32 v255, v7, v255
	v_mul_f32_e32 v214, v144, v214
	v_mul_f32_e32 v215, v144, v215
	v_mul_f32_e32 v216, v144, v216
	v_mul_f32_e32 v217, v144, v217
	v_mul_f32_e32 v218, v144, v218
	v_mul_f32_e32 v219, v144, v219
	v_mul_f32_e32 v220, v144, v220
	v_mul_f32_e32 v221, v144, v221
	v_mul_f32_e32 v222, v144, v222
	v_mul_f32_e32 v223, v144, v223
	v_mul_f32_e32 v224, v144, v224
	v_mul_f32_e32 v225, v144, v225
	v_mul_f32_e32 v226, v144, v226
	v_mul_f32_e32 v227, v144, v227
	v_mul_f32_e32 v228, v144, v228
	v_mul_f32_e32 v229, v144, v229
	v_mul_f32_e32 v214, v16, v214
	v_mul_f32_e32 v215, v17, v215
	v_mul_f32_e32 v216, v18, v216
	v_mul_f32_e32 v217, v19, v217
	v_mul_f32_e32 v218, v20, v218
	v_mul_f32_e32 v219, v21, v219
	v_mul_f32_e32 v220, v22, v220
	v_mul_f32_e32 v221, v23, v221
	v_mul_f32_e32 v222, v24, v222
	v_mul_f32_e32 v223, v25, v223
	v_mul_f32_e32 v224, v26, v224
	v_mul_f32_e32 v225, v27, v225
	v_mul_f32_e32 v226, v28, v226
	v_mul_f32_e32 v227, v29, v227
	v_mul_f32_e32 v228, v30, v228
	v_mul_f32_e32 v229, v31, v229
	v_mul_f32_e32 v214, v240, v214
	v_mul_f32_e32 v215, v241, v215
	v_mul_f32_e32 v216, v242, v216
	v_mul_f32_e32 v217, v243, v217
	v_mul_f32_e32 v218, v244, v218
	v_mul_f32_e32 v219, v245, v219
	v_mul_f32_e32 v220, v246, v220
	v_mul_f32_e32 v221, v247, v221
	v_mul_f32_e32 v222, v248, v222
	v_mul_f32_e32 v223, v249, v223
	v_mul_f32_e32 v224, v250, v224
	v_mul_f32_e32 v225, v251, v225
	v_mul_f32_e32 v226, v252, v226
	v_mul_f32_e32 v227, v253, v227
	v_mul_f32_e32 v228, v254, v228
	v_mul_f32_e32 v229, v255, v229
	v_cvt_pk_bf16_f32 v144, v214, v215
	v_cvt_pk_bf16_f32 v145, v216, v217
	v_cvt_pk_bf16_f32 v146, v218, v219
	v_cvt_pk_bf16_f32 v147, v220, v221
	v_cvt_pk_bf16_f32 v148, v222, v223
	v_cvt_pk_bf16_f32 v149, v224, v225
	v_cvt_pk_bf16_f32 v150, v226, v227
	v_cvt_pk_bf16_f32 v151, v228, v229
	s_mul_i32 s9, s46, 7
	s_add_i32 s9, s9, s8
	s_lshl_b32 s3, s9, 11
	s_add_u32 s24, s16, s3
	s_addc_u32 s25, s17, 0
	global_store_dwordx4 v2, v[144:147], s[24:25]
	global_store_dwordx4 v2, v[148:151], s[24:25] offset:16
	s_cmpk_lt_u32 s8, 0x400
	s_cbranch_scc0 .Lg4_done
; DI unsigned pk_bf16(float a, float b) { f32x2 v = {a, b}; bf2_t r = __builtin_convertvector(v, bf2_t); return __builtin_bit_cast(unsigned, r); }
; DI float bflo(unsigned u) { return __uint_as_float(u << 16); }
; DI float bfhi(unsigned u) { return __uint_as_float(u & 0xffff0000u); }
; DI float silu_f(float x) { return x * __builtin_amdgcn_rcpf(1.f + __expf(-x)); }
; DI void phase_gdn_gate(const Params& p) {
;     ...
;         const u32x4 a0 = *(const u32x4*)(oraw + (size_t)tok * 1024 + 16 * lane), a1 = *(const u32x4*)(oraw + (size_t)tok * 1024 + 16 * lane + 8);
;         const u32x4 z0 = *(const u32x4*)(P0 + (size_t)tok * LDP0 + 3072 + 16 * lane), z1 = *(const u32x4*)(P0 + (size_t)tok * LDP0 + 3072 + 16 * lane + 8);
;         float o[16], z[16];
;         const unsigned au[8] = {a0.x, a0.y, a0.z, a0.w, a1.x, a1.y, a1.z, a1.w}, zu[8] = {z0.x, z0.y, z0.z, z0.w, z1.x, z1.y, z1.z, z1.w};
;         float ss = 0.f;
; #pragma unroll
;         for (int i = 0; i < 8; ++i) { o[2 * i] = bflo(au[i]); o[2 * i + 1] = bfhi(au[i]); z[2 * i] = bflo(zu[i]); z[2 * i + 1] = bfhi(zu[i]); ss += o[2 * i] * o[2 * i] + o[2 * i + 1] * o[2 * i + 1]; }
;         ss += __shfl_xor(ss, 1); ss += __shfl_xor(ss, 2); ss += __shfl_xor(ss, 4);
;         const float rstd = rsqrtf(ss * (1.f / 128.f) + 1e-6f);
;         const int d0 = (16 * lane) & 127;
;         unsigned r[8];
; #pragma unroll
;         for (int i = 0; i < 8; ++i) { const float v0 = o[2 * i] * rstd * p.onorm_a[d0 + 2 * i] * silu_f(z[2 * i]), v1 = o[2 * i + 1] * rstd * p.onorm_a[d0 + 2 * i + 1] * silu_f(z[2 * i + 1]); r[i] = pk_bf16(v0, v1); }
;         *(u32x4*)(og + (size_t)tok * 1024 + 16 * lane) = (u32x4){r[0], r[1], r[2], r[3]};
;         *(u32x4*)(og + (size_t)tok * 1024 + 16 * lane + 8) = (u32x4){r[4], r[5], r[6], r[7]};
	s_waitcnt vmcnt(16)
	v_lshlrev_b32_e32 v214, 16, v198
	v_and_b32_e32 v215, 0xffff0000, v198
	v_lshlrev_b32_e32 v216, 16, v199
	v_and_b32_e32 v217, 0xffff0000, v199
	v_lshlrev_b32_e32 v218, 16, v200
	v_and_b32_e32 v219, 0xffff0000, v200
	v_lshlrev_b32_e32 v220, 16, v201
	v_and_b32_e32 v221, 0xffff0000, v201
	v_lshlrev_b32_e32 v222, 16, v202
	v_and_b32_e32 v223, 0xffff0000, v202
	v_lshlrev_b32_e32 v224, 16, v203
	v_and_b32_e32 v225, 0xffff0000, v203
	v_lshlrev_b32_e32 v226, 16, v204
	v_and_b32_e32 v227, 0xffff0000, v204
	v_lshlrev_b32_e32 v228, 16, v205
	v_and_b32_e32 v229, 0xffff0000, v205
	v_mul_f32_e32 v144, v214, v214
	v_fmac_f32_e32 v144, v215, v215
	v_fmac_f32_e32 v144, v216, v216
	v_fmac_f32_e32 v144, v217, v217
	v_fmac_f32_e32 v144, v218, v218
	v_fmac_f32_e32 v144, v219, v219
	v_fmac_f32_e32 v144, v220, v220
	v_fmac_f32_e32 v144, v221, v221
	v_mul_f32_e32 v145, v222, v222
	v_fmac_f32_e32 v145, v223, v223
	v_fmac_f32_e32 v145, v224, v224
	v_fmac_f32_e32 v145, v225, v225
	v_fmac_f32_e32 v145, v226, v226
	v_fmac_f32_e32 v145, v227, v227
	v_fmac_f32_e32 v145, v228, v228
	v_fmac_f32_e32 v145, v229, v229
	v_add_f32_e32 v144, v144, v145
	v_lshlrev_b32_e32 v240, 16, v206
	v_and_b32_e32 v241, 0xffff0000, v206
	v_lshlrev_b32_e32 v242, 16, v207
	v_and_b32_e32 v243, 0xffff0000, v207
	v_lshlrev_b32_e32 v244, 16, v208
	v_and_b32_e32 v245, 0xffff0000, v208
	v_lshlrev_b32_e32 v246, 16, v209
	v_and_b32_e32 v247, 0xffff0000, v209
	v_lshlrev_b32_e32 v248, 16, v210
	v_and_b32_e32 v249, 0xffff0000, v210
	v_lshlrev_b32_e32 v250, 16, v211
	v_and_b32_e32 v251, 0xffff0000, v211
	v_lshlrev_b32_e32 v252, 16, v212
	v_and_b32_e32 v253, 0xffff0000, v212
	v_lshlrev_b32_e32 v254, 16, v213
	v_and_b32_e32 v255, 0xffff0000, v213
	s_nop 1
	v_add_f32_dpp v144, v144, v144 quad_perm:[1,0,3,2] row_mask:0xf bank_mask:0xf
	s_nop 1
	v_add_f32_dpp v144, v144, v144 quad_perm:[2,3,0,1] row_mask:0xf bank_mask:0xf
	s_nop 1
	v_add_f32_dpp v144, v144, v144 row_half_mirror row_mask:0xf bank_mask:0xf
	v_fmamk_f32 v144, v144, 0x3c000000, v15
	v_rsq_f32_e32 v144, v144
	v_mul_f32_e32 v148, 0xbfb8aa3b, v240
	v_mul_f32_e32 v149, 0xbfb8aa3b, v241
	v_mul_f32_e32 v150, 0xbfb8aa3b, v242
	v_mul_f32_e32 v151, 0xbfb8aa3b, v243
	v_mul_f32_e32 v4, 0xbfb8aa3b, v244
	v_mul_f32_e32 v5, 0xbfb8aa3b, v245
	v_mul_f32_e32 v6, 0xbfb8aa3b, v246
	v_mul_f32_e32 v7, 0xbfb8aa3b, v247
	v_exp_f32_e32 v148, v148
	v_exp_f32_e32 v149, v149
	v_exp_f32_e32 v150, v150
	v_exp_f32_e32 v151, v151
	v_exp_f32_e32 v4, v4
	v_exp_f32_e32 v5, v5
	v_exp_f32_e32 v6, v6
	v_exp_f32_e32 v7, v7
	v_add_f32_e32 v148, 1.0, v148
	v_add_f32_e32 v149, 1.0, v149
	v_add_f32_e32 v150, 1.0, v150
	v_add_f32_e32 v151, 1.0, v151
	v_add_f32_e32 v4, 1.0, v4
	v_add_f32_e32 v5, 1.0, v5
	v_add_f32_e32 v6, 1.0, v6
	v_add_f32_e32 v7, 1.0, v7
	v_rcp_f32_e32 v148, v148
	v_rcp_f32_e32 v149, v149
	v_rcp_f32_e32 v150, v150
	v_rcp_f32_e32 v151, v151
	v_rcp_f32_e32 v4, v4
	v_rcp_f32_e32 v5, v5
	v_rcp_f32_e32 v6, v6
	v_rcp_f32_e32 v7, v7
	v_mul_f32_e32 v240, v148, v240
	v_mul_f32_e32 v241, v149, v241
	v_mul_f32_e32 v242, v150, v242
	v_mul_f32_e32 v243, v151, v243
	v_mul_f32_e32 v244, v4, v244
	v_mul_f32_e32 v245, v5, v245
	v_mul_f32_e32 v246, v6, v246
	v_mul_f32_e32 v247, v7, v247
	v_mul_f32_e32 v148, 0xbfb8aa3b, v248
	v_mul_f32_e32 v149, 0xbfb8aa3b, v249
	v_mul_f32_e32 v150, 0xbfb8aa3b, v250
	v_mul_f32_e32 v151, 0xbfb8aa3b, v251
	v_mul_f32_e32 v4, 0xbfb8aa3b, v252
	v_mul_f32_e32 v5, 0xbfb8aa3b, v253
	v_mul_f32_e32 v6, 0xbfb8aa3b, v254
	v_mul_f32_e32 v7, 0xbfb8aa3b, v255
	v_exp_f32_e32 v148, v148
	v_exp_f32_e32 v149, v149
	v_exp_f32_e32 v150, v150
	v_exp_f32_e32 v151, v151
	v_exp_f32_e32 v4, v4
	v_exp_f32_e32 v5, v5
	v_exp_f32_e32 v6, v6
	v_exp_f32_e32 v7, v7
	v_add_f32_e32 v148, 1.0, v148
	v_add_f32_e32 v149, 1.0, v149
	v_add_f32_e32 v150, 1.0, v150
	v_add_f32_e32 v151, 1.0, v151
	v_add_f32_e32 v4, 1.0, v4
	v_add_f32_e32 v5, 1.0, v5
	v_add_f32_e32 v6, 1.0, v6
	v_add_f32_e32 v7, 1.0, v7
	v_rcp_f32_e32 v148, v148
	v_rcp_f32_e32 v149, v149
	v_rcp_f32_e32 v150, v150
	v_rcp_f32_e32 v151, v151
	v_rcp_f32_e32 v4, v4
	v_rcp_f32_e32 v5, v5
	v_rcp_f32_e32 v6, v6
	v_rcp_f32_e32 v7, v7
	v_mul_f32_e32 v248, v148, v248
	v_mul_f32_e32 v249, v149, v249
	v_mul_f32_e32 v250, v150, v250
	v_mul_f32_e32 v251, v151, v251
	v_mul_f32_e32 v252, v4, v252
	v_mul_f32_e32 v253, v5, v253
	v_mul_f32_e32 v254, v6, v254
	v_mul_f32_e32 v255, v7, v255
	v_mul_f32_e32 v214, v144, v214
	v_mul_f32_e32 v215, v144, v215
	v_mul_f32_e32 v216, v144, v216
	v_mul_f32_e32 v217, v144, v217
	v_mul_f32_e32 v218, v144, v218
	v_mul_f32_e32 v219, v144, v219
	v_mul_f32_e32 v220, v144, v220
	v_mul_f32_e32 v221, v144, v221
	v_mul_f32_e32 v222, v144, v222
	v_mul_f32_e32 v223, v144, v223
	v_mul_f32_e32 v224, v144, v224
	v_mul_f32_e32 v225, v144, v225
	v_mul_f32_e32 v226, v144, v226
	v_mul_f32_e32 v227, v144, v227
	v_mul_f32_e32 v228, v144, v228
	v_mul_f32_e32 v229, v144, v229
	v_mul_f32_e32 v214, v16, v214
	v_mul_f32_e32 v215, v17, v215
	v_mul_f32_e32 v216, v18, v216
	v_mul_f32_e32 v217, v19, v217
	v_mul_f32_e32 v218, v20, v218
	v_mul_f32_e32 v219, v21, v219
	v_mul_f32_e32 v220, v22, v220
	v_mul_f32_e32 v221, v23, v221
	v_mul_f32_e32 v222, v24, v222
	v_mul_f32_e32 v223, v25, v223
	v_mul_f32_e32 v224, v26, v224
	v_mul_f32_e32 v225, v27, v225
	v_mul_f32_e32 v226, v28, v226
	v_mul_f32_e32 v227, v29, v227
	v_mul_f32_e32 v228, v30, v228
	v_mul_f32_e32 v229, v31, v229
	v_mul_f32_e32 v214, v240, v214
	v_mul_f32_e32 v215, v241, v215
	v_mul_f32_e32 v216, v242, v216
	v_mul_f32_e32 v217, v243, v217
	v_mul_f32_e32 v218, v244, v218
	v_mul_f32_e32 v219, v245, v219
	v_mul_f32_e32 v220, v246, v220
	v_mul_f32_e32 v221, v247, v221
	v_mul_f32_e32 v222, v248, v222
	v_mul_f32_e32 v223, v249, v223
	v_mul_f32_e32 v224, v250, v224
	v_mul_f32_e32 v225, v251, v225
	v_mul_f32_e32 v226, v252, v226
	v_mul_f32_e32 v227, v253, v227
	v_mul_f32_e32 v228, v254, v228
	v_mul_f32_e32 v229, v255, v229
	v_cvt_pk_bf16_f32 v144, v214, v215
	v_cvt_pk_bf16_f32 v145, v216, v217
	v_cvt_pk_bf16_f32 v146, v218, v219
	v_cvt_pk_bf16_f32 v147, v220, v221
	v_cvt_pk_bf16_f32 v148, v222, v223
	v_cvt_pk_bf16_f32 v149, v224, v225
	v_cvt_pk_bf16_f32 v150, v226, v227
	v_cvt_pk_bf16_f32 v151, v228, v229
	s_mul_i32 s9, s46, 8
	s_add_i32 s9, s9, s8
	s_lshl_b32 s3, s9, 11
	s_add_u32 s24, s16, s3
	s_addc_u32 s25, s17, 0
	global_store_dwordx4 v2, v[144:147], s[24:25]
	global_store_dwordx4 v2, v[148:151], s[24:25] offset:16
; #define LAS __attribute__((address_space(3)))
; #define SYNC(k) if (p.ph_lo < (k) && (k) < p.ph_hi) { if (p.use_cg) grid.sync(); else { xcd_barrier(xb); if ((PROBE_MASK >> 17) & 1) xcd_barrier(xb); } }
; __global__ void __launch_bounds__(512) hybrid_fwd(Params p) {
;     ...
;     _Pragma("unroll") for (int rep = 0; rep <= ((PROBE_MASK >> 0) & 1); ++rep) if (RUN(0)) phase_prep(p, smem);
;     SYNC(1);
;     _Pragma("unroll") for (int rep = 0; rep <= ((PROBE_MASK >> 1) & 1); ++rep) if (RUN(1)) { pg8::Gemm g{(const bf16_t*)(p.ws + WS_XN), (const bf16_t*)(p.ws + WS_WTA), T_TOK, LDP0, 1024, 1024}; pg8::StaticOrder S; S.init(g.M, g.N, gridDim.x, blockIdx.x);
;                   pg8::EpiBf16 E{(bf16_t*)(p.ws + WS_P0), LDP0}; pg8::gemm_phase((LAS unsigned char*)smem, g, S, E); }
;     SYNC(2);
;     _Pragma("unroll") for (int rep = 0; rep <= ((PROBE_MASK >> 2) & 1); ++rep) if (RUN(2)) phase_gdn_prep(p, smem);
;     SYNC(3);
;     _Pragma("unroll") for (int rep = 0; rep <= ((PROBE_MASK >> 3) & 1); ++rep) if (RUN(3)) phase_gdn_scan(p, smem);
;     SYNC(4);
;     _Pragma("unroll") for (int rep = 0; rep <= ((PROBE_MASK >> 4) & 1); ++rep) if (RUN(4)) phase_gdn_gate(p);
;     SYNC(5);
.Lg4_done:
.LBB0_933:
	s_or_b64 exec, exec, s[6:7]
	s_cmp_gt_i32 s81, 5
	s_cselect_b64 s[0:1], -1, 0
	v_readlane_b32 s14, v238, 18
	s_and_b64 s[4:5], s[4:5], s[0:1]
	v_readlane_b32 s15, v238, 19
	s_andn2_b64 vcc, exec, s[4:5]
	s_cbranch_vccnz .LBB0_1001
	s_cmp_eq_u32 s82, 0
	s_cbranch_scc1 .LBB0_946
	v_lshrrev_b32_e32 v2, 20, v0
	v_lshrrev_b32_e32 v3, 10, v0
	v_or_b32_e32 v2, v3, v2
	s_movk_i32 s3, 0x3ff
	v_and_or_b32 v2, v2, s3, v1
	v_cmp_eq_u32_e32 vcc, 0, v2
	s_waitcnt vmcnt(0) lgkmcnt(0)
	s_barrier
	s_and_saveexec_b64 s[4:5], vcc
	s_cbranch_execz .LBB0_945
	v_readlane_b32 s6, v238, 0
	v_readlane_b32 s7, v238, 1
	buffer_wbl2 sc1
	s_load_dwordx2 s[6:7], s[6:7], 0x58
	v_mov_b32_e32 v4, 0
	s_mov_b64 s[8:9], exec
	v_mbcnt_lo_u32_b32 v3, s8, 0
	v_mbcnt_hi_u32_b32 v3, s9, v3
	s_waitcnt lgkmcnt(0)
	global_load_dword v2, v4, s[6:7] offset:40
	v_cmp_eq_u32_e32 vcc, 0, v3
	s_and_saveexec_b64 s[10:11], vcc
	s_cbranch_execz .LBB0_938
	s_bcnt1_i32_b64 s3, s[8:9]
	v_mov_b32_e32 v5, s3
	global_atomic_add v5, v4, v5, s[6:7] offset:32 sc0

; DI unsigned pk_bf16(float a, float b) { f32x2 v = {a, b}; bf2_t r = __builtin_convertvector(v, bf2_t); return __builtin_bit_cast(unsigned, r); }
; DI float bflo(unsigned u) { return __uint_as_float(u << 16); }
; DI float bfhi(unsigned u) { return __uint_as_float(u & 0xffff0000u); }
; DI void phase_norm1(const Params& p) {
;     const int lane = threadIdx.x & 63, gw = blockIdx.x * 8 + (threadIdx.x >> 6), nw = gridDim.x * 8;
;     bf16_t* x1 = (bf16_t*)(p.ws + WS_X1); const float* part = (const float*)(p.ws + WS_PART1); bf16_t* out = (bf16_t*)(p.ws + WS_XN); const float* w = p.norm_w + 1024;
;     for (int tok = gw; tok < T_TOK; tok += nw) {
;         f32x4 v[4]; float ss = 0.f;
; #pragma unroll
;         for (int i = 0; i < 4; ++i) { const int c = 4 * lane + 256 * i;
;             if (tok < T_PR) { const u32x2 t = *(const u32x2*)(x1 + (size_t)tok * 1024 + c); v[i] = (f32x4){bflo(t.x), bfhi(t.x), bflo(t.y), bfhi(t.y)}; }
;             else { const size_t o = (size_t)(tok - T_PR) * 1024 + c; v[i] = *(const f32x4*)(p.xs + o);
; #pragma unroll
;                 for (int s = 0; s < 4; ++s) v[i] += *(const f32x4*)(part + (size_t)s * 1048576 + o);
;                 u32x2 t; t.x = pk_bf16(v[i].x, v[i].y); t.y = pk_bf16(v[i].z, v[i].w); *(u32x2*)(x1 + (size_t)tok * 1024 + c) = t; }
.LBB0_1095:
	s_cmp_lt_i32 s80, 7
	s_cselect_b64 s[6:7], -1, 0
	s_and_b64 s[0:1], s[6:7], s[0:1]
	s_and_b64 s[0:1], s[44:45], s[0:1]
	v_lshlrev_b32_e32 v164, 2, v152
	v_lshlrev_b32_e32 v166, 1, v152
	s_and_saveexec_b64 s[8:9], s[0:1]
	s_cbranch_execz .LBB0_1114
	v_lshlrev_b32_e32 v2, 3, v196
	v_lshlrev_b32_e32 v3, 4, v196
	s_add_u32 s10, s70, 0x1000
	s_addc_u32 s11, s71, 0
	s_add_u32 s12, s78, 0xc480000
	s_addc_u32 s13, s79, 0
	s_add_u32 s16, s78, 0x1a80000
	s_addc_u32 s17, s79, 0
	global_load_dwordx4 v[16:19], v3, s[10:11]
	global_load_dwordx4 v[20:23], v3, s[10:11] offset:1024
	global_load_dwordx4 v[24:27], v3, s[10:11] offset:2048
	global_load_dwordx4 v[28:31], v3, s[10:11] offset:3072
	v_readfirstlane_b32 s4, v162
	v_mov_b32_e32 v60, 0x358637bd
	s_cmpk_lt_u32 s4, 0x400
	s_cbranch_scc0 .Ln1_nosA
	s_lshl_b32 s5, s4, 12
	s_add_u32 s24, s62, s5
	s_addc_u32 s25, s63, 0
	global_load_dwordx4 v[168:171], v3, s[24:25]
	global_load_dwordx4 v[172:175], v3, s[24:25] offset:1024
	global_load_dwordx4 v[176:179], v3, s[24:25] offset:2048
	global_load_dwordx4 v[180:183], v3, s[24:25] offset:3072
	s_add_u32 s24, s78, 0x26500000
	s_addc_u32 s25, s79, 0
	s_add_u32 s24, s24, s5
	s_addc_u32 s25, s25, 0
	global_load_dwordx4 v[198:201], v3, s[24:25]
	global_load_dwordx4 v[202:205], v3, s[24:25] offset:1024
	global_load_dwordx4 v[206:209], v3, s[24:25] offset:2048
	global_load_dwordx4 v[210:213], v3, s[24:25] offset:3072
	s_add_u32 s24, s24, 0x400000
	s_addc_u32 s25, s25, 0
	global_load_dwordx4 v[214:217], v3, s[24:25]
	global_load_dwordx4 v[218:221], v3, s[24:25] offset:1024
	global_load_dwordx4 v[222:225], v3, s[24:25] offset:2048
	global_load_dwordx4 v[226:229], v3, s[24:25] offset:3072
	s_add_u32 s24, s24, 0x400000
	s_addc_u32 s25, s25, 0
	global_load_dwordx4 v[240:243], v3, s[24:25]
	global_load_dwordx4 v[244:247], v3, s[24:25] offset:1024
	global_load_dwordx4 v[248:251], v3, s[24:25] offset:2048
	global_load_dwordx4 v[252:255], v3, s[24:25] offset:3072
	s_add_u32 s24, s24, 0x400000
	s_addc_u32 s25, s25, 0
	global_load_dwordx4 v[32:35], v3, s[24:25]
	global_load_dwordx4 v[36:39], v3, s[24:25] offset:1024
	global_load_dwordx4 v[40:43], v3, s[24:25] offset:2048
	global_load_dwordx4 v[44:47], v3, s[24:25] offset:3072
.Ln1_nosA:
	s_mul_i32 s5, s46, 0
	s_add_i32 s5, s5, s4
	s_lshl_b32 s5, s5, 11
	s_add_u32 s24, s12, s5
	s_addc_u32 s25, s13, 0
	global_load_dwordx2 v[80:81], v2, s[24:25]
	global_load_dwordx2 v[82:83], v2, s[24:25] offset:512
	global_load_dwordx2 v[84:85], v2, s[24:25] offset:1024
	global_load_dwordx2 v[86:87], v2, s[24:25] offset:1536
	s_mul_i32 s5, s46, 1
	s_add_i32 s5, s5, s4
	s_lshl_b32 s5, s5, 11
	s_add_u32 s24, s12, s5
	s_addc_u32 s25, s13, 0
	global_load_dwordx2 v[88:89], v2, s[24:25]
	global_load_dwordx2 v[90:91], v2, s[24:25] offset:512
	global_load_dwordx2 v[92:93], v2, s[24:25] offset:1024
	global_load_dwordx2 v[94:95], v2, s[24:25] offset:1536
	s_mul_i32 s5, s46, 2
	s_add_i32 s5, s5, s4
	s_lshl_b32 s5, s5, 11
	s_add_u32 s24, s12, s5
	s_addc_u32 s25, s13, 0
	global_load_dwordx2 v[96:97], v2, s[24:25]
	global_load_dwordx2 v[98:99], v2, s[24:25] offset:512
	global_load_dwordx2 v[100:101], v2, s[24:25] offset:1024
	global_load_dwordx2 v[102:103], v2, s[24:25] offset:1536
	s_mul_i32 s5, s46, 3
	s_add_i32 s5, s5, s4
	s_lshl_b32 s5, s5, 11
	s_add_u32 s24, s12, s5
	s_addc_u32 s25, s13, 0
	global_load_dwordx2 v[104:105], v2, s[24:25]
	global_load_dwordx2 v[106:107], v2, s[24:25] offset:512
	global_load_dwordx2 v[108:109], v2, s[24:25] offset:1024
	global_load_dwordx2 v[110:111], v2, s[24:25] offset:1536
	s_mul_i32 s5, s46, 4
	s_add_i32 s5, s5, s4
	s_lshl_b32 s5, s5, 11
	s_add_u32 s24, s12, s5
	s_addc_u32 s25, s13, 0
	global_load_dwordx2 v[112:113], v2, s[24:25]
	global_load_dwordx2 v[114:115], v2, s[24:25] offset:512
	global_load_dwordx2 v[116:117], v2, s[24:25] offset:1024
	global_load_dwordx2 v[118:119], v2, s[24:25] offset:1536
	s_mul_i32 s5, s46, 5
	s_add_i32 s5, s5, s4
	s_lshl_b32 s5, s5, 11
	s_add_u32 s24, s12, s5
	s_addc_u32 s25, s13, 0
	global_load_dwordx2 v[120:121], v2, s[24:25]
	global_load_dwordx2 v[122:123], v2, s[24:25] offset:512
	global_load_dwordx2 v[124:125], v2, s[24:25] offset:1024
	global_load_dwordx2 v[126:127], v2, s[24:25] offset:1536
	s_mul_i32 s5, s46, 6
	s_add_i32 s5, s5, s4
	s_lshl_b32 s5, s5, 11
	s_add_u32 s24, s12, s5
	s_addc_u32 s25, s13, 0
	global_load_dwordx2 v[128:129], v2, s[24:25]
	global_load_dwordx2 v[130:131], v2, s[24:25] offset:512
	global_load_dwordx2 v[132:133], v2, s[24:25] offset:1024
	global_load_dwordx2 v[134:135], v2, s[24:25] offset:1536
	s_mul_i32 s5, s46, 7
	s_add_i32 s5, s5, s4
	s_lshl_b32 s5, s5, 11
	s_add_u32 s24, s12, s5
	s_addc_u32 s25, s13, 0
	global_load_dwordx2 v[136:137], v2, s[24:25]
	global_load_dwordx2 v[138:139], v2, s[24:25] offset:512
	global_load_dwordx2 v[140:141], v2, s[24:25] offset:1024
	global_load_dwordx2 v[142:143], v2, s[24:25] offset:1536
	s_waitcnt vmcnt(28)
; DI unsigned pk_bf16(float a, float b) { f32x2 v = {a, b}; bf2_t r = __builtin_convertvector(v, bf2_t); return __builtin_bit_cast(unsigned, r); }
; DI float bflo(unsigned u) { return __uint_as_float(u << 16); }
; DI float bfhi(unsigned u) { return __uint_as_float(u & 0xffff0000u); }
; DI void phase_norm1(const Params& p) {
;     ...
;         for (int i = 0; i < 4; ++i) { const int c = 4 * lane + 256 * i;
;             if (tok < T_PR) { const u32x2 t = *(const u32x2*)(x1 + (size_t)tok * 1024 + c); v[i] = (f32x4){bflo(t.x), bfhi(t.x), bflo(t.y), bfhi(t.y)}; }
;             else { const size_t o = (size_t)(tok - T_PR) * 1024 + c; v[i] = *(const f32x4*)(p.xs + o);
; #pragma unroll
;                 for (int s = 0; s < 4; ++s) v[i] += *(const f32x4*)(part + (size_t)s * 1048576 + o);
;                 u32x2 t; t.x = pk_bf16(v[i].x, v[i].y); t.y = pk_bf16(v[i].z, v[i].w); *(u32x2*)(x1 + (size_t)tok * 1024 + c) = t; }
;             ss += v[i].x * v[i].x + v[i].y * v[i].y + v[i].z * v[i].z + v[i].w * v[i].w; }
;         ss = wave_sum(ss);
;         const float rstd = rsqrtf(ss * (1.f / 1024.f) + 1e-6f);
; #pragma unroll
;         for (int i = 0; i < 4; ++i) { const f32x4 ww = *(const f32x4*)(w + 4 * lane + 256 * i);
;             u32x2 o; o.x = pk_bf16(v[i].x * rstd * ww.x, v[i].y * rstd * ww.y); o.y = pk_bf16(v[i].z * rstd * ww.z, v[i].w * rstd * ww.w);
;             *(u32x2*)(out + (size_t)tok * 1024 + 4 * lane + 256 * i) = o; }
	v_lshlrev_b32_e32 v64, 16, v80
	v_and_b32_e32 v65, 0xffff0000, v80
	v_lshlrev_b32_e32 v66, 16, v81
	v_and_b32_e32 v67, 0xffff0000, v81
	v_lshlrev_b32_e32 v68, 16, v82
	v_and_b32_e32 v69, 0xffff0000, v82
	v_lshlrev_b32_e32 v70, 16, v83
	v_and_b32_e32 v71, 0xffff0000, v83
	v_lshlrev_b32_e32 v72, 16, v84
	v_and_b32_e32 v73, 0xffff0000, v84
	v_lshlrev_b32_e32 v74, 16, v85
	v_and_b32_e32 v75, 0xffff0000, v85
	v_lshlrev_b32_e32 v76, 16, v86
	v_and_b32_e32 v77, 0xffff0000, v86
	v_lshlrev_b32_e32 v78, 16, v87
	v_and_b32_e32 v79, 0xffff0000, v87
	s_mul_i32 s22, s46, 0
	s_add_i32 s22, s22, s4
	v_mul_f32_e32 v48, v64, v64
	v_fmac_f32_e32 v48, v65, v65
	v_fmac_f32_e32 v48, v66, v66
	v_fmac_f32_e32 v48, v67, v67
	v_mul_f32_e32 v49, v68, v68
	v_fmac_f32_e32 v49, v69, v69
	v_fmac_f32_e32 v49, v70, v70
	v_fmac_f32_e32 v49, v71, v71
	v_mul_f32_e32 v50, v72, v72
	v_fmac_f32_e32 v50, v73, v73
	v_fmac_f32_e32 v50, v74, v74
	v_fmac_f32_e32 v50, v75, v75
	v_mul_f32_e32 v51, v76, v76
	v_fmac_f32_e32 v51, v77, v77
	v_fmac_f32_e32 v51, v78, v78
	v_fmac_f32_e32 v51, v79, v79
	v_add_f32_e32 v48, v48, v49
	v_add_f32_e32 v50, v50, v51
	v_add_f32_e32 v48, v48, v50
	s_nop 1
	v_add_f32_dpp v48, v48, v48 quad_perm:[1,0,3,2] row_mask:0xf bank_mask:0xf bound_ctrl:1
	s_nop 1
	v_add_f32_dpp v48, v48, v48 quad_perm:[2,3,0,1] row_mask:0xf bank_mask:0xf bound_ctrl:1
	s_nop 1
	v_add_f32_dpp v48, v48, v48 row_ror:4 row_mask:0xf bank_mask:0xf bound_ctrl:1
	s_nop 1
	v_add_f32_dpp v48, v48, v48 row_ror:8 row_mask:0xf bank_mask:0xf bound_ctrl:1
	s_nop 1
	v_readlane_b32 s28, v48, 0
	v_readlane_b32 s29, v48, 16
	v_readlane_b32 s30, v48, 32
	v_readlane_b32 s31, v48, 48
	s_nop 1
	v_mov_b32_e32 v52, s28
	v_add_f32_e32 v52, s29, v52
	v_add_f32_e32 v52, s30, v52
	v_add_f32_e32 v52, s31, v52
	v_fmamk_f32 v52, v52, 0x3a800000, v60
	v_rsq_f32_e32 v52, v52
	s_lshl_b32 s20, s22, 11
	s_add_u32 s20, s16, s20
	s_addc_u32 s21, s17, 0
	v_mul_f32_e32 v64, v64, v52
	v_mul_f32_e32 v65, v65, v52
	v_mul_f32_e32 v66, v66, v52
	v_mul_f32_e32 v67, v67, v52
	v_mul_f32_e32 v64, v64, v16
	v_mul_f32_e32 v65, v65, v17
	v_mul_f32_e32 v66, v66, v18
	v_mul_f32_e32 v67, v67, v19
	v_cvt_pk_bf16_f32 v64, v64, v65
	v_cvt_pk_bf16_f32 v65, v66, v67
	global_store_dwordx2 v2, v[64:65], s[20:21]
	v_mul_f32_e32 v68, v68, v52
	v_mul_f32_e32 v69, v69, v52
	v_mul_f32_e32 v70, v70, v52
	v_mul_f32_e32 v71, v71, v52
	v_mul_f32_e32 v68, v68, v20
	v_mul_f32_e32 v69, v69, v21
	v_mul_f32_e32 v70, v70, v22
	v_mul_f32_e32 v71, v71, v23
	v_cvt_pk_bf16_f32 v68, v68, v69
	v_cvt_pk_bf16_f32 v69, v70, v71
	global_store_dwordx2 v2, v[68:69], s[20:21] offset:512
	v_mul_f32_e32 v72, v72, v52
	v_mul_f32_e32 v73, v73, v52
	v_mul_f32_e32 v74, v74, v52
	v_mul_f32_e32 v75, v75, v52
	v_mul_f32_e32 v72, v72, v24
	v_mul_f32_e32 v73, v73, v25
	v_mul_f32_e32 v74, v74, v26
	v_mul_f32_e32 v75, v75, v27
	v_cvt_pk_bf16_f32 v72, v72, v73
	v_cvt_pk_bf16_f32 v73, v74, v75
	global_store_dwordx2 v2, v[72:73], s[20:21] offset:1024
	v_mul_f32_e32 v76, v76, v52
	v_mul_f32_e32 v77, v77, v52
	v_mul_f32_e32 v78, v78, v52
	v_mul_f32_e32 v79, v79, v52
	v_mul_f32_e32 v76, v76, v28
	v_mul_f32_e32 v77, v77, v29
	v_mul_f32_e32 v78, v78, v30
	v_mul_f32_e32 v79, v79, v31
	v_cvt_pk_bf16_f32 v76, v76, v77
	v_cvt_pk_bf16_f32 v77, v78, v79
	global_store_dwordx2 v2, v[76:77], s[20:21] offset:1536
	s_waitcnt vmcnt(28)
	v_lshlrev_b32_e32 v64, 16, v88
	v_and_b32_e32 v65, 0xffff0000, v88
	v_lshlrev_b32_e32 v66, 16, v89
	v_and_b32_e32 v67, 0xffff0000, v89
	v_lshlrev_b32_e32 v68, 16, v90
	v_and_b32_e32 v69, 0xffff0000, v90
	v_lshlrev_b32_e32 v70, 16, v91
	v_and_b32_e32 v71, 0xffff0000, v91
	v_lshlrev_b32_e32 v72, 16, v92
	v_and_b32_e32 v73, 0xffff0000, v92
	v_lshlrev_b32_e32 v74, 16, v93
	v_and_b32_e32 v75, 0xffff0000, v93
	v_lshlrev_b32_e32 v76, 16, v94
	v_and_b32_e32 v77, 0xffff0000, v94
	v_lshlrev_b32_e32 v78, 16, v95
	v_and_b32_e32 v79, 0xffff0000, v95
	s_mul_i32 s22, s46, 1
	s_add_i32 s22, s22, s4
	v_mul_f32_e32 v48, v64, v64
	v_fmac_f32_e32 v48, v65, v65
	v_fmac_f32_e32 v48, v66, v66
	v_fmac_f32_e32 v48, v67, v67
	v_mul_f32_e32 v49, v68, v68
	v_fmac_f32_e32 v49, v69, v69
	v_fmac_f32_e32 v49, v70, v70
	v_fmac_f32_e32 v49, v71, v71
	v_mul_f32_e32 v50, v72, v72
	v_fmac_f32_e32 v50, v73, v73
	v_fmac_f32_e32 v50, v74, v74
	v_fmac_f32_e32 v50, v75, v75
	v_mul_f32_e32 v51, v76, v76
	v_fmac_f32_e32 v51, v77, v77
	v_fmac_f32_e32 v51, v78, v78
	v_fmac_f32_e32 v51, v79, v79
	v_add_f32_e32 v48, v48, v49
	v_add_f32_e32 v50, v50, v51
	v_add_f32_e32 v48, v48, v50
	s_nop 1
	v_add_f32_dpp v48, v48, v48 quad_perm:[1,0,3,2] row_mask:0xf bank_mask:0xf bound_ctrl:1
	s_nop 1
	v_add_f32_dpp v48, v48, v48 quad_perm:[2,3,0,1] row_mask:0xf bank_mask:0xf bound_ctrl:1
	s_nop 1
	v_add_f32_dpp v48, v48, v48 row_ror:4 row_mask:0xf bank_mask:0xf bound_ctrl:1
	s_nop 1
	v_add_f32_dpp v48, v48, v48 row_ror:8 row_mask:0xf bank_mask:0xf bound_ctrl:1
	s_nop 1
	v_readlane_b32 s28, v48, 0
	v_readlane_b32 s29, v48, 16
	v_readlane_b32 s30, v48, 32
	v_readlane_b32 s31, v48, 48
	s_nop 1
	v_mov_b32_e32 v52, s28
	v_add_f32_e32 v52, s29, v52
	v_add_f32_e32 v52, s30, v52
	v_add_f32_e32 v52, s31, v52
	v_fmamk_f32 v52, v52, 0x3a800000, v60
	v_rsq_f32_e32 v52, v52
	s_lshl_b32 s20, s22, 11
	s_add_u32 s20, s16, s20
	s_addc_u32 s21, s17, 0
	v_mul_f32_e32 v64, v64, v52
	v_mul_f32_e32 v65, v65, v52
	v_mul_f32_e32 v66, v66, v52
	v_mul_f32_e32 v67, v67, v52
	v_mul_f32_e32 v64, v64, v16
	v_mul_f32_e32 v65, v65, v17
	v_mul_f32_e32 v66, v66, v18
	v_mul_f32_e32 v67, v67, v19
	v_cvt_pk_bf16_f32 v64, v64, v65
	v_cvt_pk_bf16_f32 v65, v66, v67
	global_store_dwordx2 v2, v[64:65], s[20:21]
	v_mul_f32_e32 v68, v68, v52
	v_mul_f32_e32 v69, v69, v52
	v_mul_f32_e32 v70, v70, v52
	v_mul_f32_e32 v71, v71, v52
	v_mul_f32_e32 v68, v68, v20
	v_mul_f32_e32 v69, v69, v21
	v_mul_f32_e32 v70, v70, v22
	v_mul_f32_e32 v71, v71, v23
	v_cvt_pk_bf16_f32 v68, v68, v69
	v_cvt_pk_bf16_f32 v69, v70, v71
	global_store_dwordx2 v2, v[68:69], s[20:21] offset:512
	v_mul_f32_e32 v72, v72, v52
	v_mul_f32_e32 v73, v73, v52
	v_mul_f32_e32 v74, v74, v52
	v_mul_f32_e32 v75, v75, v52
	v_mul_f32_e32 v72, v72, v24
	v_mul_f32_e32 v73, v73, v25
	v_mul_f32_e32 v74, v74, v26
	v_mul_f32_e32 v75, v75, v27
	v_cvt_pk_bf16_f32 v72, v72, v73
	v_cvt_pk_bf16_f32 v73, v74, v75
	global_store_dwordx2 v2, v[72:73], s[20:21] offset:1024
	v_mul_f32_e32 v76, v76, v52
	v_mul_f32_e32 v77, v77, v52
	v_mul_f32_e32 v78, v78, v52
	v_mul_f32_e32 v79, v79, v52
	v_mul_f32_e32 v76, v76, v28
	v_mul_f32_e32 v77, v77, v29
	v_mul_f32_e32 v78, v78, v30
	v_mul_f32_e32 v79, v79, v31
	v_cvt_pk_bf16_f32 v76, v76, v77
	v_cvt_pk_bf16_f32 v77, v78, v79
	global_store_dwordx2 v2, v[76:77], s[20:21] offset:1536
	s_waitcnt vmcnt(28)
; DI unsigned pk_bf16(float a, float b) { f32x2 v = {a, b}; bf2_t r = __builtin_convertvector(v, bf2_t); return __builtin_bit_cast(unsigned, r); }
; DI float bflo(unsigned u) { return __uint_as_float(u << 16); }
; DI float bfhi(unsigned u) { return __uint_as_float(u & 0xffff0000u); }
; DI void phase_norm1(const Params& p) {
;     ...
;         for (int i = 0; i < 4; ++i) { const int c = 4 * lane + 256 * i;
;             if (tok < T_PR) { const u32x2 t = *(const u32x2*)(x1 + (size_t)tok * 1024 + c); v[i] = (f32x4){bflo(t.x), bfhi(t.x), bflo(t.y), bfhi(t.y)}; }
;             else { const size_t o = (size_t)(tok - T_PR) * 1024 + c; v[i] = *(const f32x4*)(p.xs + o);
; #pragma unroll
;                 for (int s = 0; s < 4; ++s) v[i] += *(const f32x4*)(part + (size_t)s * 1048576 + o);
;                 u32x2 t; t.x = pk_bf16(v[i].x, v[i].y); t.y = pk_bf16(v[i].z, v[i].w); *(u32x2*)(x1 + (size_t)tok * 1024 + c) = t; }
;             ss += v[i].x * v[i].x + v[i].y * v[i].y + v[i].z * v[i].z + v[i].w * v[i].w; }
;         ss = wave_sum(ss);
;         const float rstd = rsqrtf(ss * (1.f / 1024.f) + 1e-6f);
; #pragma unroll
;         for (int i = 0; i < 4; ++i) { const f32x4 ww = *(const f32x4*)(w + 4 * lane + 256 * i);
;             u32x2 o; o.x = pk_bf16(v[i].x * rstd * ww.x, v[i].y * rstd * ww.y); o.y = pk_bf16(v[i].z * rstd * ww.z, v[i].w * rstd * ww.w);
;             *(u32x2*)(out + (size_t)tok * 1024 + 4 * lane + 256 * i) = o; }
	v_lshlrev_b32_e32 v64, 16, v96
	v_and_b32_e32 v65, 0xffff0000, v96
	v_lshlrev_b32_e32 v66, 16, v97
	v_and_b32_e32 v67, 0xffff0000, v97
	v_lshlrev_b32_e32 v68, 16, v98
	v_and_b32_e32 v69, 0xffff0000, v98
	v_lshlrev_b32_e32 v70, 16, v99
	v_and_b32_e32 v71, 0xffff0000, v99
	v_lshlrev_b32_e32 v72, 16, v100
	v_and_b32_e32 v73, 0xffff0000, v100
	v_lshlrev_b32_e32 v74, 16, v101
	v_and_b32_e32 v75, 0xffff0000, v101
	v_lshlrev_b32_e32 v76, 16, v102
	v_and_b32_e32 v77, 0xffff0000, v102
	v_lshlrev_b32_e32 v78, 16, v103
	v_and_b32_e32 v79, 0xffff0000, v103
	s_mul_i32 s22, s46, 2
	s_add_i32 s22, s22, s4
	v_mul_f32_e32 v48, v64, v64
	v_fmac_f32_e32 v48, v65, v65
	v_fmac_f32_e32 v48, v66, v66
	v_fmac_f32_e32 v48, v67, v67
	v_mul_f32_e32 v49, v68, v68
	v_fmac_f32_e32 v49, v69, v69
	v_fmac_f32_e32 v49, v70, v70
	v_fmac_f32_e32 v49, v71, v71
	v_mul_f32_e32 v50, v72, v72
	v_fmac_f32_e32 v50, v73, v73
	v_fmac_f32_e32 v50, v74, v74
	v_fmac_f32_e32 v50, v75, v75
	v_mul_f32_e32 v51, v76, v76
	v_fmac_f32_e32 v51, v77, v77
	v_fmac_f32_e32 v51, v78, v78
	v_fmac_f32_e32 v51, v79, v79
	v_add_f32_e32 v48, v48, v49
	v_add_f32_e32 v50, v50, v51
	v_add_f32_e32 v48, v48, v50
	s_nop 1
	v_add_f32_dpp v48, v48, v48 quad_perm:[1,0,3,2] row_mask:0xf bank_mask:0xf bound_ctrl:1
	s_nop 1
	v_add_f32_dpp v48, v48, v48 quad_perm:[2,3,0,1] row_mask:0xf bank_mask:0xf bound_ctrl:1
	s_nop 1
	v_add_f32_dpp v48, v48, v48 row_ror:4 row_mask:0xf bank_mask:0xf bound_ctrl:1
	s_nop 1
	v_add_f32_dpp v48, v48, v48 row_ror:8 row_mask:0xf bank_mask:0xf bound_ctrl:1
	s_nop 1
	v_readlane_b32 s28, v48, 0
	v_readlane_b32 s29, v48, 16
	v_readlane_b32 s30, v48, 32
	v_readlane_b32 s31, v48, 48
	s_nop 1
	v_mov_b32_e32 v52, s28
	v_add_f32_e32 v52, s29, v52
	v_add_f32_e32 v52, s30, v52
	v_add_f32_e32 v52, s31, v52
	v_fmamk_f32 v52, v52, 0x3a800000, v60
	v_rsq_f32_e32 v52, v52
	s_lshl_b32 s20, s22, 11
	s_add_u32 s20, s16, s20
	s_addc_u32 s21, s17, 0
	v_mul_f32_e32 v64, v64, v52
	v_mul_f32_e32 v65, v65, v52
	v_mul_f32_e32 v66, v66, v52
	v_mul_f32_e32 v67, v67, v52
	v_mul_f32_e32 v64, v64, v16
	v_mul_f32_e32 v65, v65, v17
	v_mul_f32_e32 v66, v66, v18
	v_mul_f32_e32 v67, v67, v19
	v_cvt_pk_bf16_f32 v64, v64, v65
	v_cvt_pk_bf16_f32 v65, v66, v67
	global_store_dwordx2 v2, v[64:65], s[20:21]
	v_mul_f32_e32 v68, v68, v52
	v_mul_f32_e32 v69, v69, v52
	v_mul_f32_e32 v70, v70, v52
	v_mul_f32_e32 v71, v71, v52
	v_mul_f32_e32 v68, v68, v20
	v_mul_f32_e32 v69, v69, v21
	v_mul_f32_e32 v70, v70, v22
	v_mul_f32_e32 v71, v71, v23
	v_cvt_pk_bf16_f32 v68, v68, v69
	v_cvt_pk_bf16_f32 v69, v70, v71
	global_store_dwordx2 v2, v[68:69], s[20:21] offset:512
	v_mul_f32_e32 v72, v72, v52
	v_mul_f32_e32 v73, v73, v52
	v_mul_f32_e32 v74, v74, v52
	v_mul_f32_e32 v75, v75, v52
	v_mul_f32_e32 v72, v72, v24
	v_mul_f32_e32 v73, v73, v25
	v_mul_f32_e32 v74, v74, v26
	v_mul_f32_e32 v75, v75, v27
	v_cvt_pk_bf16_f32 v72, v72, v73
	v_cvt_pk_bf16_f32 v73, v74, v75
	global_store_dwordx2 v2, v[72:73], s[20:21] offset:1024
	v_mul_f32_e32 v76, v76, v52
	v_mul_f32_e32 v77, v77, v52
	v_mul_f32_e32 v78, v78, v52
	v_mul_f32_e32 v79, v79, v52
	v_mul_f32_e32 v76, v76, v28
	v_mul_f32_e32 v77, v77, v29
	v_mul_f32_e32 v78, v78, v30
	v_mul_f32_e32 v79, v79, v31
	v_cvt_pk_bf16_f32 v76, v76, v77
	v_cvt_pk_bf16_f32 v77, v78, v79
	global_store_dwordx2 v2, v[76:77], s[20:21] offset:1536
	s_waitcnt vmcnt(28)
	v_lshlrev_b32_e32 v64, 16, v104
	v_and_b32_e32 v65, 0xffff0000, v104
	v_lshlrev_b32_e32 v66, 16, v105
	v_and_b32_e32 v67, 0xffff0000, v105
	v_lshlrev_b32_e32 v68, 16, v106
	v_and_b32_e32 v69, 0xffff0000, v106
	v_lshlrev_b32_e32 v70, 16, v107
	v_and_b32_e32 v71, 0xffff0000, v107
	v_lshlrev_b32_e32 v72, 16, v108
	v_and_b32_e32 v73, 0xffff0000, v108
	v_lshlrev_b32_e32 v74, 16, v109
	v_and_b32_e32 v75, 0xffff0000, v109
	v_lshlrev_b32_e32 v76, 16, v110
	v_and_b32_e32 v77, 0xffff0000, v110
	v_lshlrev_b32_e32 v78, 16, v111
	v_and_b32_e32 v79, 0xffff0000, v111
	s_mul_i32 s22, s46, 3
	s_add_i32 s22, s22, s4
	v_mul_f32_e32 v48, v64, v64
	v_fmac_f32_e32 v48, v65, v65
	v_fmac_f32_e32 v48, v66, v66
	v_fmac_f32_e32 v48, v67, v67
	v_mul_f32_e32 v49, v68, v68
	v_fmac_f32_e32 v49, v69, v69
	v_fmac_f32_e32 v49, v70, v70
	v_fmac_f32_e32 v49, v71, v71
	v_mul_f32_e32 v50, v72, v72
	v_fmac_f32_e32 v50, v73, v73
	v_fmac_f32_e32 v50, v74, v74
	v_fmac_f32_e32 v50, v75, v75
	v_mul_f32_e32 v51, v76, v76
	v_fmac_f32_e32 v51, v77, v77
	v_fmac_f32_e32 v51, v78, v78
	v_fmac_f32_e32 v51, v79, v79
	v_add_f32_e32 v48, v48, v49
	v_add_f32_e32 v50, v50, v51
	v_add_f32_e32 v48, v48, v50
	s_nop 1
	v_add_f32_dpp v48, v48, v48 quad_perm:[1,0,3,2] row_mask:0xf bank_mask:0xf bound_ctrl:1
	s_nop 1
	v_add_f32_dpp v48, v48, v48 quad_perm:[2,3,0,1] row_mask:0xf bank_mask:0xf bound_ctrl:1
	s_nop 1
	v_add_f32_dpp v48, v48, v48 row_ror:4 row_mask:0xf bank_mask:0xf bound_ctrl:1
	s_nop 1
	v_add_f32_dpp v48, v48, v48 row_ror:8 row_mask:0xf bank_mask:0xf bound_ctrl:1
	s_nop 1
	v_readlane_b32 s28, v48, 0
	v_readlane_b32 s29, v48, 16
	v_readlane_b32 s30, v48, 32
	v_readlane_b32 s31, v48, 48
	s_nop 1
	v_mov_b32_e32 v52, s28
	v_add_f32_e32 v52, s29, v52
	v_add_f32_e32 v52, s30, v52
	v_add_f32_e32 v52, s31, v52
	v_fmamk_f32 v52, v52, 0x3a800000, v60
	v_rsq_f32_e32 v52, v52
	s_lshl_b32 s20, s22, 11
	s_add_u32 s20, s16, s20
	s_addc_u32 s21, s17, 0
	v_mul_f32_e32 v64, v64, v52
	v_mul_f32_e32 v65, v65, v52
	v_mul_f32_e32 v66, v66, v52
	v_mul_f32_e32 v67, v67, v52
	v_mul_f32_e32 v64, v64, v16
	v_mul_f32_e32 v65, v65, v17
	v_mul_f32_e32 v66, v66, v18
	v_mul_f32_e32 v67, v67, v19
	v_cvt_pk_bf16_f32 v64, v64, v65
	v_cvt_pk_bf16_f32 v65, v66, v67
	global_store_dwordx2 v2, v[64:65], s[20:21]
	v_mul_f32_e32 v68, v68, v52
	v_mul_f32_e32 v69, v69, v52
	v_mul_f32_e32 v70, v70, v52
	v_mul_f32_e32 v71, v71, v52
	v_mul_f32_e32 v68, v68, v20
	v_mul_f32_e32 v69, v69, v21
	v_mul_f32_e32 v70, v70, v22
	v_mul_f32_e32 v71, v71, v23
	v_cvt_pk_bf16_f32 v68, v68, v69
	v_cvt_pk_bf16_f32 v69, v70, v71
	global_store_dwordx2 v2, v[68:69], s[20:21] offset:512
	v_mul_f32_e32 v72, v72, v52
	v_mul_f32_e32 v73, v73, v52
	v_mul_f32_e32 v74, v74, v52
	v_mul_f32_e32 v75, v75, v52
	v_mul_f32_e32 v72, v72, v24
	v_mul_f32_e32 v73, v73, v25
	v_mul_f32_e32 v74, v74, v26
	v_mul_f32_e32 v75, v75, v27
	v_cvt_pk_bf16_f32 v72, v72, v73
	v_cvt_pk_bf16_f32 v73, v74, v75
	global_store_dwordx2 v2, v[72:73], s[20:21] offset:1024
	v_mul_f32_e32 v76, v76, v52
	v_mul_f32_e32 v77, v77, v52
	v_mul_f32_e32 v78, v78, v52
	v_mul_f32_e32 v79, v79, v52
	v_mul_f32_e32 v76, v76, v28
	v_mul_f32_e32 v77, v77, v29
	v_mul_f32_e32 v78, v78, v30
	v_mul_f32_e32 v79, v79, v31
	v_cvt_pk_bf16_f32 v76, v76, v77
	v_cvt_pk_bf16_f32 v77, v78, v79
	global_store_dwordx2 v2, v[76:77], s[20:21] offset:1536
	s_waitcnt vmcnt(28)
; DI unsigned pk_bf16(float a, float b) { f32x2 v = {a, b}; bf2_t r = __builtin_convertvector(v, bf2_t); return __builtin_bit_cast(unsigned, r); }
; DI float bflo(unsigned u) { return __uint_as_float(u << 16); }
; DI float bfhi(unsigned u) { return __uint_as_float(u & 0xffff0000u); }
; DI void phase_norm1(const Params& p) {
;     ...
;         for (int i = 0; i < 4; ++i) { const int c = 4 * lane + 256 * i;
;             if (tok < T_PR) { const u32x2 t = *(const u32x2*)(x1 + (size_t)tok * 1024 + c); v[i] = (f32x4){bflo(t.x), bfhi(t.x), bflo(t.y), bfhi(t.y)}; }
;             else { const size_t o = (size_t)(tok - T_PR) * 1024 + c; v[i] = *(const f32x4*)(p.xs + o);
; #pragma unroll
;                 for (int s = 0; s < 4; ++s) v[i] += *(const f32x4*)(part + (size_t)s * 1048576 + o);
;                 u32x2 t; t.x = pk_bf16(v[i].x, v[i].y); t.y = pk_bf16(v[i].z, v[i].w); *(u32x2*)(x1 + (size_t)tok * 1024 + c) = t; }
;             ss += v[i].x * v[i].x + v[i].y * v[i].y + v[i].z * v[i].z + v[i].w * v[i].w; }
;         ss = wave_sum(ss);
;         const float rstd = rsqrtf(ss * (1.f / 1024.f) + 1e-6f);
; #pragma unroll
;         for (int i = 0; i < 4; ++i) { const f32x4 ww = *(const f32x4*)(w + 4 * lane + 256 * i);
;             u32x2 o; o.x = pk_bf16(v[i].x * rstd * ww.x, v[i].y * rstd * ww.y); o.y = pk_bf16(v[i].z * rstd * ww.z, v[i].w * rstd * ww.w);
;             *(u32x2*)(out + (size_t)tok * 1024 + 4 * lane + 256 * i) = o; }
	v_lshlrev_b32_e32 v64, 16, v112
	v_and_b32_e32 v65, 0xffff0000, v112
	v_lshlrev_b32_e32 v66, 16, v113
	v_and_b32_e32 v67, 0xffff0000, v113
	v_lshlrev_b32_e32 v68, 16, v114
	v_and_b32_e32 v69, 0xffff0000, v114
	v_lshlrev_b32_e32 v70, 16, v115
	v_and_b32_e32 v71, 0xffff0000, v115
	v_lshlrev_b32_e32 v72, 16, v116
	v_and_b32_e32 v73, 0xffff0000, v116
	v_lshlrev_b32_e32 v74, 16, v117
	v_and_b32_e32 v75, 0xffff0000, v117
	v_lshlrev_b32_e32 v76, 16, v118
	v_and_b32_e32 v77, 0xffff0000, v118
	v_lshlrev_b32_e32 v78, 16, v119
	v_and_b32_e32 v79, 0xffff0000, v119
	s_mul_i32 s22, s46, 4
	s_add_i32 s22, s22, s4
	v_mul_f32_e32 v48, v64, v64
	v_fmac_f32_e32 v48, v65, v65
	v_fmac_f32_e32 v48, v66, v66
	v_fmac_f32_e32 v48, v67, v67
	v_mul_f32_e32 v49, v68, v68
	v_fmac_f32_e32 v49, v69, v69
	v_fmac_f32_e32 v49, v70, v70
	v_fmac_f32_e32 v49, v71, v71
	v_mul_f32_e32 v50, v72, v72
	v_fmac_f32_e32 v50, v73, v73
	v_fmac_f32_e32 v50, v74, v74
	v_fmac_f32_e32 v50, v75, v75
	v_mul_f32_e32 v51, v76, v76
	v_fmac_f32_e32 v51, v77, v77
	v_fmac_f32_e32 v51, v78, v78
	v_fmac_f32_e32 v51, v79, v79
	v_add_f32_e32 v48, v48, v49
	v_add_f32_e32 v50, v50, v51
	v_add_f32_e32 v48, v48, v50
	s_nop 1
	v_add_f32_dpp v48, v48, v48 quad_perm:[1,0,3,2] row_mask:0xf bank_mask:0xf bound_ctrl:1
	s_nop 1
	v_add_f32_dpp v48, v48, v48 quad_perm:[2,3,0,1] row_mask:0xf bank_mask:0xf bound_ctrl:1
	s_nop 1
	v_add_f32_dpp v48, v48, v48 row_ror:4 row_mask:0xf bank_mask:0xf bound_ctrl:1
	s_nop 1
	v_add_f32_dpp v48, v48, v48 row_ror:8 row_mask:0xf bank_mask:0xf bound_ctrl:1
	s_nop 1
	v_readlane_b32 s28, v48, 0
	v_readlane_b32 s29, v48, 16
	v_readlane_b32 s30, v48, 32
	v_readlane_b32 s31, v48, 48
	s_nop 1
	v_mov_b32_e32 v52, s28
	v_add_f32_e32 v52, s29, v52
	v_add_f32_e32 v52, s30, v52
	v_add_f32_e32 v52, s31, v52
	v_fmamk_f32 v52, v52, 0x3a800000, v60
	v_rsq_f32_e32 v52, v52
	s_lshl_b32 s20, s22, 11
	s_add_u32 s20, s16, s20
	s_addc_u32 s21, s17, 0
	v_mul_f32_e32 v64, v64, v52
	v_mul_f32_e32 v65, v65, v52
	v_mul_f32_e32 v66, v66, v52
	v_mul_f32_e32 v67, v67, v52
	v_mul_f32_e32 v64, v64, v16
	v_mul_f32_e32 v65, v65, v17
	v_mul_f32_e32 v66, v66, v18
	v_mul_f32_e32 v67, v67, v19
	v_cvt_pk_bf16_f32 v64, v64, v65
	v_cvt_pk_bf16_f32 v65, v66, v67
	global_store_dwordx2 v2, v[64:65], s[20:21]
	v_mul_f32_e32 v68, v68, v52
	v_mul_f32_e32 v69, v69, v52
	v_mul_f32_e32 v70, v70, v52
	v_mul_f32_e32 v71, v71, v52
	v_mul_f32_e32 v68, v68, v20
	v_mul_f32_e32 v69, v69, v21
	v_mul_f32_e32 v70, v70, v22
	v_mul_f32_e32 v71, v71, v23
	v_cvt_pk_bf16_f32 v68, v68, v69
	v_cvt_pk_bf16_f32 v69, v70, v71
	global_store_dwordx2 v2, v[68:69], s[20:21] offset:512
	v_mul_f32_e32 v72, v72, v52
	v_mul_f32_e32 v73, v73, v52
	v_mul_f32_e32 v74, v74, v52
	v_mul_f32_e32 v75, v75, v52
	v_mul_f32_e32 v72, v72, v24
	v_mul_f32_e32 v73, v73, v25
	v_mul_f32_e32 v74, v74, v26
	v_mul_f32_e32 v75, v75, v27
	v_cvt_pk_bf16_f32 v72, v72, v73
	v_cvt_pk_bf16_f32 v73, v74, v75
	global_store_dwordx2 v2, v[72:73], s[20:21] offset:1024
	v_mul_f32_e32 v76, v76, v52
	v_mul_f32_e32 v77, v77, v52
	v_mul_f32_e32 v78, v78, v52
	v_mul_f32_e32 v79, v79, v52
	v_mul_f32_e32 v76, v76, v28
	v_mul_f32_e32 v77, v77, v29
	v_mul_f32_e32 v78, v78, v30
	v_mul_f32_e32 v79, v79, v31
	v_cvt_pk_bf16_f32 v76, v76, v77
	v_cvt_pk_bf16_f32 v77, v78, v79
	global_store_dwordx2 v2, v[76:77], s[20:21] offset:1536
	s_waitcnt vmcnt(28)
	v_lshlrev_b32_e32 v64, 16, v120
	v_and_b32_e32 v65, 0xffff0000, v120
	v_lshlrev_b32_e32 v66, 16, v121
	v_and_b32_e32 v67, 0xffff0000, v121
	v_lshlrev_b32_e32 v68, 16, v122
	v_and_b32_e32 v69, 0xffff0000, v122
	v_lshlrev_b32_e32 v70, 16, v123
	v_and_b32_e32 v71, 0xffff0000, v123
	v_lshlrev_b32_e32 v72, 16, v124
	v_and_b32_e32 v73, 0xffff0000, v124
	v_lshlrev_b32_e32 v74, 16, v125
	v_and_b32_e32 v75, 0xffff0000, v125
	v_lshlrev_b32_e32 v76, 16, v126
	v_and_b32_e32 v77, 0xffff0000, v126
	v_lshlrev_b32_e32 v78, 16, v127
	v_and_b32_e32 v79, 0xffff0000, v127
	s_mul_i32 s22, s46, 5
	s_add_i32 s22, s22, s4
	v_mul_f32_e32 v48, v64, v64
	v_fmac_f32_e32 v48, v65, v65
	v_fmac_f32_e32 v48, v66, v66
	v_fmac_f32_e32 v48, v67, v67
	v_mul_f32_e32 v49, v68, v68
	v_fmac_f32_e32 v49, v69, v69
	v_fmac_f32_e32 v49, v70, v70
	v_fmac_f32_e32 v49, v71, v71
	v_mul_f32_e32 v50, v72, v72
	v_fmac_f32_e32 v50, v73, v73
	v_fmac_f32_e32 v50, v74, v74
	v_fmac_f32_e32 v50, v75, v75
	v_mul_f32_e32 v51, v76, v76
	v_fmac_f32_e32 v51, v77, v77
	v_fmac_f32_e32 v51, v78, v78
	v_fmac_f32_e32 v51, v79, v79
	v_add_f32_e32 v48, v48, v49
	v_add_f32_e32 v50, v50, v51
	v_add_f32_e32 v48, v48, v50
	s_nop 1
	v_add_f32_dpp v48, v48, v48 quad_perm:[1,0,3,2] row_mask:0xf bank_mask:0xf bound_ctrl:1
	s_nop 1
	v_add_f32_dpp v48, v48, v48 quad_perm:[2,3,0,1] row_mask:0xf bank_mask:0xf bound_ctrl:1
	s_nop 1
	v_add_f32_dpp v48, v48, v48 row_ror:4 row_mask:0xf bank_mask:0xf bound_ctrl:1
	s_nop 1
	v_add_f32_dpp v48, v48, v48 row_ror:8 row_mask:0xf bank_mask:0xf bound_ctrl:1
	s_nop 1
	v_readlane_b32 s28, v48, 0
	v_readlane_b32 s29, v48, 16
	v_readlane_b32 s30, v48, 32
	v_readlane_b32 s31, v48, 48
	s_nop 1
	v_mov_b32_e32 v52, s28
	v_add_f32_e32 v52, s29, v52
	v_add_f32_e32 v52, s30, v52
	v_add_f32_e32 v52, s31, v52
	v_fmamk_f32 v52, v52, 0x3a800000, v60
	v_rsq_f32_e32 v52, v52
	s_lshl_b32 s20, s22, 11
	s_add_u32 s20, s16, s20
	s_addc_u32 s21, s17, 0
	v_mul_f32_e32 v64, v64, v52
	v_mul_f32_e32 v65, v65, v52
	v_mul_f32_e32 v66, v66, v52
	v_mul_f32_e32 v67, v67, v52
	v_mul_f32_e32 v64, v64, v16
	v_mul_f32_e32 v65, v65, v17
	v_mul_f32_e32 v66, v66, v18
	v_mul_f32_e32 v67, v67, v19
	v_cvt_pk_bf16_f32 v64, v64, v65
	v_cvt_pk_bf16_f32 v65, v66, v67
	global_store_dwordx2 v2, v[64:65], s[20:21]
	v_mul_f32_e32 v68, v68, v52
	v_mul_f32_e32 v69, v69, v52
	v_mul_f32_e32 v70, v70, v52
	v_mul_f32_e32 v71, v71, v52
	v_mul_f32_e32 v68, v68, v20
	v_mul_f32_e32 v69, v69, v21
	v_mul_f32_e32 v70, v70, v22
	v_mul_f32_e32 v71, v71, v23
	v_cvt_pk_bf16_f32 v68, v68, v69
	v_cvt_pk_bf16_f32 v69, v70, v71
	global_store_dwordx2 v2, v[68:69], s[20:21] offset:512
	v_mul_f32_e32 v72, v72, v52
	v_mul_f32_e32 v73, v73, v52
	v_mul_f32_e32 v74, v74, v52
	v_mul_f32_e32 v75, v75, v52
	v_mul_f32_e32 v72, v72, v24
	v_mul_f32_e32 v73, v73, v25
	v_mul_f32_e32 v74, v74, v26
	v_mul_f32_e32 v75, v75, v27
	v_cvt_pk_bf16_f32 v72, v72, v73
	v_cvt_pk_bf16_f32 v73, v74, v75
	global_store_dwordx2 v2, v[72:73], s[20:21] offset:1024
	v_mul_f32_e32 v76, v76, v52
	v_mul_f32_e32 v77, v77, v52
	v_mul_f32_e32 v78, v78, v52
	v_mul_f32_e32 v79, v79, v52
	v_mul_f32_e32 v76, v76, v28
	v_mul_f32_e32 v77, v77, v29
	v_mul_f32_e32 v78, v78, v30
	v_mul_f32_e32 v79, v79, v31
	v_cvt_pk_bf16_f32 v76, v76, v77
	v_cvt_pk_bf16_f32 v77, v78, v79
	global_store_dwordx2 v2, v[76:77], s[20:21] offset:1536
	s_waitcnt vmcnt(28)
; DI unsigned pk_bf16(float a, float b) { f32x2 v = {a, b}; bf2_t r = __builtin_convertvector(v, bf2_t); return __builtin_bit_cast(unsigned, r); }
; DI float bflo(unsigned u) { return __uint_as_float(u << 16); }
; DI float bfhi(unsigned u) { return __uint_as_float(u & 0xffff0000u); }
; DI void phase_norm1(const Params& p) {
;     ...
;         for (int i = 0; i < 4; ++i) { const int c = 4 * lane + 256 * i;
;             if (tok < T_PR) { const u32x2 t = *(const u32x2*)(x1 + (size_t)tok * 1024 + c); v[i] = (f32x4){bflo(t.x), bfhi(t.x), bflo(t.y), bfhi(t.y)}; }
;             else { const size_t o = (size_t)(tok - T_PR) * 1024 + c; v[i] = *(const f32x4*)(p.xs + o);
; #pragma unroll
;                 for (int s = 0; s < 4; ++s) v[i] += *(const f32x4*)(part + (size_t)s * 1048576 + o);
;                 u32x2 t; t.x = pk_bf16(v[i].x, v[i].y); t.y = pk_bf16(v[i].z, v[i].w); *(u32x2*)(x1 + (size_t)tok * 1024 + c) = t; }
;             ss += v[i].x * v[i].x + v[i].y * v[i].y + v[i].z * v[i].z + v[i].w * v[i].w; }
;         ss = wave_sum(ss);
;         const float rstd = rsqrtf(ss * (1.f / 1024.f) + 1e-6f);
; #pragma unroll
;         for (int i = 0; i < 4; ++i) { const f32x4 ww = *(const f32x4*)(w + 4 * lane + 256 * i);
;             u32x2 o; o.x = pk_bf16(v[i].x * rstd * ww.x, v[i].y * rstd * ww.y); o.y = pk_bf16(v[i].z * rstd * ww.z, v[i].w * rstd * ww.w);
;             *(u32x2*)(out + (size_t)tok * 1024 + 4 * lane + 256 * i) = o; }
	v_lshlrev_b32_e32 v64, 16, v128
	v_and_b32_e32 v65, 0xffff0000, v128
	v_lshlrev_b32_e32 v66, 16, v129
	v_and_b32_e32 v67, 0xffff0000, v129
	v_lshlrev_b32_e32 v68, 16, v130
	v_and_b32_e32 v69, 0xffff0000, v130
	v_lshlrev_b32_e32 v70, 16, v131
	v_and_b32_e32 v71, 0xffff0000, v131
	v_lshlrev_b32_e32 v72, 16, v132
	v_and_b32_e32 v73, 0xffff0000, v132
	v_lshlrev_b32_e32 v74, 16, v133
	v_and_b32_e32 v75, 0xffff0000, v133
	v_lshlrev_b32_e32 v76, 16, v134
	v_and_b32_e32 v77, 0xffff0000, v134
	v_lshlrev_b32_e32 v78, 16, v135
	v_and_b32_e32 v79, 0xffff0000, v135
	s_mul_i32 s22, s46, 6
	s_add_i32 s22, s22, s4
	v_mul_f32_e32 v48, v64, v64
	v_fmac_f32_e32 v48, v65, v65
	v_fmac_f32_e32 v48, v66, v66
	v_fmac_f32_e32 v48, v67, v67
	v_mul_f32_e32 v49, v68, v68
	v_fmac_f32_e32 v49, v69, v69
	v_fmac_f32_e32 v49, v70, v70
	v_fmac_f32_e32 v49, v71, v71
	v_mul_f32_e32 v50, v72, v72
	v_fmac_f32_e32 v50, v73, v73
	v_fmac_f32_e32 v50, v74, v74
	v_fmac_f32_e32 v50, v75, v75
	v_mul_f32_e32 v51, v76, v76
	v_fmac_f32_e32 v51, v77, v77
	v_fmac_f32_e32 v51, v78, v78
	v_fmac_f32_e32 v51, v79, v79
	v_add_f32_e32 v48, v48, v49
	v_add_f32_e32 v50, v50, v51
	v_add_f32_e32 v48, v48, v50
	s_nop 1
	v_add_f32_dpp v48, v48, v48 quad_perm:[1,0,3,2] row_mask:0xf bank_mask:0xf bound_ctrl:1
	s_nop 1
	v_add_f32_dpp v48, v48, v48 quad_perm:[2,3,0,1] row_mask:0xf bank_mask:0xf bound_ctrl:1
	s_nop 1
	v_add_f32_dpp v48, v48, v48 row_ror:4 row_mask:0xf bank_mask:0xf bound_ctrl:1
	s_nop 1
	v_add_f32_dpp v48, v48, v48 row_ror:8 row_mask:0xf bank_mask:0xf bound_ctrl:1
	s_nop 1
	v_readlane_b32 s28, v48, 0
	v_readlane_b32 s29, v48, 16
	v_readlane_b32 s30, v48, 32
	v_readlane_b32 s31, v48, 48
	s_nop 1
	v_mov_b32_e32 v52, s28
	v_add_f32_e32 v52, s29, v52
	v_add_f32_e32 v52, s30, v52
	v_add_f32_e32 v52, s31, v52
	v_fmamk_f32 v52, v52, 0x3a800000, v60
	v_rsq_f32_e32 v52, v52
	s_lshl_b32 s20, s22, 11
	s_add_u32 s20, s16, s20
	s_addc_u32 s21, s17, 0
	v_mul_f32_e32 v64, v64, v52
	v_mul_f32_e32 v65, v65, v52
	v_mul_f32_e32 v66, v66, v52
	v_mul_f32_e32 v67, v67, v52
	v_mul_f32_e32 v64, v64, v16
	v_mul_f32_e32 v65, v65, v17
	v_mul_f32_e32 v66, v66, v18
	v_mul_f32_e32 v67, v67, v19
	v_cvt_pk_bf16_f32 v64, v64, v65
	v_cvt_pk_bf16_f32 v65, v66, v67
	global_store_dwordx2 v2, v[64:65], s[20:21]
	v_mul_f32_e32 v68, v68, v52
	v_mul_f32_e32 v69, v69, v52
	v_mul_f32_e32 v70, v70, v52
	v_mul_f32_e32 v71, v71, v52
	v_mul_f32_e32 v68, v68, v20
	v_mul_f32_e32 v69, v69, v21
	v_mul_f32_e32 v70, v70, v22
	v_mul_f32_e32 v71, v71, v23
	v_cvt_pk_bf16_f32 v68, v68, v69
	v_cvt_pk_bf16_f32 v69, v70, v71
	global_store_dwordx2 v2, v[68:69], s[20:21] offset:512
	v_mul_f32_e32 v72, v72, v52
	v_mul_f32_e32 v73, v73, v52
	v_mul_f32_e32 v74, v74, v52
	v_mul_f32_e32 v75, v75, v52
	v_mul_f32_e32 v72, v72, v24
	v_mul_f32_e32 v73, v73, v25
	v_mul_f32_e32 v74, v74, v26
	v_mul_f32_e32 v75, v75, v27
	v_cvt_pk_bf16_f32 v72, v72, v73
	v_cvt_pk_bf16_f32 v73, v74, v75
	global_store_dwordx2 v2, v[72:73], s[20:21] offset:1024
	v_mul_f32_e32 v76, v76, v52
	v_mul_f32_e32 v77, v77, v52
	v_mul_f32_e32 v78, v78, v52
	v_mul_f32_e32 v79, v79, v52
	v_mul_f32_e32 v76, v76, v28
	v_mul_f32_e32 v77, v77, v29
	v_mul_f32_e32 v78, v78, v30
	v_mul_f32_e32 v79, v79, v31
	v_cvt_pk_bf16_f32 v76, v76, v77
	v_cvt_pk_bf16_f32 v77, v78, v79
	global_store_dwordx2 v2, v[76:77], s[20:21] offset:1536
	s_waitcnt vmcnt(28)
	v_lshlrev_b32_e32 v64, 16, v136
	v_and_b32_e32 v65, 0xffff0000, v136
	v_lshlrev_b32_e32 v66, 16, v137
	v_and_b32_e32 v67, 0xffff0000, v137
	v_lshlrev_b32_e32 v68, 16, v138
	v_and_b32_e32 v69, 0xffff0000, v138
	v_lshlrev_b32_e32 v70, 16, v139
	v_and_b32_e32 v71, 0xffff0000, v139
	v_lshlrev_b32_e32 v72, 16, v140
	v_and_b32_e32 v73, 0xffff0000, v140
	v_lshlrev_b32_e32 v74, 16, v141
	v_and_b32_e32 v75, 0xffff0000, v141
	v_lshlrev_b32_e32 v76, 16, v142
	v_and_b32_e32 v77, 0xffff0000, v142
	v_lshlrev_b32_e32 v78, 16, v143
	v_and_b32_e32 v79, 0xffff0000, v143
	s_mul_i32 s22, s46, 7
	s_add_i32 s22, s22, s4
	v_mul_f32_e32 v48, v64, v64
	v_fmac_f32_e32 v48, v65, v65
	v_fmac_f32_e32 v48, v66, v66
	v_fmac_f32_e32 v48, v67, v67
	v_mul_f32_e32 v49, v68, v68
	v_fmac_f32_e32 v49, v69, v69
	v_fmac_f32_e32 v49, v70, v70
	v_fmac_f32_e32 v49, v71, v71
	v_mul_f32_e32 v50, v72, v72
	v_fmac_f32_e32 v50, v73, v73
	v_fmac_f32_e32 v50, v74, v74
	v_fmac_f32_e32 v50, v75, v75
	v_mul_f32_e32 v51, v76, v76
	v_fmac_f32_e32 v51, v77, v77
	v_fmac_f32_e32 v51, v78, v78
	v_fmac_f32_e32 v51, v79, v79
	v_add_f32_e32 v48, v48, v49
	v_add_f32_e32 v50, v50, v51
	v_add_f32_e32 v48, v48, v50
	s_nop 1
	v_add_f32_dpp v48, v48, v48 quad_perm:[1,0,3,2] row_mask:0xf bank_mask:0xf bound_ctrl:1
	s_nop 1
	v_add_f32_dpp v48, v48, v48 quad_perm:[2,3,0,1] row_mask:0xf bank_mask:0xf bound_ctrl:1
	s_nop 1
	v_add_f32_dpp v48, v48, v48 row_ror:4 row_mask:0xf bank_mask:0xf bound_ctrl:1
	s_nop 1
	v_add_f32_dpp v48, v48, v48 row_ror:8 row_mask:0xf bank_mask:0xf bound_ctrl:1
	s_nop 1
	v_readlane_b32 s28, v48, 0
	v_readlane_b32 s29, v48, 16
	v_readlane_b32 s30, v48, 32
	v_readlane_b32 s31, v48, 48
	s_nop 1
	v_mov_b32_e32 v52, s28
	v_add_f32_e32 v52, s29, v52
	v_add_f32_e32 v52, s30, v52
	v_add_f32_e32 v52, s31, v52
	v_fmamk_f32 v52, v52, 0x3a800000, v60
	v_rsq_f32_e32 v52, v52
	s_lshl_b32 s20, s22, 11
	s_add_u32 s20, s16, s20
	s_addc_u32 s21, s17, 0
	v_mul_f32_e32 v64, v64, v52
	v_mul_f32_e32 v65, v65, v52
	v_mul_f32_e32 v66, v66, v52
	v_mul_f32_e32 v67, v67, v52
	v_mul_f32_e32 v64, v64, v16
	v_mul_f32_e32 v65, v65, v17
	v_mul_f32_e32 v66, v66, v18
	v_mul_f32_e32 v67, v67, v19
	v_cvt_pk_bf16_f32 v64, v64, v65
	v_cvt_pk_bf16_f32 v65, v66, v67
	global_store_dwordx2 v2, v[64:65], s[20:21]
	v_mul_f32_e32 v68, v68, v52
	v_mul_f32_e32 v69, v69, v52
	v_mul_f32_e32 v70, v70, v52
	v_mul_f32_e32 v71, v71, v52
	v_mul_f32_e32 v68, v68, v20
	v_mul_f32_e32 v69, v69, v21
	v_mul_f32_e32 v70, v70, v22
	v_mul_f32_e32 v71, v71, v23
	v_cvt_pk_bf16_f32 v68, v68, v69
	v_cvt_pk_bf16_f32 v69, v70, v71
	global_store_dwordx2 v2, v[68:69], s[20:21] offset:512
	v_mul_f32_e32 v72, v72, v52
	v_mul_f32_e32 v73, v73, v52
	v_mul_f32_e32 v74, v74, v52
	v_mul_f32_e32 v75, v75, v52
	v_mul_f32_e32 v72, v72, v24
	v_mul_f32_e32 v73, v73, v25
	v_mul_f32_e32 v74, v74, v26
	v_mul_f32_e32 v75, v75, v27
	v_cvt_pk_bf16_f32 v72, v72, v73
	v_cvt_pk_bf16_f32 v73, v74, v75
	global_store_dwordx2 v2, v[72:73], s[20:21] offset:1024
	v_mul_f32_e32 v76, v76, v52
	v_mul_f32_e32 v77, v77, v52
	v_mul_f32_e32 v78, v78, v52
	v_mul_f32_e32 v79, v79, v52
	v_mul_f32_e32 v76, v76, v28
	v_mul_f32_e32 v77, v77, v29
	v_mul_f32_e32 v78, v78, v30
	v_mul_f32_e32 v79, v79, v31
	v_cvt_pk_bf16_f32 v76, v76, v77
	v_cvt_pk_bf16_f32 v77, v78, v79
	global_store_dwordx2 v2, v[76:77], s[20:21] offset:1536
	s_cmpk_lt_u32 s4, 0x400
	s_cbranch_scc0 .Ln1_done
; DI unsigned pk_bf16(float a, float b) { f32x2 v = {a, b}; bf2_t r = __builtin_convertvector(v, bf2_t); return __builtin_bit_cast(unsigned, r); }
; DI void phase_norm1(const Params& p) {
;     ...
;             else { const size_t o = (size_t)(tok - T_PR) * 1024 + c; v[i] = *(const f32x4*)(p.xs + o);
; #pragma unroll
;                 for (int s = 0; s < 4; ++s) v[i] += *(const f32x4*)(part + (size_t)s * 1048576 + o);
;                 u32x2 t; t.x = pk_bf16(v[i].x, v[i].y); t.y = pk_bf16(v[i].z, v[i].w); *(u32x2*)(x1 + (size_t)tok * 1024 + c) = t; }
;             ss += v[i].x * v[i].x + v[i].y * v[i].y + v[i].z * v[i].z + v[i].w * v[i].w; }
;         ss = wave_sum(ss);
;         const float rstd = rsqrtf(ss * (1.f / 1024.f) + 1e-6f);
; #pragma unroll
;         for (int i = 0; i < 4; ++i) { const f32x4 ww = *(const f32x4*)(w + 4 * lane + 256 * i);
;             u32x2 o; o.x = pk_bf16(v[i].x * rstd * ww.x, v[i].y * rstd * ww.y); o.y = pk_bf16(v[i].z * rstd * ww.z, v[i].w * rstd * ww.w);
;             *(u32x2*)(out + (size_t)tok * 1024 + 4 * lane + 256 * i) = o; }
	s_waitcnt vmcnt(32)
	s_add_i32 s4, s4, 0x4000
	v_add_f32_e32 v64, v168, v198
	v_add_f32_e32 v65, v169, v199
	v_add_f32_e32 v66, v170, v200
	v_add_f32_e32 v67, v171, v201
	v_add_f32_e32 v68, v172, v202
	v_add_f32_e32 v69, v173, v203
	v_add_f32_e32 v70, v174, v204
	v_add_f32_e32 v71, v175, v205
	v_add_f32_e32 v72, v176, v206
	v_add_f32_e32 v73, v177, v207
	v_add_f32_e32 v74, v178, v208
	v_add_f32_e32 v75, v179, v209
	v_add_f32_e32 v76, v180, v210
	v_add_f32_e32 v77, v181, v211
	v_add_f32_e32 v78, v182, v212
	v_add_f32_e32 v79, v183, v213
	v_add_f32_e32 v64, v64, v214
	v_add_f32_e32 v65, v65, v215
	v_add_f32_e32 v66, v66, v216
	v_add_f32_e32 v67, v67, v217
	v_add_f32_e32 v68, v68, v218
	v_add_f32_e32 v69, v69, v219
	v_add_f32_e32 v70, v70, v220
	v_add_f32_e32 v71, v71, v221
	v_add_f32_e32 v72, v72, v222
	v_add_f32_e32 v73, v73, v223
	v_add_f32_e32 v74, v74, v224
	v_add_f32_e32 v75, v75, v225
	v_add_f32_e32 v76, v76, v226
	v_add_f32_e32 v77, v77, v227
	v_add_f32_e32 v78, v78, v228
	v_add_f32_e32 v79, v79, v229
	v_add_f32_e32 v64, v64, v240
	v_add_f32_e32 v65, v65, v241
	v_add_f32_e32 v66, v66, v242
	v_add_f32_e32 v67, v67, v243
	v_add_f32_e32 v68, v68, v244
	v_add_f32_e32 v69, v69, v245
	v_add_f32_e32 v70, v70, v246
	v_add_f32_e32 v71, v71, v247
	v_add_f32_e32 v72, v72, v248
	v_add_f32_e32 v73, v73, v249
	v_add_f32_e32 v74, v74, v250
	v_add_f32_e32 v75, v75, v251
	v_add_f32_e32 v76, v76, v252
	v_add_f32_e32 v77, v77, v253
	v_add_f32_e32 v78, v78, v254
	v_add_f32_e32 v79, v79, v255
	v_add_f32_e32 v64, v64, v32
	v_add_f32_e32 v65, v65, v33
	v_add_f32_e32 v66, v66, v34
	v_add_f32_e32 v67, v67, v35
	v_add_f32_e32 v68, v68, v36
	v_add_f32_e32 v69, v69, v37
	v_add_f32_e32 v70, v70, v38
	v_add_f32_e32 v71, v71, v39
	v_add_f32_e32 v72, v72, v40
	v_add_f32_e32 v73, v73, v41
	v_add_f32_e32 v74, v74, v42
	v_add_f32_e32 v75, v75, v43
	v_add_f32_e32 v76, v76, v44
	v_add_f32_e32 v77, v77, v45
	v_add_f32_e32 v78, v78, v46
	v_add_f32_e32 v79, v79, v47
	s_lshl_b32 s26, s4, 11
	s_add_u32 s26, s12, s26
	s_addc_u32 s27, s13, 0
	v_cvt_pk_bf16_f32 v144, v64, v65
	v_cvt_pk_bf16_f32 v145, v66, v67
	global_store_dwordx2 v2, v[144:145], s[26:27]
	v_cvt_pk_bf16_f32 v146, v68, v69
	v_cvt_pk_bf16_f32 v147, v70, v71
	global_store_dwordx2 v2, v[146:147], s[26:27] offset:512
	v_cvt_pk_bf16_f32 v148, v72, v73
	v_cvt_pk_bf16_f32 v149, v74, v75
	global_store_dwordx2 v2, v[148:149], s[26:27] offset:1024
	v_cvt_pk_bf16_f32 v150, v76, v77
	v_cvt_pk_bf16_f32 v151, v78, v79
	global_store_dwordx2 v2, v[150:151], s[26:27] offset:1536
	v_mul_f32_e32 v48, v64, v64
	v_fmac_f32_e32 v48, v65, v65
	v_fmac_f32_e32 v48, v66, v66
	v_fmac_f32_e32 v48, v67, v67
	v_mul_f32_e32 v49, v68, v68
	v_fmac_f32_e32 v49, v69, v69
	v_fmac_f32_e32 v49, v70, v70
	v_fmac_f32_e32 v49, v71, v71
	v_mul_f32_e32 v50, v72, v72
	v_fmac_f32_e32 v50, v73, v73
	v_fmac_f32_e32 v50, v74, v74
	v_fmac_f32_e32 v50, v75, v75
	v_mul_f32_e32 v51, v76, v76
	v_fmac_f32_e32 v51, v77, v77
	v_fmac_f32_e32 v51, v78, v78
	v_fmac_f32_e32 v51, v79, v79
	v_add_f32_e32 v48, v48, v49
	v_add_f32_e32 v50, v50, v51
	v_add_f32_e32 v48, v48, v50
	s_nop 1
	v_add_f32_dpp v48, v48, v48 quad_perm:[1,0,3,2] row_mask:0xf bank_mask:0xf bound_ctrl:1
	s_nop 1
	v_add_f32_dpp v48, v48, v48 quad_perm:[2,3,0,1] row_mask:0xf bank_mask:0xf bound_ctrl:1
	s_nop 1
	v_add_f32_dpp v48, v48, v48 row_ror:4 row_mask:0xf bank_mask:0xf bound_ctrl:1
	s_nop 1
	v_add_f32_dpp v48, v48, v48 row_ror:8 row_mask:0xf bank_mask:0xf bound_ctrl:1
	s_nop 1
	v_readlane_b32 s28, v48, 0
	v_readlane_b32 s29, v48, 16
	v_readlane_b32 s30, v48, 32
	v_readlane_b32 s31, v48, 48
	s_nop 1
	v_mov_b32_e32 v52, s28
	v_add_f32_e32 v52, s29, v52
	v_add_f32_e32 v52, s30, v52
	v_add_f32_e32 v52, s31, v52
	v_fmamk_f32 v52, v52, 0x3a800000, v60
	v_rsq_f32_e32 v52, v52
	s_lshl_b32 s20, s4, 11
	s_add_u32 s20, s16, s20
	s_addc_u32 s21, s17, 0
	v_mul_f32_e32 v64, v64, v52
	v_mul_f32_e32 v65, v65, v52
	v_mul_f32_e32 v66, v66, v52
	v_mul_f32_e32 v67, v67, v52
	v_mul_f32_e32 v64, v64, v16
	v_mul_f32_e32 v65, v65, v17
	v_mul_f32_e32 v66, v66, v18
	v_mul_f32_e32 v67, v67, v19
	v_cvt_pk_bf16_f32 v64, v64, v65
	v_cvt_pk_bf16_f32 v65, v66, v67
	global_store_dwordx2 v2, v[64:65], s[20:21]
	v_mul_f32_e32 v68, v68, v52
	v_mul_f32_e32 v69, v69, v52
	v_mul_f32_e32 v70, v70, v52
	v_mul_f32_e32 v71, v71, v52
	v_mul_f32_e32 v68, v68, v20
	v_mul_f32_e32 v69, v69, v21
	v_mul_f32_e32 v70, v70, v22
	v_mul_f32_e32 v71, v71, v23
	v_cvt_pk_bf16_f32 v68, v68, v69
	v_cvt_pk_bf16_f32 v69, v70, v71
	global_store_dwordx2 v2, v[68:69], s[20:21] offset:512
	v_mul_f32_e32 v72, v72, v52
	v_mul_f32_e32 v73, v73, v52
	v_mul_f32_e32 v74, v74, v52
	v_mul_f32_e32 v75, v75, v52
	v_mul_f32_e32 v72, v72, v24
	v_mul_f32_e32 v73, v73, v25
	v_mul_f32_e32 v74, v74, v26
	v_mul_f32_e32 v75, v75, v27
	v_cvt_pk_bf16_f32 v72, v72, v73
	v_cvt_pk_bf16_f32 v73, v74, v75
	global_store_dwordx2 v2, v[72:73], s[20:21] offset:1024
	v_mul_f32_e32 v76, v76, v52
	v_mul_f32_e32 v77, v77, v52
	v_mul_f32_e32 v78, v78, v52
	v_mul_f32_e32 v79, v79, v52
	v_mul_f32_e32 v76, v76, v28
	v_mul_f32_e32 v77, v77, v29
	v_mul_f32_e32 v78, v78, v30
	v_mul_f32_e32 v79, v79, v31
	v_cvt_pk_bf16_f32 v76, v76, v77
	v_cvt_pk_bf16_f32 v77, v78, v79
	global_store_dwordx2 v2, v[76:77], s[20:21] offset:1536
